# flat barrier release: all workgroups poll cross-XCC generation; leaders skip per-XCC release add and waits
# speedup vs baseline: 1.0382x; 1.0057x over previous
.LBB0_67:
	s_or_b64 exec, exec, s[8:9]
	v_cvt_f32_u32_e32 v4, v2
	s_waitcnt vmcnt(0)
	v_readfirstlane_b32 s2, v3
	v_sub_u32_e32 v3, 0, v2
	v_rcp_iflag_f32_e32 v4, v4
	v_add_u32_e32 v5, s2, v1
	v_mul_f32_e32 v4, 0x4f7ffffe, v4
	v_cvt_u32_f32_e32 v4, v4
	v_mul_lo_u32 v1, v3, v4
	v_mul_hi_u32 v1, v4, v1
	v_add_u32_e32 v1, v4, v1
	v_mul_hi_u32 v1, v5, v1
	v_mul_lo_u32 v3, v1, v2
	v_sub_u32_e32 v3, v5, v3
	v_add_u32_e32 v4, 1, v1
	v_sub_u32_e32 v6, v3, v2
	v_cmp_ge_u32_e32 vcc, v3, v2
	s_nop 1
	v_cndmask_b32_e32 v1, v1, v4, vcc
	v_cndmask_b32_e32 v3, v3, v6, vcc
	v_add_u32_e32 v4, 1, v1
	v_cmp_ge_u32_e32 vcc, v3, v2
	v_add_u32_e32 v3, 1, v5
	s_nop 0
	v_cndmask_b32_e32 v1, v1, v4, vcc
	v_mul_lo_u32 v4, v2, v1
	v_add_u32_e32 v2, v4, v2
	v_cmp_ne_u32_e32 vcc, v3, v2
	s_and_saveexec_b64 s[2:3], vcc
	s_xor_b64 s[6:7], exec, s[2:3]
	s_cbranch_execz .LBB0_81
	s_waitcnt lgkmcnt(0)
	v_mov_b32_e32 v0, 0x3500
	global_load_dword v0, v0, s[96:97] sc1
	s_add_u32 s10, s96, 0x3500
	s_addc_u32 s11, s97, 0
	s_waitcnt vmcnt(0)
	v_cmp_eq_u32_e32 vcc, v0, v1
	s_and_saveexec_b64 s[8:9], vcc
	s_cbranch_execz .LBB0_80
	s_mov_b32 s2, 1
	s_mov_b64 s[12:13], 0
	v_mov_b32_e32 v0, 0
	s_branch .LBB0_71

.LBB0_98:
	s_or_b64 exec, exec, s[6:7]
	s_mov_b64 s[6:7], exec
	v_mbcnt_lo_u32_b32 v0, s6, 0
	v_mbcnt_hi_u32_b32 v0, s7, v0
	v_cmp_eq_u32_e32 vcc, 0, v0
	s_and_saveexec_b64 s[8:9], vcc
	s_cbranch_execz .LBB0_100
	s_bcnt1_i32_b64 s2, s[6:7]
	v_mov_b32_e32 v0, 0x2000
	v_mov_b32_e32 v1, s2
.LBB0_100:
	s_or_b64 exec, exec, s[8:9]
.LBB0_101:
	s_or_b64 exec, exec, s[0:1]
	s_waitcnt lgkmcnt(0)
	s_barrier
	v_mbcnt_lo_u32_b32 v0, -1, 0
	v_mbcnt_hi_u32_b32 v0, -1, v0
	v_readlane_b32 s0, v240, 44
	s_nop 1
	v_add_u32_e32 v0, s0, v0
	s_lshl_b32 s0, s84, 9
	v_writelane_b32 v238, s0, 8
	v_add_u32_e32 v0, s0, v0
	s_mov_b32 s0, 0x24000
	v_cmp_gt_i32_e32 vcc, s0, v0
	s_and_saveexec_b64 s[4:5], vcc
	s_cbranch_execz .LBB0_106
	s_lshl_b32 s2, s33, 9
	s_mov_b64 s[6:7], 0

.LBB0_157:
	s_or_b64 exec, exec, s[8:9]
.LBB0_158:
	s_or_b64 exec, exec, s[0:1]
	s_cmp_gt_i32 s84, -1
	s_cselect_b64 s[0:1], -1, 0
	s_cmp_lt_i32 s84, s33
	s_cselect_b64 s[4:5], -1, 0
	v_writelane_b32 v238, s4, 9
	s_waitcnt lgkmcnt(0)
	s_barrier
	v_writelane_b32 v238, s5, 10
	s_and_b64 s[4:5], s[0:1], s[4:5]
	s_cmpk_lt_u32 s84, 0x80
	s_cselect_b64 s[0:1], -1, 0
	v_mbcnt_lo_u32_b32 v0, -1, 0
	v_mbcnt_hi_u32_b32 v0, -1, v0
	v_readlane_b32 s2, v240, 44
	v_writelane_b32 v238, s4, 11
	s_and_b64 s[0:1], s[4:5], s[0:1]
	v_add_u32_e32 v64, s2, v0
	v_cndmask_b32_e64 v0, 0, 1, s[0:1]
	v_writelane_b32 v238, s5, 12
	v_cmp_ne_u32_e64 s[4:5], 1, v0
	s_andn2_b64 vcc, exec, s[0:1]
	s_nop 0
	v_writelane_b32 v238, s4, 13
	s_nop 1
	v_writelane_b32 v238, s5, 14
	s_cbranch_vccnz .LBB0_182
	v_readlane_b32 s1, v238, 8
	v_lshlrev_b32_e32 v0, 2, v64
	v_ashrrev_i32_e32 v68, 7, v64
	s_lshl_b32 s0, s84, 4
	s_and_b32 s1, s1, 0x600
	v_and_b32_e32 v69, 0x1fc, v0
	s_and_b32 s0, s0, 0x7c0
	v_or_b32_e32 v2, s1, v69
	v_add_u32_e32 v70, 4, v68
	v_add_u32_e32 v71, 8, v68
	v_add_u32_e32 v72, 12, v68
	v_add_u32_e32 v73, 16, v68
	v_add_u32_e32 v74, 20, v68
	v_add_u32_e32 v75, 24, v68
	v_add_u32_e32 v76, 28, v68
	v_add_u32_e32 v77, 32, v68
	v_add_u32_e32 v78, 36, v68
	v_add_u32_e32 v79, 40, v68
	v_add_u32_e32 v80, 44, v68
	v_add_u32_e32 v81, 48, v68
	v_add_u32_e32 v82, 52, v68
	v_add_u32_e32 v83, 56, v68
	v_add_u32_e32 v84, 60, v68
	v_add_u32_e32 v0, s0, v68
	v_readlane_b32 s4, v240, 49
	v_lshlrev_b32_e32 v66, 2, v2
	v_add_u32_e32 v2, s0, v70
	v_add_u32_e32 v8, s0, v71
	v_add_u32_e32 v10, s0, v72
	v_add_u32_e32 v16, s0, v73
	v_add_u32_e32 v18, s0, v74
	v_add_u32_e32 v24, s0, v75
	v_add_u32_e32 v26, s0, v76
	v_add_u32_e32 v32, s0, v77
	v_add_u32_e32 v34, s0, v78
	v_add_u32_e32 v40, s0, v79
	v_add_u32_e32 v42, s0, v80
	v_add_u32_e32 v48, s0, v81
	v_add_u32_e32 v50, s0, v82
	v_add_u32_e32 v56, s0, v83
	v_add_u32_e32 v58, s0, v84
	v_ashrrev_i32_e32 v1, 31, v0
	v_readlane_b32 s6, v240, 51
	v_readlane_b32 s7, v240, 52
	v_readlane_b32 s10, v240, 55
	v_readlane_b32 s11, v240, 56
	v_ashrrev_i32_e32 v3, 31, v2
	v_ashrrev_i32_e32 v9, 31, v8
	v_ashrrev_i32_e32 v11, 31, v10
	v_ashrrev_i32_e32 v17, 31, v16
	v_ashrrev_i32_e32 v19, 31, v18
	v_ashrrev_i32_e32 v25, 31, v24
	v_ashrrev_i32_e32 v27, 31, v26
	v_ashrrev_i32_e32 v33, 31, v32
	v_ashrrev_i32_e32 v35, 31, v34
	v_ashrrev_i32_e32 v41, 31, v40
	v_ashrrev_i32_e32 v43, 31, v42
	v_ashrrev_i32_e32 v49, 31, v48
	v_ashrrev_i32_e32 v51, 31, v50
	v_ashrrev_i32_e32 v57, 31, v56
	v_ashrrev_i32_e32 v59, 31, v58
	v_lshlrev_b64 v[0:1], 14, v[0:1]
	s_mov_b64 s[6:7], s[10:11]
	v_lshlrev_b64 v[2:3], 14, v[2:3]
	v_lshlrev_b64 v[8:9], 14, v[8:9]
	v_lshlrev_b64 v[10:11], 14, v[10:11]
	v_lshlrev_b64 v[16:17], 14, v[16:17]
	v_lshlrev_b64 v[18:19], 14, v[18:19]
	v_lshlrev_b64 v[24:25], 14, v[24:25]
	v_lshlrev_b64 v[26:27], 14, v[26:27]
	v_lshlrev_b64 v[32:33], 14, v[32:33]
	v_lshlrev_b64 v[34:35], 14, v[34:35]
	v_lshlrev_b64 v[40:41], 14, v[40:41]
	v_lshlrev_b64 v[42:43], 14, v[42:43]
	v_lshlrev_b64 v[48:49], 14, v[48:49]
	v_lshlrev_b64 v[50:51], 14, v[50:51]
	v_lshlrev_b64 v[56:57], 14, v[56:57]
	v_lshlrev_b64 v[58:59], 14, v[58:59]
	v_lshl_add_u64 v[0:1], s[6:7], 0, v[0:1]
	v_mov_b32_e32 v67, 0
	v_lshl_add_u64 v[2:3], s[6:7], 0, v[2:3]
	v_lshl_add_u64 v[8:9], s[6:7], 0, v[8:9]
	v_lshl_add_u64 v[10:11], s[6:7], 0, v[10:11]
	v_lshl_add_u64 v[16:17], s[6:7], 0, v[16:17]
	v_lshl_add_u64 v[18:19], s[6:7], 0, v[18:19]
	v_lshl_add_u64 v[24:25], s[6:7], 0, v[24:25]
	v_lshl_add_u64 v[26:27], s[6:7], 0, v[26:27]
	v_lshl_add_u64 v[32:33], s[6:7], 0, v[32:33]
	v_lshl_add_u64 v[34:35], s[6:7], 0, v[34:35]
	v_lshl_add_u64 v[40:41], s[6:7], 0, v[40:41]
	v_lshl_add_u64 v[42:43], s[6:7], 0, v[42:43]
	v_lshl_add_u64 v[48:49], s[6:7], 0, v[48:49]
	v_lshl_add_u64 v[50:51], s[6:7], 0, v[50:51]
	v_lshl_add_u64 v[56:57], s[6:7], 0, v[56:57]
	v_lshl_add_u64 v[58:59], s[6:7], 0, v[58:59]
	v_lshl_add_u64 v[0:1], v[0:1], 0, v[66:67]
	v_lshl_add_u64 v[4:5], v[2:3], 0, v[66:67]
	v_lshl_add_u64 v[8:9], v[8:9], 0, v[66:67]
	v_lshl_add_u64 v[12:13], v[10:11], 0, v[66:67]
	v_lshl_add_u64 v[16:17], v[16:17], 0, v[66:67]
	v_lshl_add_u64 v[20:21], v[18:19], 0, v[66:67]
	v_lshl_add_u64 v[24:25], v[24:25], 0, v[66:67]
	v_lshl_add_u64 v[28:29], v[26:27], 0, v[66:67]
	v_lshl_add_u64 v[32:33], v[32:33], 0, v[66:67]
	v_lshl_add_u64 v[36:37], v[34:35], 0, v[66:67]
	v_lshl_add_u64 v[40:41], v[40:41], 0, v[66:67]
	v_lshl_add_u64 v[44:45], v[42:43], 0, v[66:67]
	v_lshl_add_u64 v[48:49], v[48:49], 0, v[66:67]
	v_lshl_add_u64 v[52:53], v[50:51], 0, v[66:67]
	v_lshl_add_u64 v[56:57], v[56:57], 0, v[66:67]
	v_lshl_add_u64 v[60:61], v[58:59], 0, v[66:67]
	global_load_dwordx4 v[0:3], v[0:1], off
	s_nop 0
	global_load_dwordx4 v[4:7], v[4:5], off
	s_nop 0
	global_load_dwordx4 v[8:11], v[8:9], off
	s_nop 0
	global_load_dwordx4 v[12:15], v[12:13], off
	s_nop 0
	global_load_dwordx4 v[16:19], v[16:17], off
	s_nop 0
	global_load_dwordx4 v[20:23], v[20:21], off
	s_nop 0
	global_load_dwordx4 v[24:27], v[24:25], off
	s_nop 0
	global_load_dwordx4 v[28:31], v[28:29], off
	s_nop 0
	global_load_dwordx4 v[32:35], v[32:33], off
	s_nop 0
	global_load_dwordx4 v[36:39], v[36:37], off
	s_nop 0
	global_load_dwordx4 v[40:43], v[40:41], off
	s_nop 0
	global_load_dwordx4 v[44:47], v[44:45], off
	s_nop 0
	global_load_dwordx4 v[48:51], v[48:49], off
	s_nop 0
	global_load_dwordx4 v[52:55], v[52:53], off
	s_nop 0
	global_load_dwordx4 v[56:59], v[56:57], off
	s_nop 0
	global_load_dwordx4 v[60:63], v[60:61], off
	v_readlane_b32 s8, v240, 53
	v_readlane_b32 s9, v240, 54
	v_readlane_b32 s12, v240, 57
	v_readlane_b32 s13, v240, 58
	v_readlane_b32 s14, v240, 59
	v_readlane_b32 s15, v240, 60
	v_bfe_u32 v85, v64, 5, 1
	v_readlane_b32 s16, v240, 61
	v_readlane_b32 s17, v240, 62
	v_readlane_b32 s18, v240, 63
	v_readlane_b32 s19, v239, 0
	s_mov_b64 s[8:9], s[12:13]
	v_lshlrev_b32_e32 v95, 1, v85
	v_readlane_b32 s1, v238, 5
	v_readlane_b32 s5, v240, 50
	s_mov_b64 s[10:11], s[14:15]
	s_mov_b64 s[12:13], s[16:17]
	s_mov_b64 s[14:15], s[18:19]
	v_lshlrev_b32_e32 v64, 1, v64
	v_lshl_or_b32 v95, s1, 7, v95
	s_lshl_b32 s1, s1, 8
	v_and_b32_e32 v97, 62, v64
	v_readlane_b32 s4, v239, 51
	s_movk_i32 s0, 0x810
	v_mov_b32_e32 v98, s1
	v_lshlrev_b32_e32 v66, 1, v97
	v_readlane_b32 s16, v239, 63
	v_readlane_b32 s17, v238, 0
	v_mul_lo_u32 v87, v68, s0
	v_mad_u32_u24 v97, v97, s0, v98
	v_lshl_add_u32 v86, v69, 2, 0
	v_lshl_add_u64 v[64:65], s[16:17], 0, v[66:67]
	v_add_u32_e32 v66, 0xc180, v87
	v_add_u32_e32 v67, 0xe1c0, v87
	v_add_u32_e32 v100, 0x10200, v87
	v_lshl_or_b32 v97, v85, 2, v97
	v_readlane_b32 s5, v239, 52
	v_readlane_b32 s6, v239, 53
	v_readlane_b32 s7, v239, 54
	v_readlane_b32 s8, v239, 55
	v_readlane_b32 s9, v239, 56
	v_readlane_b32 s10, v239, 57
	v_readlane_b32 s11, v239, 58
	v_readlane_b32 s12, v239, 59
	v_readlane_b32 s13, v239, 60
	v_readlane_b32 s14, v239, 61
	v_readlane_b32 s15, v239, 62
	v_readlane_b32 s18, v238, 1
	v_readlane_b32 s19, v238, 2
	v_or_b32_e32 v88, 2, v85
	v_or_b32_e32 v89, 4, v85
	v_or_b32_e32 v90, 6, v85
	v_or_b32_e32 v91, 8, v85
	v_or_b32_e32 v92, 10, v85
	v_or_b32_e32 v93, 12, v85
	v_or_b32_e32 v94, 14, v85
	v_add3_u32 v96, s2, v85, 14
	v_add_u32_e32 v97, 0, v97
	v_add_u32_e32 v98, v86, v66
	v_add_u32_e32 v99, v86, v67
	v_add_u32_e32 v100, v86, v100
	s_movk_i32 s2, 0x800
	s_movk_i32 s3, 0xffe0
	s_mov_b32 s4, s84
	s_branch .LBB0_161

.LBB0_263:
	s_or_b64 exec, exec, s[8:9]
.LBB0_264:
	s_or_b64 exec, exec, s[0:1]
	v_readlane_b32 s2, v240, 45
	v_readlane_b32 s1, v238, 5
	v_readlane_b32 s3, v240, 46
	s_lshr_b32 s0, s77, 8
	s_lshl_b32 s1, s1, 4
	v_cndmask_b32_e64 v1, 0, 1, s[2:3]
	v_writelane_b32 v238, s1, 15
	s_and_b32 s1, s1, 48
	v_cmp_ne_u32_e64 s[20:21], 1, v1
	s_andn2_b64 vcc, exec, s[2:3]
	s_mul_i32 s16, s0, 0x2100
	s_waitcnt lgkmcnt(0)
	s_barrier
	v_mbcnt_lo_u32_b32 v0, -1, 0
	v_mbcnt_hi_u32_b32 v0, -1, v0
	v_writelane_b32 v238, s1, 16
	s_cbranch_vccnz .LBB0_297
	v_and_b32_e32 v1, 15, v0
	v_readlane_b32 s1, v238, 16
	v_lshlrev_b32_e32 v5, 3, v0
	v_and_b32_e32 v6, 0xf8, v5
	v_or_b32_e32 v72, s1, v1
	v_readlane_b32 s1, v240, 44
	s_movk_i32 s2, 0x210
	v_ashrrev_i32_e32 v7, 4, v0
	v_add_u32_e32 v4, s1, v0
	s_lshl_b32 s1, s0, 7
	v_ashrrev_i32_e32 v4, 5, v4
	v_ashrrev_i32_e32 v5, 31, v4
	s_cmpk_lt_u32 s77, 0x100
	v_lshlrev_b64 v[80:81], 10, v[4:5]
	v_mul_lo_u32 v4, v4, s2
	v_lshlrev_b32_e32 v5, 1, v6
	s_cselect_b64 vcc, -1, 0
	s_mov_b64 s[2:3], 0x40000
	v_add3_u32 v73, 0, v4, v5
	v_mul_u32_u24_e32 v4, 0x210, v1
	v_and_b32_e32 v5, -16, v0
	v_lshl_add_u64 v[84:85], v[80:81], 0, s[2:3]
	s_and_b64 s[2:3], vcc, exec
	v_add3_u32 v150, 0, v4, v5
	v_sub_u32_e32 v4, 3, v7
	v_lshlrev_b32_e32 v152, 2, v7
	s_cselect_b32 s2, 0, 3
	v_cndmask_b32_e32 v151, v4, v7, vcc
	v_or_b32_e32 v4, s2, v152
	s_cselect_b32 s3, 1, 2
	v_ashrrev_i32_e32 v5, 31, v4
	v_lshlrev_b64 v[86:87], 10, v[4:5]
	v_or_b32_e32 v4, s3, v152
	s_cselect_b32 s26, 2, 1
	v_ashrrev_i32_e32 v5, 31, v4
	v_lshlrev_b64 v[88:89], 10, v[4:5]
	v_or_b32_e32 v4, s26, v152
	s_cselect_b32 s27, 3, 0
	v_ashrrev_i32_e32 v5, 31, v4
	v_lshlrev_b32_e32 v1, 2, v1
	v_lshlrev_b64 v[90:91], 10, v[4:5]
	v_or_b32_e32 v4, s27, v152
	s_cselect_b32 s6, 0x100, 16
	v_lshl_or_b32 v153, s2, 6, v1
	v_lshl_or_b32 v154, s3, 6, v1
	v_lshl_or_b32 v155, s26, 6, v1
	v_lshl_or_b32 v156, s27, 6, v1
	v_ashrrev_i32_e32 v5, 31, v4
	v_add_u32_e32 v1, s6, v152
	v_lshlrev_b64 v[92:93], 10, v[4:5]
	v_or_b32_e32 v4, s2, v1
	v_ashrrev_i32_e32 v5, 31, v4
	v_lshlrev_b64 v[94:95], 10, v[4:5]
	v_or_b32_e32 v4, s3, v1
	v_ashrrev_i32_e32 v5, 31, v4
	v_lshlrev_b64 v[96:97], 10, v[4:5]
	v_or_b32_e32 v4, s26, v1
	v_ashrrev_i32_e32 v5, 31, v4
	v_and_b32_e32 v0, 31, v0
	v_lshlrev_b64 v[98:99], 10, v[4:5]
	v_or_b32_e32 v4, s27, v1
	v_lshl_or_b32 v0, v0, 4, v80
	v_mov_b32_e32 v1, v81
	v_or_b32_e32 v74, s1, v72
	v_mov_b32_e32 v75, 0
	v_lshlrev_b32_e32 v2, 3, v7
	v_lshl_add_u64 v[0:1], s[62:63], 0, v[0:1]
	s_mov_b64 s[6:7], 0x3c000
	v_lshlrev_b64 v[76:77], 9, v[74:75]
	v_ashrrev_i32_e32 v3, 31, v2
	v_or_b32_e32 v74, 64, v74
	s_mov_b64 s[18:19], 0x4000
	v_ashrrev_i32_e32 v5, 31, v4
	v_lshl_add_u64 v[102:103], v[0:1], 0, s[6:7]
	s_mov_b64 s[6:7], 0x8000
	s_mov_b32 s15, 0
	v_lshlrev_b64 v[78:79], 9, v[74:75]
	v_cmp_eq_u32_e64 s[4:5], 2, v151
	v_lshl_add_u64 v[82:83], v[80:81], 0, s[18:19]
	v_lshlrev_b64 v[100:101], 10, v[4:5]
	s_lshl_b32 s28, s84, 2
	s_lshl_b32 s29, s33, 2
	v_lshl_add_u64 v[104:105], v[0:1], 0, s[6:7]
	s_mov_b32 s30, 0x3fb8aa3b
	s_mov_b32 s31, 0xc2ce8ed0
	s_mov_b32 s34, 0x42b17218
	v_mov_b32_e32 v157, 0x3c0881c4
	v_mov_b32_e32 v158, 0xbab64f3b
	v_lshlrev_b64 v[106:107], 1, v[2:3]
	v_lshlrev_b32_e32 v74, 1, v6
	v_lshlrev_b32_e32 v108, 1, v72
	v_mov_b32_e32 v159, 0x7f800000
	v_not_b32_e32 v160, 63
	v_not_b32_e32 v161, 31
	v_mov_b32_e32 v162, 0x7fc00000
	s_mov_b32 s35, s84
	s_branch .LBB0_267

.LBB0_372:
	s_or_b64 exec, exec, s[10:11]
	v_cvt_f32_u32_e32 v4, v2
	s_waitcnt vmcnt(0)
	v_readfirstlane_b32 s1, v3
	v_sub_u32_e32 v3, 0, v2
	v_rcp_iflag_f32_e32 v4, v4
	v_add_u32_e32 v5, s1, v1
	v_mul_f32_e32 v4, 0x4f7ffffe, v4
	v_cvt_u32_f32_e32 v4, v4
	v_mul_lo_u32 v1, v3, v4
	v_mul_hi_u32 v1, v4, v1
	v_add_u32_e32 v1, v4, v1
	v_mul_hi_u32 v1, v5, v1
	v_mul_lo_u32 v3, v1, v2
	v_sub_u32_e32 v3, v5, v3
	v_add_u32_e32 v4, 1, v1
	v_cmp_ge_u32_e32 vcc, v3, v2
	s_nop 1
	v_cndmask_b32_e32 v1, v1, v4, vcc
	v_sub_u32_e32 v4, v3, v2
	v_cndmask_b32_e32 v3, v3, v4, vcc
	v_add_u32_e32 v4, 1, v1
	v_cmp_ge_u32_e32 vcc, v3, v2
	v_add_u32_e32 v3, 1, v5
	s_nop 0
	v_cndmask_b32_e32 v1, v1, v4, vcc
	v_mul_lo_u32 v4, v2, v1
	v_add_u32_e32 v2, v4, v2
	v_cmp_ne_u32_e32 vcc, v3, v2
	s_and_saveexec_b64 s[2:3], vcc
	s_xor_b64 s[8:9], exec, s[2:3]
	s_cbranch_execz .LBB0_386
	s_waitcnt lgkmcnt(0)
	v_mov_b32_e32 v0, 0x3500
	global_load_dword v0, v0, s[96:97] sc1
	s_add_u32 s12, s96, 0x3500
	s_addc_u32 s13, s97, 0
	s_waitcnt vmcnt(0)
	v_cmp_eq_u32_e32 vcc, v0, v1
	s_and_saveexec_b64 s[10:11], vcc
	s_cbranch_execz .LBB0_385
	s_mov_b32 s1, 1
	s_mov_b64 s[14:15], 0
	v_mov_b32_e32 v0, 0
	s_branch .LBB0_376

.LBB0_403:
	s_or_b64 exec, exec, s[8:9]
	s_mov_b64 s[8:9], exec
	v_mbcnt_lo_u32_b32 v0, s8, 0
	v_mbcnt_hi_u32_b32 v0, s9, v0
	v_cmp_eq_u32_e32 vcc, 0, v0
	s_and_saveexec_b64 s[10:11], vcc
	s_cbranch_execz .LBB0_405
	s_bcnt1_i32_b64 s1, s[8:9]
	v_mov_b32_e32 v0, 0x2000
	v_mov_b32_e32 v1, s1
.LBB0_405:
	s_or_b64 exec, exec, s[10:11]
.LBB0_406:
	s_or_b64 exec, exec, s[4:5]
	s_cmpk_lt_i32 s84, 0x220
	s_cselect_b64 s[2:3], -1, 0
	v_writelane_b32 v238, s2, 17
	v_readlane_b32 s1, v240, 44
	s_waitcnt lgkmcnt(0)
	v_writelane_b32 v238, s3, 18
	s_barrier
	s_barrier
	v_mbcnt_lo_u32_b32 v0, -1, 0
	v_mbcnt_hi_u32_b32 v0, -1, v0
	v_writelane_b32 v238, s20, 19
	v_add_u32_e32 v16, s1, v0
	s_cmpk_gt_i32 s84, 0x21f
	v_readfirstlane_b32 s1, v16
	v_writelane_b32 v238, s21, 20
	v_writelane_b32 v238, s77, 21
	s_cbranch_scc1 .LBB0_418
	v_lshlrev_b32_e32 v0, 4, v16
	v_add_u32_e32 v1, 0x2000, v0
	v_ashrrev_i32_e32 v2, 31, v1
	v_lshrrev_b32_e32 v2, 22, v2
	v_add_u32_e32 v2, v1, v2
	v_ashrrev_i32_e32 v8, 10, v2
	v_mul_i32_i24_e32 v2, 0x400, v8
	v_sub_u32_e32 v1, v1, v2
	v_lshrrev_b32_e32 v2, 4, v1
	v_bitop3_b32 v1, v2, v1, 32 bitop3:0x6c
	v_ashrrev_i32_e32 v2, 31, v1
	v_lshrrev_b32_e32 v2, 26, v2
	v_add_u32_e32 v2, v1, v2
	s_ashr_i32 s3, s84, 31
	v_ashrrev_i32_e32 v9, 6, v2
	v_and_b32_e32 v2, 0xc0, v2
	s_lshr_b32 s4, s3, 29
	v_sub_u32_e32 v1, v1, v2
	v_mov_b32_e32 v2, 1
	s_add_i32 s4, s84, s4
	s_ashr_i32 s6, s1, 6
	v_ashrrev_i16_sdwa v1, v2, sext(v1) dst_sel:DWORD dst_unused:UNUSED_PAD src0_sel:DWORD src1_sel:BYTE_0
	s_ashr_i32 s7, s4, 3
	s_and_b32 s4, s4, -8
	s_ashr_i32 s5, s1, 8
	s_lshl_b32 s2, s6, 10
	v_bfe_i32 v11, v1, 0, 16
	v_bfe_i32 v1, v16, 27, 1
	s_sub_i32 s4, s84, s4
	v_lshrrev_b32_e32 v1, 22, v1
	s_cmp_lt_i32 s4, 0
	s_movk_i32 s30, 0x45
	v_add_u32_e32 v1, v0, v1
	s_cselect_b32 s8, s30, 0x44
	v_and_b32_e32 v1, 0xfffffc00, v1
	s_mul_i32 s4, s8, s4
	v_sub_u32_e32 v0, v0, v1
	s_add_i32 s4, s4, s7
	v_lshrrev_b32_e32 v1, 4, v0
	s_ashr_i32 s7, s4, 31
	v_bitop3_b32 v0, v1, v0, 32 bitop3:0x6c
	s_lshr_b32 s7, s7, 25
	v_ashrrev_i32_e32 v1, 31, v0
	s_add_i32 s7, s4, s7
	v_lshrrev_b32_e32 v1, 26, v1
	s_ashr_i32 s7, s7, 7
	v_add_u32_e32 v1, v0, v1
	s_lshl_b32 s10, s7, 3
	v_ashrrev_i32_e32 v12, 6, v1
	v_and_b32_e32 v1, 0xc0, v1
	s_sub_i32 s8, 34, s10
	s_lshl_b32 s7, s7, 7
	v_sub_u32_e32 v0, v0, v1
	s_min_u32 s11, s8, 8
	s_sub_i32 s7, s4, s7
	v_ashrrev_i16_sdwa v0, v2, sext(v0) dst_sel:DWORD dst_unused:UNUSED_PAD src0_sel:DWORD src1_sel:BYTE_0
	s_sext_i32_i8 s4, s7
	v_cvt_f32_ubyte0_e32 v1, s11
	v_bfe_i32 v15, v0, 0, 16
	v_cvt_f32_i32_e32 v0, s4
	v_rcp_iflag_f32_e32 v2, v1
	s_ashr_i32 s4, s4, 30
	v_lshlrev_b32_e32 v3, 3, v8
	s_or_b32 s4, s4, 1
	v_mul_f32_e32 v2, v0, v2
	v_trunc_f32_e32 v2, v2
	v_fma_f32 v0, -v2, v1, v0
	v_cvt_i32_f32_e32 v2, v2
	v_cmp_ge_f32_e64 s[8:9], |v0|, v1
	v_and_b32_e32 v3, 0xffff0, v3
	v_lshlrev_b32_e32 v4, 5, v8
	s_and_b64 s[8:9], s[8:9], exec
	v_add_u32_e32 v3, v9, v3
	v_and_b32_e32 v10, 32, v4
	s_cselect_b32 s4, s4, 0
	v_readfirstlane_b32 s8, v2
	v_lshl_or_b32 v3, v3, 11, v10
	s_add_i32 s4, s8, s4
	v_add_lshl_u32 v140, v3, v11, 1
	v_ashrrev_i32_e32 v3, 31, v16
	s_mul_i32 s8, s4, s11
	v_lshrrev_b32_e32 v3, 26, v3
	s_sub_i32 s7, s7, s8
	v_add_u32_e32 v3, v16, v3
	s_sext_i32_i8 s7, s7
	v_ashrrev_i32_e32 v13, 6, v3
	s_add_i32 s18, s10, s7
	v_lshlrev_b32_e32 v3, 3, v13
	s_ashr_i32 s19, s18, 31
	s_bfe_i64 s[10:11], s[4:5], 0x80000
	v_readlane_b32 s60, v239, 51
	v_and_b32_e32 v3, 0xffff0, v3
	v_lshlrev_b32_e32 v4, 5, v13
	s_lshl_b64 s[8:9], s[18:19], 20
	s_lshl_b64 s[10:11], s[10:11], 20
	v_readlane_b32 s72, v239, 63
	v_add_u32_e32 v3, v12, v3
	v_and_b32_e32 v14, 32, v4
	v_readlane_b32 s73, v238, 0
	s_add_u32 s24, s72, s10
	v_lshl_or_b32 v3, v3, 11, v14
	s_addc_u32 s25, s73, s11
	s_add_i32 s31, s2, 0
	v_add_lshl_u32 v142, v3, v15, 1
	s_add_i32 m0, s31, 0x10000
	v_readlane_b32 s66, v239, 57
	global_load_lds_dwordx4 v142, s[24:25]
	s_add_i32 m0, s31, 0x12000
	v_readlane_b32 s67, v239, 58
	s_add_u32 s22, s66, s8
	global_load_lds_dwordx4 v140, s[24:25]
	s_addc_u32 s23, s67, s9
	s_mov_b32 m0, s31
	s_add_i32 s34, s31, 0x2000
	global_load_lds_dwordx4 v142, s[22:23]
	s_mov_b32 m0, s34
	s_add_u32 s8, s24, 0x80000
	global_load_lds_dwordx4 v140, s[22:23]
	s_addc_u32 s9, s25, 0
	s_add_i32 m0, s31, 0x14000
	v_mov_b32_e32 v143, 0
	global_load_lds_dwordx4 v142, s[8:9]
	s_add_i32 m0, s31, 0x16000
	v_mov_b32_e32 v141, v143
	global_load_lds_dwordx4 v140, s[8:9]
	s_add_u32 s8, s22, 0x80000
	s_addc_u32 s9, s23, 0
	s_add_i32 s35, s31, 0x4000
	s_mov_b32 m0, s35
	s_add_i32 s36, s31, 0x6000
	global_load_lds_dwordx4 v142, s[8:9]
	s_mov_b32 m0, s36
	s_mov_b32 s37, 0
	global_load_lds_dwordx4 v140, s[8:9]
	v_lshl_add_u64 v[6:7], s[24:25], 0, v[142:143]
	v_lshl_add_u64 v[4:5], s[24:25], 0, v[140:141]
	v_lshl_add_u64 v[2:3], s[22:23], 0, v[142:143]
	s_cmp_lg_u32 s5, 1
	v_lshl_add_u64 v[0:1], s[22:23], 0, v[140:141]
	v_readlane_b32 s61, v239, 52
	v_readlane_b32 s62, v239, 53
	v_readlane_b32 s63, v239, 54
	v_readlane_b32 s64, v239, 55
	v_readlane_b32 s65, v239, 56
	v_readlane_b32 s68, v239, 59
	v_readlane_b32 s69, v239, 60
	v_readlane_b32 s70, v239, 61
	v_readlane_b32 s71, v239, 62
	v_readlane_b32 s74, v238, 1
	v_readlane_b32 s75, v238, 2
	s_cbranch_scc1 .LBB0_409
	s_barrier

.LBB0_541:
	s_or_b64 exec, exec, s[10:11]
.LBB0_542:
	s_or_b64 exec, exec, s[4:5]
	v_cndmask_b32_e64 v1, 0, 1, s[80:81]
	v_cmp_ne_u32_e64 s[2:3], 1, v1
	s_andn2_b64 vcc, exec, s[80:81]
	s_waitcnt lgkmcnt(0)
	v_writelane_b32 v238, s2, 22
	s_barrier
	v_mbcnt_lo_u32_b32 v0, -1, 0
	v_mbcnt_hi_u32_b32 v0, -1, v0
	s_nop 0
	v_writelane_b32 v238, s3, 23
	s_cbranch_vccnz .LBB0_547
	s_waitcnt vmcnt(7)
	v_lshlrev_b32_e32 v32, 2, v0
	v_ashrrev_i32_e32 v33, 31, v32
	v_readlane_b32 s4, v239, 3
	v_lshlrev_b64 v[0:1], 2, v[32:33]
	v_readlane_b32 s5, v239, 4
	v_readlane_b32 s16, v239, 15
	v_readlane_b32 s17, v239, 16
	s_mov_b64 s[4:5], 0x3000
	v_readlane_b32 s12, v239, 11
	v_lshl_add_u64 v[2:3], s[16:17], 0, v[0:1]
	v_readlane_b32 s13, v239, 12
	v_readlane_b32 s14, v239, 13
	v_readlane_b32 s15, v239, 14
	v_readlane_b32 s18, v239, 17
	v_readlane_b32 s19, v239, 18
	s_waitcnt vmcnt(6)
	v_lshl_add_u64 v[36:37], v[2:3], 0, s[4:5]
	s_mov_b64 s[4:5], 0x3400
	v_readlane_b32 s12, v239, 51
	v_lshl_add_u64 v[38:39], v[2:3], 0, s[4:5]
	s_mov_b64 s[4:5], 0x3800
	v_readlane_b32 s16, v239, 55
	v_readlane_b32 s17, v239, 56
	s_waitcnt vmcnt(5)
	v_lshl_add_u64 v[40:41], v[2:3], 0, s[4:5]
	s_mov_b64 s[4:5], 0x3c00
	s_mov_b64 s[2:3], 0x2000
	v_readlane_b32 s13, v239, 52
	s_cmp_lg_u64 s[16:17], 0
	v_lshl_add_u64 v[42:43], v[2:3], 0, s[4:5]
	v_readlane_b32 s4, v238, 6
	v_lshl_add_u64 v[34:35], v[2:3], 0, s[2:3]
	s_cselect_b64 s[2:3], -1, 0
	v_readlane_b32 s5, v238, 7
	s_mov_b32 s12, s4
	s_ashr_i32 s13, s4, 31
	s_lshl_b64 s[4:5], s[12:13], 13
	s_add_u32 s4, s56, s4
	s_addc_u32 s5, s57, s5
	v_lshl_add_u64 v[0:1], s[4:5], 0, v[0:1]
	s_mov_b64 s[4:5], 0x1000
	v_readlane_b32 s6, v239, 5
	v_readlane_b32 s7, v239, 6
	s_waitcnt vmcnt(4)
	v_lshl_add_u64 v[44:45], v[0:1], 0, s[4:5]
	v_readlane_b32 s4, v238, 3
	v_readlane_b32 s8, v239, 7
	v_readlane_b32 s9, v239, 8
	v_readlane_b32 s5, v238, 4
	s_mov_b32 s6, s4
	s_ashr_i32 s7, s4, 31
	s_lshl_b64 s[8:9], s[6:7], 13
	s_lshl_b64 s[4:5], s[12:13], 12
	s_add_u32 s4, s16, s4
	s_addc_u32 s5, s17, s5
	v_lshl_add_u64 v[0:1], v[32:33], 1, s[4:5]
	s_mov_b64 s[4:5], 0x800
	v_lshl_add_u64 v[46:47], v[0:1], 0, s[4:5]
	s_mov_b32 s4, s6
	v_readlane_b32 s25, v238, 0
	v_readlane_b32 s26, v238, 1
	v_readlane_b32 s27, v238, 2
	v_writelane_b32 v238, s4, 3
	v_readlane_b32 s10, v239, 9
	v_readlane_b32 s11, v239, 10
	v_writelane_b32 v238, s5, 4
	v_cndmask_b32_e64 v0, 0, 1, s[2:3]
	s_mov_b32 s2, s12
	s_lshl_b64 s[10:11], s[6:7], 12
	v_cmp_ne_u32_e64 s[6:7], 1, v0
	s_waitcnt vmcnt(3)
	v_mov_b32_e32 v48, 0x358637bd
	v_writelane_b32 v238, s2, 6
	s_mov_b32 s1, s12
	v_readlane_b32 s14, v239, 53
	v_readlane_b32 s15, v239, 54
	v_readlane_b32 s18, v239, 57
	v_readlane_b32 s19, v239, 58
	v_readlane_b32 s20, v239, 59
	v_readlane_b32 s21, v239, 60
	v_readlane_b32 s22, v239, 61
	v_readlane_b32 s23, v239, 62
	v_readlane_b32 s24, v239, 63
	v_writelane_b32 v238, s3, 7
	s_branch .LBB0_545

.LBB0_565:
	s_or_b64 exec, exec, s[12:13]
	v_cvt_f32_u32_e32 v4, v2
	s_waitcnt vmcnt(0)
	v_readfirstlane_b32 s1, v3
	v_sub_u32_e32 v3, 0, v2
	v_rcp_iflag_f32_e32 v4, v4
	v_add_u32_e32 v5, s1, v1
	v_mul_f32_e32 v4, 0x4f7ffffe, v4
	v_cvt_u32_f32_e32 v4, v4
	v_mul_lo_u32 v1, v3, v4
	v_mul_hi_u32 v1, v4, v1
	v_add_u32_e32 v1, v4, v1
	v_mul_hi_u32 v1, v5, v1
	v_mul_lo_u32 v3, v1, v2
	v_sub_u32_e32 v3, v5, v3
	v_add_u32_e32 v4, 1, v1
	v_cmp_ge_u32_e32 vcc, v3, v2
	s_nop 1
	v_cndmask_b32_e32 v1, v1, v4, vcc
	v_sub_u32_e32 v4, v3, v2
	v_cndmask_b32_e32 v3, v3, v4, vcc
	v_add_u32_e32 v4, 1, v1
	v_cmp_ge_u32_e32 vcc, v3, v2
	v_add_u32_e32 v3, 1, v5
	s_nop 0
	v_cndmask_b32_e32 v1, v1, v4, vcc
	v_mul_lo_u32 v4, v2, v1
	v_add_u32_e32 v2, v4, v2
	v_cmp_ne_u32_e32 vcc, v3, v2
	s_and_saveexec_b64 s[2:3], vcc
	s_xor_b64 s[10:11], exec, s[2:3]
	s_cbranch_execz .LBB0_579
	s_waitcnt lgkmcnt(0)
	v_mov_b32_e32 v0, 0x3500
	global_load_dword v0, v0, s[96:97] sc1
	s_add_u32 s14, s96, 0x3500
	s_addc_u32 s15, s97, 0
	s_waitcnt vmcnt(0)
	v_cmp_eq_u32_e32 vcc, v0, v1
	s_and_saveexec_b64 s[12:13], vcc
	s_cbranch_execz .LBB0_578
	s_mov_b32 s1, 1
	s_mov_b64 s[16:17], 0
	v_mov_b32_e32 v0, 0
	s_branch .LBB0_569

.LBB0_596:
	s_or_b64 exec, exec, s[10:11]
	s_mov_b64 s[10:11], exec
	v_mbcnt_lo_u32_b32 v0, s10, 0
	v_mbcnt_hi_u32_b32 v0, s11, v0
	v_cmp_eq_u32_e32 vcc, 0, v0
	s_and_saveexec_b64 s[12:13], vcc
	s_cbranch_execz .LBB0_598
	s_bcnt1_i32_b64 s1, s[10:11]
	v_mov_b32_e32 v0, 0x2000
	v_mov_b32_e32 v1, s1
.LBB0_598:
	s_or_b64 exec, exec, s[12:13]
.LBB0_599:
	s_or_b64 exec, exec, s[6:7]
	v_readlane_b32 s1, v240, 44
	s_cmpk_lt_i32 s84, 0x5d8
	s_waitcnt lgkmcnt(0)
	s_barrier
	s_barrier
	v_mbcnt_lo_u32_b32 v0, -1, 0
	v_mbcnt_hi_u32_b32 v0, -1, v0
	s_cselect_b64 s[2:3], -1, 0
	s_waitcnt vmcnt(11)
	v_add_u32_e32 v16, s1, v0
	v_writelane_b32 v238, s2, 24
	s_cmpk_gt_i32 s84, 0x5d7
	v_readfirstlane_b32 s1, v16
	v_writelane_b32 v238, s3, 25
	s_cbranch_scc1 .LBB0_611
	v_lshlrev_b32_e32 v0, 4, v16
	v_add_u32_e32 v1, 0x2000, v0
	v_ashrrev_i32_e32 v2, 31, v1
	v_lshrrev_b32_e32 v2, 22, v2
	v_add_u32_e32 v2, v1, v2
	v_ashrrev_i32_e32 v8, 10, v2
	v_mul_i32_i24_e32 v2, 0x400, v8
	v_sub_u32_e32 v1, v1, v2
	v_lshrrev_b32_e32 v2, 4, v1
	v_bitop3_b32 v1, v2, v1, 32 bitop3:0x6c
	v_ashrrev_i32_e32 v2, 31, v1
	v_lshrrev_b32_e32 v2, 26, v2
	v_add_u32_e32 v2, v1, v2
	v_ashrrev_i32_e32 v9, 6, v2
	v_and_b32_e32 v2, 0xc0, v2
	s_ashr_i32 s3, s84, 31
	v_sub_u32_e32 v1, v1, v2
	v_mov_b32_e32 v2, 1
	s_lshr_b32 s4, s3, 29
	v_ashrrev_i16_sdwa v1, v2, sext(v1) dst_sel:DWORD dst_unused:UNUSED_PAD src0_sel:DWORD src1_sel:BYTE_0
	s_add_i32 s4, s84, s4
	s_ashr_i32 s8, s1, 6
	v_bfe_i32 v11, v1, 0, 16
	v_bfe_i32 v1, v16, 27, 1
	s_ashr_i32 s5, s4, 3
	s_and_b32 s4, s4, -8
	s_ashr_i32 s7, s1, 8
	s_lshl_b32 s2, s8, 10
	v_lshrrev_b32_e32 v1, 22, v1
	s_sub_i32 s6, s84, s4
	v_add_u32_e32 v1, v0, v1
	s_cmp_lt_i32 s6, 0
	s_movk_i32 s4, 0xbc
	v_and_b32_e32 v1, 0xfffffc00, v1
	s_cselect_b32 s9, s4, 0xbb
	v_sub_u32_e32 v0, v0, v1
	s_mul_i32 s6, s9, s6
	v_lshrrev_b32_e32 v1, 4, v0
	s_add_i32 s6, s6, s5
	v_bitop3_b32 v0, v1, v0, 32 bitop3:0x6c
	s_mul_hi_i32 s5, s6, 0x2e8ba2e9
	v_ashrrev_i32_e32 v1, 31, v0
	s_lshr_b32 s9, s5, 31
	s_ashr_i32 s5, s5, 6
	v_lshrrev_b32_e32 v1, 26, v1
	s_add_i32 s5, s5, s9
	v_add_u32_e32 v1, v0, v1
	s_lshl_b32 s9, s5, 3
	v_ashrrev_i32_e32 v12, 6, v1
	v_and_b32_e32 v1, 0xc0, v1
	s_sub_i32 s10, 34, s9
	s_mulk_i32 s5, 0x160
	v_sub_u32_e32 v0, v0, v1
	s_min_u32 s12, s10, 8
	s_sub_i32 s5, s6, s5
	v_ashrrev_i16_sdwa v0, v2, sext(v0) dst_sel:DWORD dst_unused:UNUSED_PAD src0_sel:DWORD src1_sel:BYTE_0
	s_sext_i32_i16 s6, s5
	v_cvt_f32_ubyte0_e32 v1, s12
	v_bfe_i32 v15, v0, 0, 16
	v_cvt_f32_i32_e32 v0, s6
	v_rcp_iflag_f32_e32 v2, v1
	s_ashr_i32 s6, s6, 30
	v_lshlrev_b32_e32 v3, 3, v8
	s_or_b32 s6, s6, 1
	v_mul_f32_e32 v2, v0, v2
	v_trunc_f32_e32 v2, v2
	v_fma_f32 v0, -v2, v1, v0
	v_cvt_i32_f32_e32 v2, v2
	v_cmp_ge_f32_e64 s[10:11], |v0|, v1
	v_and_b32_e32 v3, 0xffff0, v3
	v_lshlrev_b32_e32 v4, 5, v8
	s_and_b64 s[10:11], s[10:11], exec
	v_add_u32_e32 v3, v9, v3
	v_and_b32_e32 v10, 32, v4
	s_cselect_b32 s6, s6, 0
	v_readfirstlane_b32 s10, v2
	v_lshl_or_b32 v3, v3, 11, v10
	s_add_i32 s6, s10, s6
	v_add_lshl_u32 v128, v3, v11, 1
	v_ashrrev_i32_e32 v3, 31, v16
	s_mul_i32 s10, s6, s12
	v_lshrrev_b32_e32 v3, 26, v3
	s_sub_i32 s5, s5, s10
	v_add_u32_e32 v3, v16, v3
	s_sext_i32_i16 s5, s5
	v_ashrrev_i32_e32 v13, 6, v3
	s_add_i32 s18, s9, s5
	v_lshlrev_b32_e32 v3, 3, v13
	s_ashr_i32 s19, s18, 31
	s_bfe_i64 s[12:13], s[6:7], 0x100000
	v_readlane_b32 s36, v239, 51
	v_and_b32_e32 v3, 0xffff0, v3
	v_lshlrev_b32_e32 v4, 5, v13
	s_lshl_b64 s[10:11], s[18:19], 20
	s_lshl_b64 s[12:13], s[12:13], 20
	v_readlane_b32 s44, v239, 59
	v_add_u32_e32 v3, v12, v3
	v_and_b32_e32 v14, 32, v4
	v_readlane_b32 s45, v239, 60
	s_add_u32 s22, s44, s12
	v_lshl_or_b32 v3, v3, 11, v14
	s_addc_u32 s23, s45, s13
	s_add_i32 s5, s2, 0
	v_add_lshl_u32 v130, v3, v15, 1
	s_add_i32 m0, s5, 0x10000
	v_readlane_b32 s40, v239, 55
	global_load_lds_dwordx4 v130, s[22:23]
	s_add_i32 m0, s5, 0x12000
	v_readlane_b32 s41, v239, 56
	s_add_u32 s20, s40, s10
	global_load_lds_dwordx4 v128, s[22:23]
	s_addc_u32 s21, s41, s11
	s_mov_b32 m0, s5
	s_add_i32 s28, s5, 0x2000
	global_load_lds_dwordx4 v130, s[20:21]
	s_mov_b32 m0, s28
	s_add_u32 s10, s22, 0x80000
	global_load_lds_dwordx4 v128, s[20:21]
	s_addc_u32 s11, s23, 0
	s_add_i32 m0, s5, 0x14000
	v_mov_b32_e32 v131, 0
	global_load_lds_dwordx4 v130, s[10:11]
	s_add_i32 m0, s5, 0x16000
	v_mov_b32_e32 v129, v131
	global_load_lds_dwordx4 v128, s[10:11]
	s_add_u32 s10, s20, 0x80000
	s_addc_u32 s11, s21, 0
	s_add_i32 s29, s5, 0x4000
	s_mov_b32 m0, s29
	s_add_i32 s30, s5, 0x6000
	global_load_lds_dwordx4 v130, s[10:11]
	s_mov_b32 m0, s30
	s_mov_b32 s31, 0
	global_load_lds_dwordx4 v128, s[10:11]
	v_lshl_add_u64 v[6:7], s[22:23], 0, v[130:131]
	v_lshl_add_u64 v[4:5], s[22:23], 0, v[128:129]
	v_lshl_add_u64 v[2:3], s[20:21], 0, v[130:131]
	s_cmp_lg_u32 s7, 1
	v_lshl_add_u64 v[0:1], s[20:21], 0, v[128:129]
	v_readlane_b32 s37, v239, 52
	v_readlane_b32 s38, v239, 53
	v_readlane_b32 s39, v239, 54
	v_readlane_b32 s42, v239, 57
	v_readlane_b32 s43, v239, 58
	v_readlane_b32 s46, v239, 61
	v_readlane_b32 s47, v239, 62
	v_readlane_b32 s48, v239, 63
	v_readlane_b32 s49, v238, 0
	v_readlane_b32 s50, v238, 1
	v_readlane_b32 s51, v238, 2
	s_cbranch_scc1 .LBB0_602
	s_barrier

.LBB0_662:
	s_or_b64 exec, exec, s[12:13]
.LBB0_663:
	s_or_b64 exec, exec, s[6:7]
	v_readlane_b32 s1, v240, 44
	v_readlane_b32 s2, v238, 19
	s_waitcnt lgkmcnt(0)
	s_barrier
	s_barrier
	v_mbcnt_lo_u32_b32 v0, -1, 0
	v_mbcnt_hi_u32_b32 v0, -1, v0
	v_readlane_b32 s3, v238, 20
	v_add_u32_e32 v16, s1, v0
	s_and_b64 vcc, exec, s[2:3]
	v_readfirstlane_b32 s1, v16
	s_cbranch_vccnz .LBB0_687
	s_ashr_i32 s2, s84, 31
	s_lshr_b32 s3, s2, 29
	s_add_i32 s3, s84, s3
	s_and_b32 s4, s3, -8
	s_sub_i32 s5, s84, s4
	s_cmp_gt_i32 s5, -1
	s_cbranch_scc0 .LBB0_666
	s_lshl_b32 s4, s5, 5
	s_cbranch_execz .LBB0_667
	s_branch .LBB0_668

.LBB0_754:
	s_or_b64 exec, exec, s[12:13]
.LBB0_755:
	s_or_b64 exec, exec, s[6:7]
	s_add_u32 s1, s52, 0x24000
	v_writelane_b32 v238, s1, 31
	s_addc_u32 s1, s53, 0
	v_writelane_b32 v238, s1, 32
	s_waitcnt lgkmcnt(0)
	v_readlane_b32 s2, v238, 22
	v_readlane_b32 s3, v238, 23
	s_and_b64 vcc, exec, s[2:3]
	s_barrier
	v_mbcnt_lo_u32_b32 v0, -1, 0
	v_mbcnt_hi_u32_b32 v0, -1, v0
	s_cbranch_vccnz .LBB0_762
	v_lshlrev_b32_e32 v56, 2, v0
	v_ashrrev_i32_e32 v57, 31, v56
	v_lshlrev_b64 v[0:1], 2, v[56:57]
	v_readlane_b32 s4, v239, 3
	v_lshl_add_u64 v[2:3], s[52:53], 0, v[0:1]
	s_mov_b64 s[2:3], 0x22000
	v_readlane_b32 s16, v239, 15
	v_readlane_b32 s17, v239, 16
	v_lshl_add_u64 v[60:61], v[2:3], 0, s[2:3]
	s_mov_b64 s[2:3], 0x4000
	v_lshl_add_u64 v[4:5], s[16:17], 0, v[0:1]
	v_lshl_add_u64 v[62:63], v[4:5], 0, s[2:3]
	s_mov_b64 s[2:3], 0x23000
	v_lshl_add_u64 v[64:65], v[2:3], 0, s[2:3]
	s_mov_b64 s[2:3], 0x23400
	v_lshl_add_u64 v[66:67], v[2:3], 0, s[2:3]
	s_mov_b64 s[2:3], 0x23800
	v_lshl_add_u64 v[68:69], v[2:3], 0, s[2:3]
	s_mov_b64 s[2:3], 0x23c00
	v_lshl_add_u64 v[70:71], v[2:3], 0, s[2:3]
	s_mov_b64 s[2:3], 0x5000
	v_readlane_b32 s12, v239, 11
	v_readlane_b32 s13, v239, 12
	v_readlane_b32 s14, v239, 13
	v_readlane_b32 s15, v239, 14
	v_readlane_b32 s18, v239, 17
	v_readlane_b32 s19, v239, 18
	v_lshl_add_u64 v[72:73], v[4:5], 0, s[2:3]
	s_mov_b64 s[2:3], 0x5400
	v_readlane_b32 s12, v239, 51
	v_lshl_add_u64 v[74:75], v[4:5], 0, s[2:3]
	s_mov_b64 s[2:3], 0x5800
	v_readlane_b32 s16, v239, 55
	v_readlane_b32 s17, v239, 56
	v_lshl_add_u64 v[76:77], v[4:5], 0, s[2:3]
	s_mov_b64 s[2:3], 0x5c00
	v_readlane_b32 s6, v239, 5
	v_readlane_b32 s7, v239, 6
	v_readlane_b32 s13, v239, 52
	s_cmp_lg_u64 s[16:17], 0
	v_lshl_add_u64 v[78:79], v[4:5], 0, s[2:3]
	v_readlane_b32 s2, v238, 6
	s_cselect_b64 s[6:7], -1, 0
	v_readlane_b32 s3, v238, 7
	s_mov_b32 s12, s2
	s_ashr_i32 s13, s2, 31
	s_lshl_b64 s[2:3], s[12:13], 13
	s_add_u32 s2, s56, s2
	s_addc_u32 s3, s57, s3
	v_lshl_add_u64 v[58:59], s[66:67], 0, v[0:1]
	v_lshl_add_u64 v[0:1], s[2:3], 0, v[0:1]
	s_mov_b64 s[2:3], 0x1000
	v_readlane_b32 s5, v239, 4
	v_lshl_add_u64 v[80:81], v[0:1], 0, s[2:3]
	v_readlane_b32 s2, v238, 3
	v_readlane_b32 s8, v239, 7
	v_readlane_b32 s9, v239, 8
	v_readlane_b32 s3, v238, 4
	s_mov_b32 s4, s2
	s_ashr_i32 s5, s2, 31
	s_lshl_b64 s[8:9], s[4:5], 13
	s_lshl_b64 s[2:3], s[12:13], 12
	s_add_u32 s2, s16, s2
	s_addc_u32 s3, s17, s3
	v_lshl_add_u64 v[0:1], v[56:57], 1, s[2:3]
	s_mov_b64 s[2:3], 0x800
	v_readlane_b32 s14, v239, 53
	v_readlane_b32 s15, v239, 54
	v_lshl_add_u64 v[82:83], v[0:1], 0, s[2:3]
	s_mov_b32 s2, s4
	v_readlane_b32 s25, v238, 0
	v_readlane_b32 s26, v238, 1
	v_readlane_b32 s27, v238, 2
	v_readlane_b32 s15, v238, 32
	v_readlane_b32 s14, v238, 31
	v_writelane_b32 v238, s2, 3
	v_readlane_b32 s10, v239, 9
	v_readlane_b32 s11, v239, 10
	v_writelane_b32 v238, s3, 4
	s_mov_b32 s2, s12
	v_writelane_b32 v238, s2, 6
	s_lshl_b64 s[10:11], s[4:5], 12
	s_mov_b32 s13, 0
	s_movk_i32 s1, 0x1000
	v_mov_b32_e32 v106, 0x358637bd
	v_writelane_b32 v238, s3, 7
	s_mov_b32 s2, s12
	v_readlane_b32 s18, v239, 57
	v_readlane_b32 s19, v239, 58
	v_readlane_b32 s20, v239, 59
	v_readlane_b32 s21, v239, 60
	v_readlane_b32 s22, v239, 61
	v_readlane_b32 s23, v239, 62
	v_readlane_b32 s24, v239, 63
	s_branch .LBB0_758

.LBB0_913:
	s_or_b64 exec, exec, s[12:13]
.LBB0_914:
	s_or_b64 exec, exec, s[6:7]
	v_readlane_b32 s2, v238, 17
	s_waitcnt lgkmcnt(0)
	s_barrier
	s_barrier
	v_mbcnt_lo_u32_b32 v0, -1, 0
	v_mbcnt_hi_u32_b32 v0, -1, v0
	v_readlane_b32 s1, v240, 44
	v_readlane_b32 s3, v238, 18
	s_andn2_b64 vcc, exec, s[2:3]
	s_waitcnt vmcnt(13)
	v_add_u32_e32 v8, s1, v0
	v_cndmask_b32_e64 v0, 0, 1, s[2:3]
	v_cmp_ne_u32_e64 s[6:7], 1, v0
	v_readfirstlane_b32 s1, v8
	s_nop 1
	v_writelane_b32 v238, s1, 33
	s_cbranch_vccnz .LBB0_916
	s_ashr_i32 s1, s84, 31
	s_lshr_b32 s1, s1, 29
	s_add_i32 s1, s84, s1
	s_ashr_i32 s2, s1, 3
	s_and_b32 s1, s1, -8
	s_sub_i32 s1, s84, s1
	s_cmp_lt_i32 s1, 0
	s_movk_i32 s3, 0x45
	s_cselect_b32 s3, s3, 0x44
	s_mul_i32 s1, s3, s1
	s_add_i32 s1, s1, s2
	s_mul_hi_i32 s2, s1, 0x78787879
	s_lshr_b32 s3, s2, 31
	s_ashr_i32 s2, s2, 6
	s_add_i32 s2, s2, s3
	s_lshl_b32 s3, s2, 3
	s_mulk_i32 s2, 0x88
	s_sub_i32 s1, s1, s2
	s_sext_i32_i16 s2, s1
	s_bfe_u32 s2, s2, 0x3001c
	s_add_i32 s2, s1, s2
	s_sext_i32_i16 s4, s2
	s_and_b32 s2, s2, 0xfff8
	s_sub_i32 s1, s1, s2
	s_sext_i32_i16 s1, s1
	s_add_i32 s16, s3, s1
	s_ashr_i32 s8, s4, 3

.LBB0_1545:
	s_or_b64 exec, exec, s[12:13]
.LBB0_1546:
	s_or_b64 exec, exec, s[6:7]
	v_readlane_b32 s1, v240, 44
	s_waitcnt lgkmcnt(0)
	s_barrier
	v_mbcnt_lo_u32_b32 v0, -1, 0
	v_mbcnt_hi_u32_b32 v0, -1, v0
	s_cmpk_gt_i32 s84, 0x7ff
	s_waitcnt vmcnt(7)
	v_add_u32_e32 v35, s1, v0
	s_movk_i32 s43, 0x7ff
	s_barrier
	s_cbranch_scc1 .LBB0_1695
	v_readlane_b32 s2, v239, 1
	s_cmp_lt_u32 s2, s33
	s_cselect_b32 s1, 12, 18
	v_readlane_b32 s4, v240, 47
	s_mov_b32 s20, 0
	v_readlane_b32 s5, v240, 48
	s_add_u32 s44, s4, s1
	s_mov_b32 s26, 0x3f6c835e
	s_mov_b32 s30, 0x3f3504f3
	s_mov_b32 s38, 0.5
	s_mov_b32 s21, -1.0
	s_addc_u32 s45, s5, 0
	s_movk_i32 s68, 0x800
	s_movk_i32 s69, 0x1000
	s_movk_i32 s70, 0x200
	s_movk_i32 s71, 0x400
	s_movk_i32 s72, 0x600
	s_movk_i32 s73, 0x2000
	s_movk_i32 s74, 0xa00
	s_movk_i32 s75, 0xc00
	s_movk_i32 s94, 0x3000
	s_movk_i32 s95, 0xe00
	s_mov_b64 s[48:49], 0x4000
	s_movk_i32 s1, 0x4000
	s_add_i32 s3, 0, 0x11000
	s_waitcnt vmcnt(6)
	v_mov_b32_e32 v39, 0
	s_waitcnt vmcnt(5)
	v_mov_b32_e32 v43, 0x2000
	s_movk_i32 s24, 0x5000
	s_movk_i32 s46, 0x6000
	s_movk_i32 s47, 0x7000
	s_mov_b32 s27, 0xbec3ef15
	s_mov_b32 s28, 0x3ec3ef15
	s_mov_b32 s31, 0xbf3504f3
	s_mov_b32 s34, 0xbf6c835e
	s_mov_b32 s36, 1.0
	s_movk_i32 s50, 0xf000
	s_waitcnt vmcnt(4)
	v_mov_b32_e32 v47, 0x6000
	s_waitcnt vmcnt(3)
	v_mov_b32_e32 v51, 0xc000
	s_movk_i32 s51, 0xfff
	s_movk_i32 s25, 0x1ff
	s_movk_i32 s22, 0x1dff
	s_waitcnt vmcnt(2)
	v_mov_b32_e32 v55, 0x8000
	v_mov_b32_e32 v118, 0xe000
	s_mov_b32 s39, -0.5
	v_mov_b32_e32 v119, 0x4000
	v_mov_b32_e32 v120, 0xa000
	v_mov_b32_e32 v121, 0x10000
	s_mov_b32 s40, s2
	s_branch .LBB0_1549

.LBB0_1753:
	s_or_b64 exec, exec, s[12:13]
.LBB0_1754:
	s_or_b64 exec, exec, s[6:7]
	v_readlane_b32 s2, v238, 11
	v_readlane_b32 s6, v238, 17
	v_readlane_b32 s3, v238, 12
	v_readlane_b32 s7, v238, 18
	v_readlane_b32 s5, v240, 44
	s_and_b64 s[2:3], s[6:7], s[2:3]
	s_waitcnt lgkmcnt(0)
	s_barrier
	v_mbcnt_lo_u32_b32 v0, -1, 0
	v_mbcnt_hi_u32_b32 v0, -1, v0
	s_andn2_b64 vcc, exec, s[2:3]
	v_add_u32_e32 v64, s5, v0
	s_cbranch_vccnz .LBB0_1778
	s_mul_i32 s1, s94, 0xf0f1
	s_lshr_b32 s1, s1, 20
	s_lshl_b32 s4, s1, 6
	s_mul_i32 s1, s1, 17
	s_sub_i32 s1, s94, s1
	s_lshl_b32 s1, s1, 9
	v_lshlrev_b32_e32 v0, 2, v64
	v_ashrrev_i32_e32 v72, 7, v64
	s_and_b32 s1, s1, 0xfe00
	v_and_b32_e32 v73, 0x1fc, v0
	v_or_b32_e32 v2, s1, v73
	v_add_u32_e32 v74, 4, v72
	v_add_u32_e32 v75, 8, v72
	v_add_u32_e32 v76, 12, v72
	v_add_u32_e32 v77, 16, v72
	v_add_u32_e32 v78, 20, v72
	v_add_u32_e32 v79, 24, v72
	v_add_u32_e32 v80, 28, v72
	v_add_u32_e32 v81, 32, v72
	v_add_u32_e32 v82, 36, v72
	v_add_u32_e32 v83, 40, v72
	v_add_u32_e32 v84, 44, v72
	v_add_u32_e32 v85, 48, v72
	v_add_u32_e32 v86, 52, v72
	v_add_u32_e32 v87, 56, v72
	v_add_u32_e32 v88, 60, v72
	v_add_u32_e32 v0, s4, v72
	s_mov_b32 s1, 0x8800
	s_waitcnt vmcnt(1)
	v_mov_b64_e32 v[56:57], s[66:67]
	v_lshlrev_b32_e32 v66, 2, v2
	v_add_u32_e32 v2, s4, v74
	v_add_u32_e32 v8, s4, v75
	v_add_u32_e32 v10, s4, v76
	v_add_u32_e32 v16, s4, v77
	v_add_u32_e32 v18, s4, v78
	v_add_u32_e32 v24, s4, v79
	v_add_u32_e32 v26, s4, v80
	v_add_u32_e32 v32, s4, v81
	v_add_u32_e32 v34, s4, v82
	v_add_u32_e32 v40, s4, v83
	v_add_u32_e32 v42, s4, v84
	v_add_u32_e32 v48, s4, v85
	v_add_u32_e32 v50, s4, v86
	v_add_u32_e32 v58, s4, v87
	s_waitcnt vmcnt(0)
	v_add_u32_e32 v60, s4, v88
	v_mad_i64_i32 v[0:1], s[2:3], v0, s1, v[56:57]
	v_mov_b32_e32 v67, 0
	v_mad_i64_i32 v[2:3], s[2:3], v2, s1, v[56:57]
	v_mad_i64_i32 v[8:9], s[2:3], v8, s1, v[56:57]
	v_mad_i64_i32 v[10:11], s[2:3], v10, s1, v[56:57]
	v_mad_i64_i32 v[16:17], s[2:3], v16, s1, v[56:57]
	v_mad_i64_i32 v[18:19], s[2:3], v18, s1, v[56:57]
	v_mad_i64_i32 v[24:25], s[2:3], v24, s1, v[56:57]
	v_mad_i64_i32 v[26:27], s[2:3], v26, s1, v[56:57]
	v_mad_i64_i32 v[32:33], s[2:3], v32, s1, v[56:57]
	v_mad_i64_i32 v[34:35], s[2:3], v34, s1, v[56:57]
	v_mad_i64_i32 v[40:41], s[2:3], v40, s1, v[56:57]
	v_mad_i64_i32 v[42:43], s[2:3], v42, s1, v[56:57]
	v_mad_i64_i32 v[48:49], s[2:3], v48, s1, v[56:57]
	v_mad_i64_i32 v[50:51], s[2:3], v50, s1, v[56:57]
	v_mad_i64_i32 v[58:59], s[2:3], v58, s1, v[56:57]
	v_mad_i64_i32 v[56:57], s[2:3], v60, s1, v[56:57]
	v_lshl_add_u64 v[0:1], v[0:1], 0, v[66:67]
	v_lshl_add_u64 v[4:5], v[2:3], 0, v[66:67]
	v_lshl_add_u64 v[8:9], v[8:9], 0, v[66:67]
	v_lshl_add_u64 v[12:13], v[10:11], 0, v[66:67]
	v_lshl_add_u64 v[16:17], v[16:17], 0, v[66:67]
	v_lshl_add_u64 v[20:21], v[18:19], 0, v[66:67]
	v_lshl_add_u64 v[24:25], v[24:25], 0, v[66:67]
	v_lshl_add_u64 v[28:29], v[26:27], 0, v[66:67]
	v_lshl_add_u64 v[32:33], v[32:33], 0, v[66:67]
	v_lshl_add_u64 v[36:37], v[34:35], 0, v[66:67]
	v_lshl_add_u64 v[40:41], v[40:41], 0, v[66:67]
	v_lshl_add_u64 v[44:45], v[42:43], 0, v[66:67]
	v_lshl_add_u64 v[48:49], v[48:49], 0, v[66:67]
	v_lshl_add_u64 v[52:53], v[50:51], 0, v[66:67]
	v_lshl_add_u64 v[58:59], v[58:59], 0, v[66:67]
	v_lshl_add_u64 v[60:61], v[56:57], 0, v[66:67]
	global_load_dwordx4 v[0:3], v[0:1], off
	s_nop 0
	global_load_dwordx4 v[4:7], v[4:5], off
	s_nop 0
	global_load_dwordx4 v[8:11], v[8:9], off
	s_nop 0
	global_load_dwordx4 v[12:15], v[12:13], off
	s_nop 0
	global_load_dwordx4 v[16:19], v[16:17], off
	s_nop 0
	global_load_dwordx4 v[20:23], v[20:21], off
	s_nop 0
	global_load_dwordx4 v[24:27], v[24:25], off
	s_nop 0
	global_load_dwordx4 v[28:31], v[28:29], off
	s_nop 0
	global_load_dwordx4 v[32:35], v[32:33], off
	s_nop 0
	global_load_dwordx4 v[36:39], v[36:37], off
	s_nop 0
	global_load_dwordx4 v[40:43], v[40:41], off
	s_nop 0
	global_load_dwordx4 v[44:47], v[44:45], off
	s_nop 0
	global_load_dwordx4 v[48:51], v[48:49], off
	s_nop 0
	global_load_dwordx4 v[52:55], v[52:53], off
	s_nop 0
	global_load_dwordx4 v[56:59], v[58:59], off
	s_nop 0
	global_load_dwordx4 v[60:63], v[60:61], off
	v_readlane_b32 s3, v238, 5
	v_bfe_u32 v68, v64, 5, 1
	v_lshlrev_b32_e32 v64, 1, v64
	s_lshl_b32 s3, s3, 8
	v_and_b32_e32 v69, 62, v64
	v_readlane_b32 s8, v239, 51
	s_movk_i32 s2, 0x810
	v_mov_b32_e32 v71, s3
	v_lshlrev_b32_e32 v66, 1, v69
	v_readlane_b32 s14, v239, 57
	v_readlane_b32 s15, v239, 58
	v_mul_lo_u32 v90, v72, s2
	v_mad_u32_u24 v69, v69, s2, v71
	v_lshl_add_u32 v89, v73, 2, 0
	v_lshl_add_u64 v[64:65], s[14:15], 0, v[66:67]
	v_add_u32_e32 v66, 0xc180, v90
	v_add_u32_e32 v67, 0xe1c0, v90
	v_add_u32_e32 v70, 0x10200, v90
	v_add_u32_e32 v91, s5, v68
	v_lshl_or_b32 v68, v68, 2, v69
	v_readlane_b32 s9, v239, 52
	v_readlane_b32 s10, v239, 53
	v_readlane_b32 s11, v239, 54
	v_readlane_b32 s12, v239, 55
	v_readlane_b32 s13, v239, 56
	v_readlane_b32 s16, v239, 59
	v_readlane_b32 s17, v239, 60
	v_readlane_b32 s18, v239, 61
	v_readlane_b32 s19, v239, 62
	v_readlane_b32 s20, v239, 63
	v_readlane_b32 s21, v238, 0
	v_readlane_b32 s22, v238, 1
	v_readlane_b32 s23, v238, 2
	v_add_u32_e32 v92, 0, v68
	v_add_u32_e32 v93, v89, v66
	v_add_u32_e32 v94, v89, v67
	v_add_u32_e32 v95, v89, v70
	s_movk_i32 s2, 0x2200
	s_mov_b32 s4, s94
	s_branch .LBB0_1757

.LBB0_1829:
	s_or_b64 exec, exec, s[12:13]
.LBB0_1830:
	s_or_b64 exec, exec, s[6:7]
	v_readlane_b32 s1, v240, 44
	v_readlane_b32 s2, v238, 19
	s_waitcnt lgkmcnt(0)
	s_barrier
	s_barrier
	v_mbcnt_lo_u32_b32 v0, -1, 0
	v_mbcnt_hi_u32_b32 v0, -1, v0
	v_readlane_b32 s3, v238, 20
	s_waitcnt vmcnt(11)
	v_add_u32_e32 v16, s1, v0
	s_and_b64 vcc, exec, s[2:3]
	v_readfirstlane_b32 s1, v16
	s_cbranch_vccnz .LBB0_1858
	s_ashr_i32 s2, s94, 31
	s_lshr_b32 s3, s2, 29
	s_add_i32 s3, s94, s3
	s_and_b32 s4, s3, -8
	s_sub_i32 s5, s94, s4
	s_cmp_gt_i32 s5, -1
	s_cbranch_scc0 .LBB0_1833
	s_lshl_b32 s4, s5, 5
	s_cbranch_execz .LBB0_1834
	s_branch .LBB0_1835

.LBB0_1921:
	s_or_b64 exec, exec, s[12:13]
.LBB0_1922:
	s_or_b64 exec, exec, s[6:7]
	v_readlane_b32 s2, v238, 22
	v_readlane_b32 s3, v238, 23
	s_and_b64 vcc, exec, s[2:3]
	s_waitcnt lgkmcnt(0)
	s_barrier
	v_mbcnt_lo_u32_b32 v0, -1, 0
	v_mbcnt_hi_u32_b32 v0, -1, v0
	s_cbranch_vccnz .LBB0_1946
	v_lshlrev_b32_e32 v54, 2, v0
	v_ashrrev_i32_e32 v55, 31, v54
	v_readlane_b32 s4, v239, 35
	v_lshlrev_b64 v[0:1], 2, v[54:55]
	v_readlane_b32 s5, v239, 36
	v_readlane_b32 s6, v239, 37
	v_readlane_b32 s7, v239, 38
	v_readlane_b32 s10, v239, 41
	v_readlane_b32 s11, v239, 42
	s_mov_b64 s[6:7], s[10:11]
	v_lshl_add_u64 v[2:3], s[52:53], 0, v[0:1]
	s_mov_b64 s[4:5], 0x41000
	v_lshl_add_u64 v[60:61], s[6:7], 0, v[0:1]
	v_lshl_add_u64 v[66:67], v[2:3], 0, s[4:5]
	s_mov_b64 s[4:5], 0x1400
	v_readlane_b32 s8, v239, 39
	v_readlane_b32 s9, v239, 40
	v_readlane_b32 s12, v239, 43
	v_readlane_b32 s13, v239, 44
	v_readlane_b32 s14, v239, 45
	v_readlane_b32 s15, v239, 46
	v_lshl_add_u64 v[68:69], v[60:61], 0, s[4:5]
	s_mov_b64 s[4:5], 0x41400
	v_readlane_b32 s16, v239, 47
	v_readlane_b32 s17, v239, 48
	v_readlane_b32 s18, v239, 49
	v_readlane_b32 s19, v239, 50
	s_mov_b64 s[8:9], s[12:13]
	v_lshl_add_u64 v[70:71], v[2:3], 0, s[4:5]
	s_mov_b64 s[4:5], 0x1800
	s_mov_b64 s[10:11], s[14:15]
	s_mov_b64 s[12:13], s[16:17]
	s_mov_b64 s[14:15], s[18:19]
	v_lshl_add_u64 v[72:73], v[60:61], 0, s[4:5]
	s_mov_b64 s[4:5], 0x41800
	v_readlane_b32 s12, v239, 3
	v_lshl_add_u64 v[74:75], v[2:3], 0, s[4:5]
	s_mov_b64 s[4:5], 0x1c00
	v_readlane_b32 s24, v239, 15
	v_readlane_b32 s25, v239, 16
	v_lshl_add_u64 v[76:77], v[60:61], 0, s[4:5]
	s_mov_b64 s[4:5], 0x41c00
	v_lshl_add_u64 v[4:5], s[24:25], 0, v[0:1]
	v_lshl_add_u64 v[78:79], v[2:3], 0, s[4:5]
	s_mov_b64 s[4:5], 0x7000
	v_readlane_b32 s13, v239, 4
	v_readlane_b32 s14, v239, 5
	v_readlane_b32 s15, v239, 6
	v_readlane_b32 s16, v239, 7
	v_readlane_b32 s17, v239, 8
	v_readlane_b32 s18, v239, 9
	v_readlane_b32 s19, v239, 10
	v_readlane_b32 s20, v239, 11
	v_readlane_b32 s21, v239, 12
	v_readlane_b32 s22, v239, 13
	v_readlane_b32 s23, v239, 14
	v_readlane_b32 s26, v239, 17
	v_readlane_b32 s27, v239, 18
	v_lshl_add_u64 v[80:81], v[4:5], 0, s[4:5]
	s_mov_b64 s[4:5], 0x7400
	v_readlane_b32 s12, v239, 51
	v_lshl_add_u64 v[82:83], v[4:5], 0, s[4:5]
	s_mov_b64 s[4:5], 0x7800
	s_cmp_lg_u64 s[6:7], 0
	v_readlane_b32 s16, v239, 55
	v_readlane_b32 s17, v239, 56
	v_lshl_add_u64 v[84:85], v[4:5], 0, s[4:5]
	s_mov_b64 s[4:5], 0x7c00
	s_cselect_b64 s[8:9], -1, 0
	v_readlane_b32 s13, v239, 52
	s_cmp_lg_u64 s[16:17], 0
	v_lshl_add_u64 v[86:87], v[4:5], 0, s[4:5]
	v_readlane_b32 s4, v238, 6
	s_cselect_b64 s[12:13], -1, 0
	v_readlane_b32 s5, v238, 7
	s_mov_b32 s6, s4
	s_ashr_i32 s7, s4, 31
	s_lshl_b64 s[4:5], s[6:7], 13
	s_add_u32 s4, s56, s4
	s_mov_b64 s[2:3], 0x40000
	s_addc_u32 s5, s57, s5
	v_lshl_add_u64 v[56:57], s[66:67], 0, v[0:1]
	v_lshl_add_u64 v[58:59], v[2:3], 0, s[2:3]
	v_readlane_b32 s14, v239, 53
	v_readlane_b32 s15, v239, 54
	s_mov_b64 s[2:3], 0x1000
	v_lshl_add_u64 v[0:1], s[4:5], 0, v[0:1]
	s_ashr_i32 s91, s90, 31
	v_lshl_add_u64 v[64:65], v[60:61], 0, s[2:3]
	v_lshl_add_u64 v[88:89], v[0:1], 0, s[2:3]
	s_lshl_b64 s[14:15], s[90:91], 13
	s_lshl_b64 s[2:3], s[6:7], 12
	s_add_u32 s2, s16, s2
	s_addc_u32 s3, s17, s3
	v_lshl_add_u64 v[0:1], v[54:55], 1, s[2:3]
	s_mov_b64 s[2:3], 0x800
	v_lshl_add_u64 v[90:91], v[0:1], 0, s[2:3]
	s_mov_b32 s2, s6
	v_readlane_b32 s25, v238, 0
	v_readlane_b32 s26, v238, 1
	v_readlane_b32 s27, v238, 2
	v_writelane_b32 v238, s2, 6
	s_mov_b64 s[10:11], 0x6000
	v_readlane_b32 s19, v239, 58
	v_writelane_b32 v238, s3, 7
	v_lshl_add_u64 v[62:63], v[4:5], 0, s[10:11]
	s_lshl_b64 s[16:17], s[90:91], 12
	s_mov_b32 s19, 0
	v_mov_b32_e32 v96, 0x358637bd
	s_mov_b32 s1, s6
	v_readlane_b32 s4, v238, 31
	v_readlane_b32 s5, v238, 32
	v_readlane_b32 s18, v239, 57
	v_readlane_b32 s20, v239, 59
	v_readlane_b32 s21, v239, 60
	v_readlane_b32 s22, v239, 61
	v_readlane_b32 s23, v239, 62
	v_readlane_b32 s24, v239, 63
	s_branch .LBB0_1925

.LBB0_1997:
	s_or_b64 exec, exec, s[12:13]
.LBB0_1998:
	s_or_b64 exec, exec, s[6:7]
	v_readlane_b32 s2, v238, 24
	s_waitcnt lgkmcnt(0)
	s_barrier
	s_barrier
	v_mbcnt_lo_u32_b32 v0, -1, 0
	v_mbcnt_hi_u32_b32 v0, -1, v0
	v_readlane_b32 s1, v240, 44
	v_readlane_b32 s3, v238, 25
	s_andn2_b64 vcc, exec, s[2:3]
	v_add_u32_e32 v16, s1, v0
	v_cndmask_b32_e64 v0, 0, 1, s[2:3]
	v_cmp_ne_u32_e64 s[8:9], 1, v0
	v_readfirstlane_b32 s1, v16
	s_cbranch_vccnz .LBB0_2010
	v_lshlrev_b32_e32 v0, 4, v16
	v_add_u32_e32 v1, 0x2000, v0
	v_ashrrev_i32_e32 v2, 31, v1
	v_lshrrev_b32_e32 v2, 22, v2
	v_add_u32_e32 v2, v1, v2
	v_ashrrev_i32_e32 v8, 10, v2
	v_mul_i32_i24_e32 v2, 0x400, v8
	v_sub_u32_e32 v1, v1, v2
	v_lshrrev_b32_e32 v2, 4, v1
	v_bitop3_b32 v1, v2, v1, 32 bitop3:0x6c
	v_ashrrev_i32_e32 v2, 31, v1
	v_lshrrev_b32_e32 v2, 26, v2
	v_add_u32_e32 v2, v1, v2
	v_ashrrev_i32_e32 v9, 6, v2
	v_and_b32_e32 v2, 0xc0, v2
	s_ashr_i32 s3, s94, 31
	v_sub_u32_e32 v1, v1, v2
	v_mov_b32_e32 v2, 1
	s_lshr_b32 s4, s3, 29
	v_ashrrev_i16_sdwa v1, v2, sext(v1) dst_sel:DWORD dst_unused:UNUSED_PAD src0_sel:DWORD src1_sel:BYTE_0
	s_add_i32 s4, s94, s4
	s_ashr_i32 s10, s1, 6
	v_bfe_i32 v11, v1, 0, 16
	v_bfe_i32 v1, v16, 27, 1
	s_ashr_i32 s5, s4, 3
	s_and_b32 s4, s4, -8
	s_ashr_i32 s7, s1, 8
	s_lshl_b32 s2, s10, 10
	v_lshrrev_b32_e32 v1, 22, v1
	s_sub_i32 s6, s94, s4
	v_add_u32_e32 v1, v0, v1
	s_cmp_lt_i32 s6, 0
	s_movk_i32 s4, 0xbc
	v_and_b32_e32 v1, 0xfffffc00, v1
	s_cselect_b32 s11, s4, 0xbb
	v_sub_u32_e32 v0, v0, v1
	s_mul_i32 s6, s11, s6
	v_lshrrev_b32_e32 v1, 4, v0
	s_add_i32 s6, s6, s5
	v_bitop3_b32 v0, v1, v0, 32 bitop3:0x6c
	s_mul_hi_i32 s5, s6, 0x2e8ba2e9
	v_ashrrev_i32_e32 v1, 31, v0
	s_lshr_b32 s11, s5, 31
	s_ashr_i32 s5, s5, 6
	v_lshrrev_b32_e32 v1, 26, v1
	s_add_i32 s5, s5, s11
	v_add_u32_e32 v1, v0, v1
	s_lshl_b32 s11, s5, 3
	v_ashrrev_i32_e32 v12, 6, v1
	v_and_b32_e32 v1, 0xc0, v1
	s_sub_i32 s12, 34, s11
	s_mulk_i32 s5, 0x160
	v_sub_u32_e32 v0, v0, v1
	s_min_u32 s14, s12, 8
	s_sub_i32 s5, s6, s5
	v_ashrrev_i16_sdwa v0, v2, sext(v0) dst_sel:DWORD dst_unused:UNUSED_PAD src0_sel:DWORD src1_sel:BYTE_0
	s_sext_i32_i16 s6, s5
	v_cvt_f32_ubyte0_e32 v1, s14
	v_bfe_i32 v15, v0, 0, 16
	v_cvt_f32_i32_e32 v0, s6
	v_rcp_iflag_f32_e32 v2, v1
	s_ashr_i32 s6, s6, 30
	v_lshlrev_b32_e32 v3, 3, v8
	s_or_b32 s6, s6, 1
	v_mul_f32_e32 v2, v0, v2
	v_trunc_f32_e32 v2, v2
	v_fma_f32 v0, -v2, v1, v0
	v_cvt_i32_f32_e32 v2, v2
	v_cmp_ge_f32_e64 s[12:13], |v0|, v1
	v_and_b32_e32 v3, 0xffff0, v3
	v_lshlrev_b32_e32 v4, 5, v8
	s_and_b64 s[12:13], s[12:13], exec
	v_add_u32_e32 v3, v9, v3
	v_and_b32_e32 v10, 32, v4
	s_cselect_b32 s6, s6, 0
	v_readfirstlane_b32 s12, v2
	v_lshl_or_b32 v3, v3, 11, v10
	s_add_i32 s6, s12, s6
	v_add_lshl_u32 v128, v3, v11, 1
	v_ashrrev_i32_e32 v3, 31, v16
	s_mul_i32 s12, s6, s14
	v_lshrrev_b32_e32 v3, 26, v3
	s_sub_i32 s5, s5, s12
	v_add_u32_e32 v3, v16, v3
	s_sext_i32_i16 s5, s5
	v_ashrrev_i32_e32 v13, 6, v3
	s_add_i32 s20, s11, s5
	v_lshlrev_b32_e32 v3, 3, v13
	s_ashr_i32 s21, s20, 31
	s_bfe_i64 s[14:15], s[6:7], 0x100000
	v_readlane_b32 s36, v239, 51
	v_and_b32_e32 v3, 0xffff0, v3
	v_lshlrev_b32_e32 v4, 5, v13
	s_lshl_b64 s[12:13], s[20:21], 20
	s_lshl_b64 s[14:15], s[14:15], 20
	v_readlane_b32 s44, v239, 59
	v_add_u32_e32 v3, v12, v3
	v_and_b32_e32 v14, 32, v4
	v_readlane_b32 s45, v239, 60
	s_add_u32 s24, s44, s14
	v_lshl_or_b32 v3, v3, 11, v14
	s_addc_u32 s25, s45, s15
	s_add_i32 s5, s2, 0
	v_add_lshl_u32 v130, v3, v15, 1
	s_add_i32 m0, s5, 0x10000
	v_readlane_b32 s40, v239, 55
	global_load_lds_dwordx4 v130, s[24:25]
	s_add_i32 m0, s5, 0x12000
	v_readlane_b32 s41, v239, 56
	s_add_u32 s22, s40, s12
	global_load_lds_dwordx4 v128, s[24:25]
	s_addc_u32 s23, s41, s13
	s_mov_b32 m0, s5
	s_add_i32 s30, s5, 0x2000
	global_load_lds_dwordx4 v130, s[22:23]
	s_mov_b32 m0, s30
	s_add_u32 s12, s24, 0x80000
	global_load_lds_dwordx4 v128, s[22:23]
	s_addc_u32 s13, s25, 0
	s_add_i32 m0, s5, 0x14000
	v_mov_b32_e32 v131, 0
	global_load_lds_dwordx4 v130, s[12:13]
	s_add_i32 m0, s5, 0x16000
	v_mov_b32_e32 v129, v131
	global_load_lds_dwordx4 v128, s[12:13]
	s_add_u32 s12, s22, 0x80000
	s_addc_u32 s13, s23, 0
	s_add_i32 s31, s5, 0x4000
	s_mov_b32 m0, s31
	s_add_i32 s34, s5, 0x6000
	global_load_lds_dwordx4 v130, s[12:13]
	s_mov_b32 m0, s34
	s_mov_b32 s35, 0
	global_load_lds_dwordx4 v128, s[12:13]
	v_lshl_add_u64 v[6:7], s[24:25], 0, v[130:131]
	v_lshl_add_u64 v[4:5], s[24:25], 0, v[128:129]
	v_lshl_add_u64 v[2:3], s[22:23], 0, v[130:131]
	s_cmp_lg_u32 s7, 1
	v_lshl_add_u64 v[0:1], s[22:23], 0, v[128:129]
	v_readlane_b32 s37, v239, 52
	v_readlane_b32 s38, v239, 53
	v_readlane_b32 s39, v239, 54
	v_readlane_b32 s42, v239, 57
	v_readlane_b32 s43, v239, 58
	v_readlane_b32 s46, v239, 61
	v_readlane_b32 s47, v239, 62
	v_readlane_b32 s48, v239, 63
	v_readlane_b32 s49, v238, 0
	v_readlane_b32 s50, v238, 1
	v_readlane_b32 s51, v238, 2
	s_cbranch_scc1 .LBB0_2001
	s_barrier

.LBB0_2028:
	s_or_b64 exec, exec, s[14:15]
	v_cvt_f32_u32_e32 v4, v2
	s_waitcnt vmcnt(0)
	v_readfirstlane_b32 s1, v3
	v_sub_u32_e32 v3, 0, v2
	v_rcp_iflag_f32_e32 v4, v4
	v_add_u32_e32 v5, s1, v1
	v_mul_f32_e32 v4, 0x4f7ffffe, v4
	v_cvt_u32_f32_e32 v4, v4
	v_mul_lo_u32 v1, v3, v4
	v_mul_hi_u32 v1, v4, v1
	v_add_u32_e32 v1, v4, v1
	v_mul_hi_u32 v1, v5, v1
	v_mul_lo_u32 v3, v1, v2
	v_sub_u32_e32 v3, v5, v3
	v_add_u32_e32 v4, 1, v1
	v_cmp_ge_u32_e32 vcc, v3, v2
	s_nop 1
	v_cndmask_b32_e32 v1, v1, v4, vcc
	v_sub_u32_e32 v4, v3, v2
	v_cndmask_b32_e32 v3, v3, v4, vcc
	v_add_u32_e32 v4, 1, v1
	v_cmp_ge_u32_e32 vcc, v3, v2
	v_add_u32_e32 v3, 1, v5
	s_nop 0
	v_cndmask_b32_e32 v1, v1, v4, vcc
	v_mul_lo_u32 v4, v2, v1
	v_add_u32_e32 v2, v4, v2
	v_cmp_ne_u32_e32 vcc, v3, v2
	s_and_saveexec_b64 s[2:3], vcc
	s_xor_b64 s[12:13], exec, s[2:3]
	s_cbranch_execz .LBB0_2042
	s_waitcnt lgkmcnt(0)
	v_mov_b32_e32 v0, 0x3500
	global_load_dword v0, v0, s[96:97] sc1
	s_add_u32 s16, s96, 0x3500
	s_addc_u32 s17, s97, 0
	s_waitcnt vmcnt(0)
	v_cmp_eq_u32_e32 vcc, v0, v1
	s_and_saveexec_b64 s[14:15], vcc
	s_cbranch_execz .LBB0_2041
	s_mov_b32 s1, 1
	s_mov_b64 s[18:19], 0
	v_mov_b32_e32 v0, 0
	s_branch .LBB0_2032

.LBB0_2059:
	s_or_b64 exec, exec, s[12:13]
	s_mov_b64 s[12:13], exec
	v_mbcnt_lo_u32_b32 v0, s12, 0
	v_mbcnt_hi_u32_b32 v0, s13, v0
	v_cmp_eq_u32_e32 vcc, 0, v0
	s_and_saveexec_b64 s[14:15], vcc
	s_cbranch_execz .LBB0_2061
	s_bcnt1_i32_b64 s1, s[12:13]
	v_mov_b32_e32 v0, 0x2000
	v_mov_b32_e32 v1, s1
.LBB0_2061:
	s_or_b64 exec, exec, s[14:15]
.LBB0_2062:
	s_or_b64 exec, exec, s[6:7]
	v_readlane_b32 s1, v240, 44
	v_readlane_b32 s2, v238, 19
	s_waitcnt lgkmcnt(0)
	s_barrier
	s_barrier
	v_mbcnt_lo_u32_b32 v0, -1, 0
	v_mbcnt_hi_u32_b32 v0, -1, v0
	v_readlane_b32 s3, v238, 20
	v_add_u32_e32 v16, s1, v0
	s_and_b64 vcc, exec, s[2:3]
	v_readfirstlane_b32 s1, v16
	s_cbranch_vccnz .LBB0_2086
	s_ashr_i32 s2, s94, 31
	s_lshr_b32 s3, s2, 29
	s_add_i32 s3, s94, s3
	s_and_b32 s4, s3, -8
	s_sub_i32 s5, s94, s4
	s_cmp_gt_i32 s5, -1
	s_cbranch_scc0 .LBB0_2065
	s_lshl_b32 s4, s5, 5
	s_cbranch_execz .LBB0_2066
	s_branch .LBB0_2067

.LBB0_2120:
	s_or_b64 exec, exec, s[16:17]
	v_cvt_f32_u32_e32 v4, v2
	s_waitcnt vmcnt(0)
	v_readfirstlane_b32 s1, v3
	v_sub_u32_e32 v3, 0, v2
	v_rcp_iflag_f32_e32 v4, v4
	v_add_u32_e32 v5, s1, v1
	v_mul_f32_e32 v4, 0x4f7ffffe, v4
	v_cvt_u32_f32_e32 v4, v4
	v_mul_lo_u32 v1, v3, v4
	v_mul_hi_u32 v1, v4, v1
	v_add_u32_e32 v1, v4, v1
	v_mul_hi_u32 v1, v5, v1
	v_mul_lo_u32 v3, v1, v2
	v_sub_u32_e32 v3, v5, v3
	v_add_u32_e32 v4, 1, v1
	v_cmp_ge_u32_e32 vcc, v3, v2
	s_nop 1
	v_cndmask_b32_e32 v1, v1, v4, vcc
	v_sub_u32_e32 v4, v3, v2
	v_cndmask_b32_e32 v3, v3, v4, vcc
	v_add_u32_e32 v4, 1, v1
	v_cmp_ge_u32_e32 vcc, v3, v2
	v_add_u32_e32 v3, 1, v5
	s_nop 0
	v_cndmask_b32_e32 v1, v1, v4, vcc
	v_mul_lo_u32 v4, v2, v1
	v_add_u32_e32 v2, v4, v2
	v_cmp_ne_u32_e32 vcc, v3, v2
	s_and_saveexec_b64 s[2:3], vcc
	s_xor_b64 s[14:15], exec, s[2:3]
	s_cbranch_execz .LBB0_2134
	s_waitcnt lgkmcnt(0)
	v_mov_b32_e32 v0, 0x3500
	global_load_dword v0, v0, s[96:97] sc1
	s_add_u32 s18, s96, 0x3500
	s_addc_u32 s19, s97, 0
	s_waitcnt vmcnt(0)
	v_cmp_eq_u32_e32 vcc, v0, v1
	s_and_saveexec_b64 s[16:17], vcc
	s_cbranch_execz .LBB0_2133
	s_mov_b32 s1, 1
	s_mov_b64 s[20:21], 0
	v_mov_b32_e32 v0, 0
	s_branch .LBB0_2124

.LBB0_2151:
	s_or_b64 exec, exec, s[14:15]
	s_mov_b64 s[14:15], exec
	v_mbcnt_lo_u32_b32 v0, s14, 0
	v_mbcnt_hi_u32_b32 v0, s15, v0
	v_cmp_eq_u32_e32 vcc, 0, v0
	s_and_saveexec_b64 s[16:17], vcc
	s_cbranch_execz .LBB0_2153
	s_bcnt1_i32_b64 s1, s[14:15]
	v_mov_b32_e32 v0, 0x2000
	v_mov_b32_e32 v1, s1
.LBB0_2153:
	s_or_b64 exec, exec, s[16:17]
.LBB0_2154:
	s_or_b64 exec, exec, s[10:11]
	v_readlane_b32 s2, v238, 22
	s_add_u32 s6, s52, 0x48000
	v_readlane_b32 s3, v238, 23
	s_addc_u32 s7, s53, 0
	s_and_b64 vcc, exec, s[2:3]
	s_waitcnt lgkmcnt(0)
	s_barrier
	v_mbcnt_lo_u32_b32 v0, -1, 0
	v_mbcnt_hi_u32_b32 v0, -1, v0
	s_cbranch_vccnz .LBB0_2162
	v_lshlrev_b32_e32 v56, 2, v0
	v_ashrrev_i32_e32 v57, 31, v56
	v_lshlrev_b64 v[0:1], 2, v[56:57]
	v_readlane_b32 s12, v239, 3
	v_lshl_add_u64 v[2:3], s[52:53], 0, v[0:1]
	s_mov_b64 s[2:3], 0x46000
	v_readlane_b32 s24, v239, 15
	v_readlane_b32 s25, v239, 16
	v_lshl_add_u64 v[60:61], v[2:3], 0, s[2:3]
	s_mov_b64 s[2:3], 0x8000
	v_lshl_add_u64 v[4:5], s[24:25], 0, v[0:1]
	v_lshl_add_u64 v[62:63], v[4:5], 0, s[2:3]
	s_mov_b64 s[2:3], 0x47000
	v_lshl_add_u64 v[64:65], v[2:3], 0, s[2:3]
	s_mov_b64 s[2:3], 0x47400
	v_lshl_add_u64 v[66:67], v[2:3], 0, s[2:3]
	s_mov_b64 s[2:3], 0x47800
	v_lshl_add_u64 v[68:69], v[2:3], 0, s[2:3]
	s_mov_b64 s[2:3], 0x47c00
	v_lshl_add_u64 v[70:71], v[2:3], 0, s[2:3]
	s_mov_b64 s[2:3], 0x9000
	v_readlane_b32 s13, v239, 4
	v_readlane_b32 s14, v239, 5
	v_readlane_b32 s15, v239, 6
	v_readlane_b32 s16, v239, 7
	v_readlane_b32 s17, v239, 8
	v_readlane_b32 s18, v239, 9
	v_readlane_b32 s19, v239, 10
	v_readlane_b32 s20, v239, 11
	v_readlane_b32 s21, v239, 12
	v_readlane_b32 s22, v239, 13
	v_readlane_b32 s23, v239, 14
	v_readlane_b32 s26, v239, 17
	v_readlane_b32 s27, v239, 18
	v_lshl_add_u64 v[72:73], v[4:5], 0, s[2:3]
	s_mov_b64 s[2:3], 0x9400
	v_readlane_b32 s12, v239, 51
	v_lshl_add_u64 v[74:75], v[4:5], 0, s[2:3]
	s_mov_b64 s[2:3], 0x9800
	v_readlane_b32 s16, v239, 55
	v_readlane_b32 s17, v239, 56
	v_lshl_add_u64 v[76:77], v[4:5], 0, s[2:3]
	s_mov_b64 s[2:3], 0x9c00
	s_cmp_lg_u64 s[16:17], 0
	v_lshl_add_u64 v[78:79], v[4:5], 0, s[2:3]
	v_readlane_b32 s2, v238, 6
	s_cselect_b64 s[10:11], -1, 0
	v_readlane_b32 s3, v238, 7
	s_mov_b32 s4, s2
	s_ashr_i32 s5, s2, 31
	s_lshl_b64 s[2:3], s[4:5], 13
	s_add_u32 s2, s56, s2
	s_addc_u32 s3, s57, s3
	v_lshl_add_u64 v[58:59], s[66:67], 0, v[0:1]
	v_readlane_b32 s13, v239, 52
	v_lshl_add_u64 v[0:1], s[2:3], 0, v[0:1]
	s_mov_b64 s[2:3], 0x1000
	s_ashr_i32 s91, s90, 31
	v_lshl_add_u64 v[80:81], v[0:1], 0, s[2:3]
	s_lshl_b64 s[12:13], s[90:91], 13
	s_lshl_b64 s[2:3], s[4:5], 12
	s_add_u32 s2, s16, s2
	s_addc_u32 s3, s17, s3
	v_lshl_add_u64 v[0:1], v[56:57], 1, s[2:3]
	s_mov_b64 s[2:3], 0x800
	v_lshl_add_u64 v[82:83], v[0:1], 0, s[2:3]
	s_mov_b32 s2, s4
	v_readlane_b32 s14, v239, 53
	v_readlane_b32 s15, v239, 54
	v_readlane_b32 s25, v238, 0
	v_readlane_b32 s26, v238, 1
	v_readlane_b32 s27, v238, 2
	v_writelane_b32 v238, s2, 6
	s_lshl_b64 s[14:15], s[90:91], 12
	s_mov_b32 s17, 0
	s_movk_i32 s1, 0x1000
	v_mov_b32_e32 v106, 0x358637bd
	v_writelane_b32 v238, s3, 7
	s_mov_b32 s2, s4
	v_readlane_b32 s18, v239, 57
	v_readlane_b32 s19, v239, 58
	v_readlane_b32 s20, v239, 59
	v_readlane_b32 s21, v239, 60
	v_readlane_b32 s22, v239, 61
	v_readlane_b32 s23, v239, 62
	v_readlane_b32 s24, v239, 63
	s_branch .LBB0_2157

.LBB0_2264:
	s_or_b64 exec, exec, s[16:17]
.LBB0_2265:
	s_or_b64 exec, exec, s[10:11]
	s_add_u32 s14, s60, 0xcc00000
	v_readlane_b32 s1, v240, 44
	s_addc_u32 s15, s61, 0
	s_waitcnt lgkmcnt(0)
	s_barrier
	s_barrier
	v_mbcnt_lo_u32_b32 v0, -1, 0
	v_mbcnt_hi_u32_b32 v0, -1, v0
	s_cmpk_gt_i32 s94, 0x681
	s_waitcnt vmcnt(11)
	v_add_u32_e32 v16, s1, v0
	s_nop 0
	v_readfirstlane_b32 s1, v16
	s_cbranch_scc1 .LBB0_2289
	s_ashr_i32 s2, s94, 31
	s_lshr_b32 s3, s2, 29
	s_add_i32 s4, s94, s3
	s_and_b32 s3, s4, -8
	s_sub_i32 s5, s94, s3
	s_cmp_gt_i32 s5, 1
	s_cbranch_scc0 .LBB0_2268
	s_mul_i32 s3, s5, 0xd0
	s_or_b32 s3, s3, 2
	s_cbranch_execz .LBB0_2269
	s_branch .LBB0_2270

.LBB0_2355:
	s_or_b64 exec, exec, s[18:19]
	v_cvt_f32_u32_e32 v4, v2
	s_waitcnt vmcnt(0)
	v_readfirstlane_b32 s1, v3
	v_sub_u32_e32 v3, 0, v2
	v_rcp_iflag_f32_e32 v4, v4
	v_add_u32_e32 v5, s1, v1
	v_mul_f32_e32 v4, 0x4f7ffffe, v4
	v_cvt_u32_f32_e32 v4, v4
	v_mul_lo_u32 v1, v3, v4
	v_mul_hi_u32 v1, v4, v1
	v_add_u32_e32 v1, v4, v1
	v_mul_hi_u32 v1, v5, v1
	v_mul_lo_u32 v3, v1, v2
	v_sub_u32_e32 v3, v5, v3
	v_add_u32_e32 v4, 1, v1
	v_cmp_ge_u32_e32 vcc, v3, v2
	s_nop 1
	v_cndmask_b32_e32 v1, v1, v4, vcc
	v_sub_u32_e32 v4, v3, v2
	v_cndmask_b32_e32 v3, v3, v4, vcc
	v_add_u32_e32 v4, 1, v1
	v_cmp_ge_u32_e32 vcc, v3, v2
	v_add_u32_e32 v3, 1, v5
	s_nop 0
	v_cndmask_b32_e32 v1, v1, v4, vcc
	v_mul_lo_u32 v4, v2, v1
	v_add_u32_e32 v2, v4, v2
	v_cmp_ne_u32_e32 vcc, v3, v2
	s_and_saveexec_b64 s[2:3], vcc
	s_xor_b64 s[16:17], exec, s[2:3]
	s_cbranch_execz .LBB0_2369
	s_waitcnt lgkmcnt(0)
	v_mov_b32_e32 v0, 0x3500
	global_load_dword v0, v0, s[96:97] sc1
	s_add_u32 s20, s96, 0x3500
	s_addc_u32 s21, s97, 0
	s_waitcnt vmcnt(0)
	v_cmp_eq_u32_e32 vcc, v0, v1
	s_and_saveexec_b64 s[18:19], vcc
	s_cbranch_execz .LBB0_2368
	s_mov_b32 s1, 1
	s_mov_b64 s[22:23], 0
	v_mov_b32_e32 v0, 0
	s_branch .LBB0_2359

.LBB0_2386:
	s_or_b64 exec, exec, s[16:17]
	s_mov_b64 s[16:17], exec
	v_mbcnt_lo_u32_b32 v0, s16, 0
	v_mbcnt_hi_u32_b32 v0, s17, v0
	v_cmp_eq_u32_e32 vcc, 0, v0
	s_and_saveexec_b64 s[18:19], vcc
	s_cbranch_execz .LBB0_2388
	s_bcnt1_i32_b64 s1, s[16:17]
	v_mov_b32_e32 v0, 0x2000
	v_mov_b32_e32 v1, s1
.LBB0_2388:
	s_or_b64 exec, exec, s[18:19]
.LBB0_2389:
	s_or_b64 exec, exec, s[10:11]
	v_readlane_b32 s1, v240, 44
	s_waitcnt lgkmcnt(0)
	s_barrier
	v_mbcnt_lo_u32_b32 v208, -1, 0
	v_mbcnt_hi_u32_b32 v208, -1, v208
	s_nop 0
	v_add_u32_e32 v84, s1, v208
	s_movk_i32 s1, 0x2000
	v_cmp_gt_i32_e32 vcc, s1, v84
	s_barrier
	s_and_saveexec_b64 s[10:11], vcc
	s_cbranch_execz .LBB0_2392
	v_readlane_b32 s1, v238, 5
	s_lshl_b32 s1, s1, 10
	v_readlane_b32 s16, v239, 35
	s_add_i32 s1, s1, 0
	v_ashrrev_i32_e32 v85, 31, v84
	v_readlane_b32 s26, v239, 45
	v_readlane_b32 s27, v239, 46
	v_add_u32_e32 v2, 0xfffffe00, v84
	v_lshl_add_u32 v3, v208, 4, s1
	v_lshl_add_u64 v[0:1], v[84:85], 4, s[26:27]
	s_mov_b64 s[12:13], 0
	s_mov_b64 s[2:3], 0x2000
	s_movk_i32 s1, 0x1dff
	v_readlane_b32 s17, v239, 36
	v_readlane_b32 s18, v239, 37
	v_readlane_b32 s19, v239, 38
	v_readlane_b32 s20, v239, 39
	v_readlane_b32 s21, v239, 40
	v_readlane_b32 s22, v239, 41
	v_readlane_b32 s23, v239, 42
	v_readlane_b32 s24, v239, 43
	v_readlane_b32 s25, v239, 44
	v_readlane_b32 s28, v239, 47
	v_readlane_b32 s29, v239, 48
	v_readlane_b32 s30, v239, 49
	v_readlane_b32 s31, v239, 50

.LBB0_2454:
	s_or_b64 exec, exec, s[16:17]
.LBB0_2455:
	s_or_b64 exec, exec, s[10:11]
	s_add_u32 s30, s62, 0x2200000
	s_addc_u32 s31, s63, 0
	s_add_u32 s34, s62, 0x8800000
	s_addc_u32 s35, s63, 0
	s_cmpk_gt_i32 s94, 0x87f
	s_waitcnt lgkmcnt(0)
	s_barrier
	s_waitcnt vmcnt(11)
	v_mbcnt_lo_u32_b32 v16, -1, 0
	v_mbcnt_hi_u32_b32 v16, -1, v16
	s_cbranch_scc1 .LBB0_2487
	v_readlane_b32 s1, v240, 44
	v_lshlrev_b32_e32 v0, 3, v16
	v_and_b32_e32 v18, 0x78, v0
	v_add_u32_e32 v8, s1, v16
	s_ashr_i32 s1, s94, 4
	s_mul_hi_i32 s2, s1, 0x78787879
	s_lshr_b32 s3, s2, 31
	s_ashr_i32 s2, s2, 5
	s_add_i32 s2, s2, s3
	s_mulk_i32 s2, 0x44
	s_sub_i32 s1, s1, s2
	s_mul_hi_i32 s2, s94, 0x78787879
	s_lshr_b32 s3, s2, 31
	s_ashr_i32 s2, s2, 9
	s_add_i32 s2, s2, s3
	s_lshl_b32 s3, s94, 7
	s_lshl_b32 s4, s2, 12
	s_lshl_b32 s2, s2, 8
	s_and_b32 s3, s3, 0x780
	s_lshl_b32 s5, s1, 6
	s_addk_i32 s4, 0xff00
	s_addk_i32 s2, 0x2000
	s_cmp_lt_i32 s1, 4
	v_ashrrev_i32_e32 v19, 4, v8
	s_cselect_b32 s1, s2, s4
	v_add_u32_e32 v8, 0x200, v8
	s_add_i32 s1, s1, s5
	s_waitcnt vmcnt(7)
	v_ashrrev_i32_e32 v32, 4, v8
	v_add_u32_e32 v0, s1, v19
	v_add_u32_e32 v8, s1, v32
	v_ashrrev_i32_e32 v1, 31, v0
	v_readlane_b32 s44, v240, 22
	v_ashrrev_i32_e32 v9, 31, v8
	v_lshlrev_b64 v[0:1], 11, v[0:1]
	v_readlane_b32 s45, v240, 23
	v_readlane_b32 s46, v240, 24
	v_readlane_b32 s47, v240, 25
	v_readlane_b32 s48, v240, 26
	v_readlane_b32 s49, v240, 27
	v_readlane_b32 s50, v240, 28
	v_readlane_b32 s51, v240, 29
	v_readlane_b32 s52, v240, 30
	v_readlane_b32 s53, v240, 31
	v_readlane_b32 s54, v240, 32
	v_readlane_b32 s55, v240, 33
	v_lshlrev_b64 v[8:9], 11, v[8:9]
	v_or3_b32 v0, v0, v18, s3
	v_readlane_b32 s56, v240, 34
	v_readlane_b32 s57, v240, 35
	v_readlane_b32 s58, v240, 36
	v_readlane_b32 s59, v240, 37
	s_mov_b64 s[44:45], s[48:49]
	v_or3_b32 v8, v8, v18, s3
	v_lshlrev_b64 v[0:1], 1, v[0:1]
	s_mov_b64 s[46:47], s[50:51]
	s_mov_b64 s[48:49], s[52:53]
	s_mov_b64 s[50:51], s[54:55]
	v_lshlrev_b64 v[8:9], 1, v[8:9]
	v_lshl_add_u64 v[2:3], s[30:31], 0, v[0:1]
	v_lshl_add_u64 v[4:5], s[50:51], 0, v[0:1]
	v_lshl_add_u64 v[10:11], s[30:31], 0, v[8:9]
	v_lshl_add_u64 v[12:13], s[50:51], 0, v[8:9]
	global_load_dwordx4 v[0:3], v[2:3], off
	s_nop 0
	global_load_dwordx4 v[4:7], v[4:5], off
	s_nop 0
	global_load_dwordx4 v[8:11], v[10:11], off
	s_nop 0
	global_load_dwordx4 v[12:15], v[12:13], off
	v_cmp_eq_u32_e32 vcc, 0, v16
	v_and_b32_e32 v28, 15, v16
	s_add_i32 s1, 0, 0x4400
	s_waitcnt vmcnt(10)
	v_cndmask_b32_e64 v39, 0, 1.0, vcc
	v_cmp_eq_u32_e32 vcc, 1, v16
	s_add_i32 s2, 0, 0x8800
	s_add_i32 s3, 0, 0xc900
	s_waitcnt vmcnt(9)
	v_cndmask_b32_e64 v41, 0, 1.0, vcc
	v_cmp_eq_u32_e32 vcc, 2, v16
	v_readlane_b32 s12, v238, 21
	v_readlane_b32 s4, v238, 16
	v_cndmask_b32_e64 v42, 0, 1.0, vcc
	v_cmp_eq_u32_e32 vcc, 3, v16
	s_cmpk_lt_u32 s12, 0x100
	v_or_b32_e32 v17, s4, v28
	v_cndmask_b32_e64 v43, 0, 1.0, vcc
	v_cmp_eq_u32_e32 vcc, 4, v16
	s_cselect_b32 s1, 0, s1
	v_mul_u32_u24_e32 v17, 0x110, v17
	s_waitcnt vmcnt(8)
	v_cndmask_b32_e64 v44, 0, 1.0, vcc
	v_cmp_eq_u32_e32 vcc, 5, v16
	v_and_b32_e32 v20, -16, v16
	v_add3_u32 v33, s1, v17, v20
	v_cndmask_b32_e64 v45, 0, 1.0, vcc
	v_cmp_eq_u32_e32 vcc, 6, v16
	s_cselect_b32 s1, s2, s3
	v_lshrrev_b32_e32 v17, 2, v16
	v_cndmask_b32_e64 v46, 0, 1.0, vcc
	v_cmp_eq_u32_e32 vcc, 7, v16
	v_and_b32_e32 v17, 0x3ffffffc, v17
	v_lshl_add_u32 v31, v28, 2, s1
	v_cndmask_b32_e64 v47, 0, 1.0, vcc
	v_cmp_eq_u32_e32 vcc, 8, v16
	s_bfe_u32 s1, s12, 0x20006
	v_add_u32_e32 v29, s4, v17
	s_waitcnt vmcnt(7)
	v_cndmask_b32_e64 v48, 0, 1.0, vcc
	v_cmp_eq_u32_e32 vcc, 9, v16
	s_lshl_b32 s4, s1, 14
	v_readlane_b32 s3, v238, 5
	v_cndmask_b32_e64 v49, 0, 1.0, vcc
	v_cmp_eq_u32_e32 vcc, 10, v16
	s_add_i32 s4, s4, 0
	s_bfe_u32 s2, s12, 0x10006
	v_cndmask_b32_e64 v50, 0, 1.0, vcc
	v_cmp_eq_u32_e32 vcc, 11, v16
	s_bfe_u32 s3, s3, 0x10001
	s_add_i32 s4, s4, 0x10a00
	v_cndmask_b32_e64 v51, 0, 1.0, vcc
	v_cmp_eq_u32_e32 vcc, 12, v16
	s_cmp_eq_u32 s2, 0
	v_lshl_add_u32 v26, v18, 1, 0
	s_waitcnt vmcnt(6)
	v_cndmask_b32_e64 v52, 0, 1.0, vcc
	v_cmp_eq_u32_e32 vcc, 13, v16
	s_movk_i32 s14, 0x110
	s_cselect_b64 s[10:11], -1, 0
	v_cndmask_b32_e64 v53, 0, 1.0, vcc
	v_cmp_eq_u32_e32 vcc, 14, v16
	s_lshl_b32 s5, s2, 5
	s_and_b32 s12, s12, 0xffffff00
	v_cndmask_b32_e64 v54, 0, 1.0, vcc
	v_cmp_eq_u32_e32 vcc, 15, v16
	s_cmpk_lg_i32 s12, 0x100
	v_mad_u64_u32 v[24:25], s[12:13], v19, s14, v[26:27]
	v_cndmask_b32_e64 v55, 0, 1.0, vcc
	v_cmp_eq_u32_e32 vcc, 16, v16
	v_mad_u64_u32 v[26:27], s[12:13], v32, s14, v[26:27]
	s_waitcnt vmcnt(5)
	v_cndmask_b32_e64 v56, 0, 1.0, vcc
	v_cmp_eq_u32_e32 vcc, 17, v16
	v_mul_u32_u24_e32 v105, 0x110, v28
	s_movk_i32 s12, 0x104
	v_cndmask_b32_e64 v57, 0, 1.0, vcc
	v_cmp_eq_u32_e32 vcc, 18, v16
	v_lshlrev_b32_e32 v28, 2, v16
	v_sub_u32_e32 v17, 63, v16
	v_cndmask_b32_e64 v58, 0, 1.0, vcc
	v_cmp_eq_u32_e32 vcc, 19, v16
	v_mul_lo_u32 v106, v29, s12
	v_add_u32_e32 v29, 0xe0, v28
	v_cndmask_b32_e64 v59, 0, 1.0, vcc
	v_cmp_eq_u32_e32 vcc, 20, v16
	s_mov_b64 s[52:53], s[56:57]
	s_mov_b64 s[54:55], s[58:59]
	s_waitcnt vmcnt(4)
	v_cndmask_b32_e64 v60, 0, 1.0, vcc
	v_cmp_eq_u32_e32 vcc, 21, v16
	v_cndmask_b32_e64 v34, v17, v16, s[10:11]
	v_ashrrev_i32_e32 v17, 31, v16
	v_cndmask_b32_e64 v61, 0, 1.0, vcc
	v_cmp_eq_u32_e32 vcc, 22, v16
	v_and_b32_e32 v36, 0xfc, v29
	v_add_u32_e32 v29, 0xc0, v28
	v_cndmask_b32_e64 v62, 0, 1.0, vcc
	v_cmp_eq_u32_e32 vcc, 23, v16
	v_add_u32_e32 v30, 0, v20
	v_lshl_add_u64 v[20:21], v[16:17], 1, s[54:55]
	v_cndmask_b32_e64 v63, 0, 1.0, vcc
	v_cmp_eq_u32_e32 vcc, 24, v16
	v_lshl_add_u64 v[22:23], v[16:17], 2, s[34:35]
	v_add_u32_e32 v17, 0xfc, v28
	v_cndmask_b32_e64 v64, 0, 1.0, vcc
	v_cmp_eq_u32_e32 vcc, 25, v16
	v_add_u32_e32 v25, 0xf8, v28
	v_add_u32_e32 v27, 0xf0, v28
	v_cndmask_b32_e64 v65, 0, 1.0, vcc
	v_cmp_eq_u32_e32 vcc, 26, v16
	v_and_b32_e32 v37, 0xfc, v29
	s_movk_i32 s22, 0x80
	v_cndmask_b32_e64 v66, 0, 1.0, vcc
	v_cmp_eq_u32_e32 vcc, 27, v16
	v_bfrev_b32_e32 v29, 0.5
	s_mov_b64 s[38:39], 0x4400180
	v_cndmask_b32_e64 v67, 0, 1.0, vcc
	v_cmp_eq_u32_e32 vcc, 28, v16
	s_cselect_b64 s[36:37], -1, 0
	v_lshl_add_u32 v35, v34, 2, 0
	v_cndmask_b32_e64 v68, 0, 1.0, vcc
	v_cmp_eq_u32_e32 vcc, 29, v16
	v_and_b32_e32 v17, 0xfc, v17
	v_cmp_gt_i32_e64 s[12:13], 1, v16
	v_cndmask_b32_e64 v69, 0, 1.0, vcc
	v_cmp_eq_u32_e32 vcc, 30, v16
	v_and_b32_e32 v25, 0xfc, v25
	v_cmp_gt_i32_e64 s[14:15], 2, v16
	v_cndmask_b32_e64 v70, 0, 1.0, vcc
	v_cmp_eq_u32_e32 vcc, 31, v16
	v_and_b32_e32 v27, 0xfc, v27
	v_cmp_gt_i32_e64 s[16:17], 4, v16
	v_cndmask_b32_e64 v71, 0, 1.0, vcc
	v_cmp_eq_u32_e32 vcc, 32, v16
	v_cmp_gt_i32_e64 s[18:19], 8, v16
	v_cmp_gt_i32_e64 s[20:21], 16, v16
	v_cndmask_b32_e64 v72, 0, 1.0, vcc
	v_cmp_eq_u32_e32 vcc, 33, v16
	v_bitop3_b32 v38, v28, s22, v29 bitop3:0x6c
	v_cmp_gt_i32_e64 s[22:23], 32, v16
	v_cndmask_b32_e64 v73, 0, 1.0, vcc
	v_cmp_eq_u32_e32 vcc, 34, v16
	v_cvt_pk_bf16_f32 v40, v39, s0
	v_add_u32_e32 v104, s4, v28
	v_cndmask_b32_e64 v74, 0, 1.0, vcc
	v_cmp_eq_u32_e32 vcc, 35, v16
	v_lshl_add_u64 v[28:29], v[20:21], 0, s[38:39]
	s_lshl_b32 s27, s94, 1
	v_cndmask_b32_e64 v75, 0, 1.0, vcc
	v_cmp_eq_u32_e32 vcc, 36, v16
	s_lshl_b32 s42, s33, 1
	v_add_u32_e32 v105, v30, v105
	v_cndmask_b32_e64 v76, 0, 1.0, vcc
	v_cmp_eq_u32_e32 vcc, 37, v16
	v_add_u32_e32 v106, v31, v106
	s_mov_b32 s46, s94
	v_cndmask_b32_e64 v77, 0, 1.0, vcc
	v_cmp_eq_u32_e32 vcc, 38, v16
	s_nop 1
	v_cndmask_b32_e64 v78, 0, 1.0, vcc
	v_cmp_eq_u32_e32 vcc, 39, v16
	s_nop 1
	v_cndmask_b32_e64 v79, 0, 1.0, vcc
	v_cmp_eq_u32_e32 vcc, 40, v16
	s_nop 1
	v_cndmask_b32_e64 v80, 0, 1.0, vcc
	v_cmp_eq_u32_e32 vcc, 41, v16
	s_nop 1
	v_cndmask_b32_e64 v81, 0, 1.0, vcc
	v_cmp_eq_u32_e32 vcc, 42, v16
	s_nop 1
	v_cndmask_b32_e64 v82, 0, 1.0, vcc
	v_cmp_eq_u32_e32 vcc, 43, v16
	s_nop 1
	v_cndmask_b32_e64 v83, 0, 1.0, vcc
	v_cmp_eq_u32_e32 vcc, 44, v16
	s_nop 1
	v_cndmask_b32_e64 v84, 0, 1.0, vcc
	v_cmp_eq_u32_e32 vcc, 45, v16
	s_nop 1
	v_cndmask_b32_e64 v85, 0, 1.0, vcc
	v_cmp_eq_u32_e32 vcc, 46, v16
	s_nop 1
	v_cndmask_b32_e64 v86, 0, 1.0, vcc
	v_cmp_eq_u32_e32 vcc, 47, v16
	s_nop 1
	v_cndmask_b32_e64 v87, 0, 1.0, vcc
	v_cmp_eq_u32_e32 vcc, 48, v16
	s_nop 1
	v_cndmask_b32_e64 v88, 0, 1.0, vcc
	v_cmp_eq_u32_e32 vcc, 49, v16
	s_nop 1
	v_cndmask_b32_e64 v89, 0, 1.0, vcc
	v_cmp_eq_u32_e32 vcc, 50, v16
	s_nop 1
	v_cndmask_b32_e64 v90, 0, 1.0, vcc
	v_cmp_eq_u32_e32 vcc, 51, v16
	s_nop 1
	v_cndmask_b32_e64 v91, 0, 1.0, vcc
	v_cmp_eq_u32_e32 vcc, 52, v16
	s_nop 1
	v_cndmask_b32_e64 v92, 0, 1.0, vcc
	v_cmp_eq_u32_e32 vcc, 53, v16
	s_nop 1
	v_cndmask_b32_e64 v93, 0, 1.0, vcc
	v_cmp_eq_u32_e32 vcc, 54, v16
	s_nop 1
	v_cndmask_b32_e64 v94, 0, 1.0, vcc
	v_cmp_eq_u32_e32 vcc, 55, v16
	s_nop 1
	v_cndmask_b32_e64 v95, 0, 1.0, vcc
	v_cmp_eq_u32_e32 vcc, 56, v16
	s_nop 1
	v_cndmask_b32_e64 v96, 0, 1.0, vcc
	v_cmp_eq_u32_e32 vcc, 57, v16
	s_nop 1
	v_cndmask_b32_e64 v97, 0, 1.0, vcc
	v_cmp_eq_u32_e32 vcc, 58, v16
	s_nop 1
	v_cndmask_b32_e64 v98, 0, 1.0, vcc
	v_cmp_eq_u32_e32 vcc, 59, v16
	s_nop 1
	v_cndmask_b32_e64 v99, 0, 1.0, vcc
	v_cmp_eq_u32_e32 vcc, 60, v16
	s_nop 1
	v_cndmask_b32_e64 v100, 0, 1.0, vcc
	v_cmp_eq_u32_e32 vcc, 61, v16
	s_nop 1
	v_cndmask_b32_e64 v101, 0, 1.0, vcc
	v_cmp_eq_u32_e32 vcc, 62, v16
	s_nop 1
	v_cndmask_b32_e64 v102, 0, 1.0, vcc
	v_cmp_eq_u32_e32 vcc, 63, v16
	s_nop 1
	v_cndmask_b32_e64 v103, 0, 1.0, vcc
	s_branch .LBB0_2458

.LBB0_2538:
	s_or_b64 exec, exec, s[16:17]
.LBB0_2539:
	s_or_b64 exec, exec, s[10:11]
	v_readlane_b32 s44, v240, 22
	s_and_b64 vcc, exec, s[76:77]
	v_readlane_b32 s45, v240, 23
	v_readlane_b32 s48, v240, 26
	v_readlane_b32 s49, v240, 27
	v_readlane_b32 s52, v240, 30
	v_readlane_b32 s53, v240, 31
	v_readlane_b32 s54, v240, 32
	v_readlane_b32 s55, v240, 33
	v_readlane_b32 s56, v240, 34
	v_readlane_b32 s57, v240, 35
	v_readlane_b32 s58, v240, 36
	v_readlane_b32 s59, v240, 37
	s_waitcnt lgkmcnt(0)
	s_barrier
	v_mbcnt_lo_u32_b32 v68, -1, 0
	v_mbcnt_hi_u32_b32 v68, -1, v68
	v_readlane_b32 s46, v240, 24
	v_readlane_b32 s47, v240, 25
	v_readlane_b32 s50, v240, 28
	v_readlane_b32 s51, v240, 29
	s_cbranch_vccnz .LBB0_2552
	v_ashrrev_i32_e32 v7, 4, v68
	v_and_b32_e32 v4, 15, v68
	v_lshlrev_b32_e32 v9, 3, v7
	v_readlane_b32 s23, v238, 15
	v_or_b32_e32 v0, 7, v9
	v_or_b32_e32 v1, 6, v9
	v_and_or_b32 v6, s23, 16, v4
	v_cmp_eq_u32_e32 vcc, v0, v6
	v_mov_b32_e32 v8, 0x3f80
	v_readlane_b32 s1, v240, 44
	v_cndmask_b32_e64 v0, 0, 1.0, vcc
	v_cmp_eq_u32_e32 vcc, v1, v6
	v_add_u32_e32 v5, s1, v68
	v_add_u32_e32 v10, 0x200, v5
	v_cndmask_b32_e32 v1, 0, v8, vcc
	v_or_b32_e32 v3, v0, v1
	v_or_b32_e32 v0, 5, v9
	v_cmp_eq_u32_e32 vcc, v0, v6
	v_or_b32_e32 v1, 4, v9
	v_ashrrev_i32_e32 v101, 3, v5
	v_cndmask_b32_e64 v0, 0, 1.0, vcc
	v_cmp_eq_u32_e32 vcc, v1, v6
	v_ashrrev_i32_e32 v99, 4, v10
	v_lshlrev_b32_e32 v10, 6, v101
	v_cndmask_b32_e32 v1, 0, v8, vcc
	v_or_b32_e32 v2, v0, v1
	v_or_b32_e32 v0, 3, v9
	v_cmp_eq_u32_e32 vcc, v0, v6
	v_or_b32_e32 v1, 2, v9
	v_ashrrev_i32_e32 v11, 31, v10
	v_cndmask_b32_e64 v0, 0, 1.0, vcc
	v_cmp_eq_u32_e32 vcc, v1, v6
	v_mov_b32_e32 v71, 0
	v_lshl_add_u64 v[10:11], v[10:11], 1, s[58:59]
	v_cndmask_b32_e32 v1, 0, v8, vcc
	v_or_b32_e32 v1, v0, v1
	v_or_b32_e32 v0, 1, v9
	v_cmp_eq_u32_e32 vcc, v0, v6
	s_mov_b64 s[2:3], 0x4400000
	s_add_u32 s14, s54, 0x4400000
	v_cndmask_b32_e64 v0, 0, 1.0, vcc
	v_cmp_eq_u32_e32 vcc, v9, v6
	s_addc_u32 s15, s55, 0
	s_movk_i32 s1, 0x1100
	v_cndmask_b32_e32 v6, 0, v8, vcc
	v_lshlrev_b32_e32 v8, 3, v5
	v_or_b32_e32 v0, v0, v6
	v_and_b32_e32 v6, 0x78, v8
	v_and_b32_e32 v8, 56, v8
	v_lshlrev_b32_e32 v70, 1, v8
	v_lshl_add_u64 v[72:73], v[10:11], 0, v[70:71]
	v_lshl_add_u64 v[74:75], v[72:73], 0, s[2:3]
	v_readlane_b32 s2, v238, 21
	v_cmp_gt_i32_e64 s[10:11], s1, v5
	s_movk_i32 s1, 0x90
	s_cmp_lt_u32 s2, 64
	v_readlane_b32 s22, v238, 5
	v_mul_lo_u32 v11, v101, s1
	s_cselect_b64 s[18:19], -1, 0
	s_lshl_b32 s13, s22, 3
	v_lshlrev_b32_e32 v10, 1, v6
	v_add3_u32 v103, 0, v11, v70
	v_mov_b32_e32 v11, v71
	s_and_b32 s13, s13, 0x1ffffff0
	v_add_u32_e32 v12, 0, v10
	v_lshl_add_u64 v[76:77], s[30:31], 0, v[10:11]
	v_lshl_add_u64 v[78:79], s[54:55], 0, v[10:11]
	v_lshlrev_b32_e32 v10, 2, v68
	s_add_i32 s2, 0, 0x11800
	s_add_i32 s3, 0, 0x11900
	s_lshl_b32 s16, s13, 2
	v_add_u32_e32 v104, s2, v10
	v_add_u32_e32 v105, s3, v10
	v_lshl_add_u32 v107, v7, 2, s13
	s_add_i32 s2, s2, s16
	v_and_b32_e32 v7, -16, v68
	s_add_i32 s3, s3, s16
	v_add_u32_e32 v115, s2, v7
	v_add_u32_e32 v116, s3, v7
	v_or_b32_e32 v11, s13, v4
	s_movk_i32 s20, 0x110
	s_add_i32 s2, 0, 0x15c00
	s_lshl_b32 s3, s13, 1
	v_mul_lo_u32 v13, v11, s20
	s_add_i32 s13, s2, s3
	s_add_i32 s4, 0, 0x11a00
	v_add3_u32 v117, 0, v13, v7
	v_add_u32_e32 v118, s13, v9
	s_and_b32 s13, s23, 0x3fffffe0
	v_lshlrev_b32_e32 v11, 7, v11
	v_add_u32_e32 v106, s4, v10
	s_lshl_b32 s5, s22, 5
	s_add_i32 s21, 0, 0x1a400
	s_lshl_b32 s13, s13, 1
	s_add_i32 s4, s4, s16
	v_sub_u32_e32 v120, v117, v11
	v_add_u32_e32 v11, s2, v7
	s_add_i32 s2, 0, 0x18000
	v_ashrrev_i32_e32 v97, 4, v5
	s_and_b32 s12, s5, 32
	v_add_u32_e32 v13, s21, v7
	s_add_i32 s13, s13, 0
	v_add_u32_e32 v119, s4, v7
	s_add_i32 s4, s2, s3
	s_add_i32 s3, s3, 0
	v_add_u32_e32 v121, s2, v7
	s_add_i32 s2, s21, s5
	v_add_u32_e32 v14, s13, v7
	v_add_u32_e32 v15, s4, v9
	v_add_u32_e32 v16, s3, v9
	v_add_u32_e32 v7, 0, v9
	v_add_u32_e32 v9, s2, v9
	v_mad_u64_u32 v[80:81], s[2:3], v97, s20, v[12:13]
	v_or_b32_e32 v17, s12, v4
	v_mad_u64_u32 v[82:83], s[2:3], v99, s20, v[12:13]
	v_mul_lo_u32 v12, v107, s1
	v_mul_u32_u24_e32 v18, 0x110, v17
	s_lshl_b32 s1, s12, 1
	v_mul_u32_u24_e32 v81, 0x90, v17
	s_waitcnt vmcnt(10)
	v_or_b32_e32 v20, 16, v17
	v_mul_u32_u24_e32 v17, 0x48, v17
	s_add_i32 s1, s1, 0
	v_lshlrev_b32_e32 v17, 1, v17
	v_lshl_add_u32 v19, v4, 1, s1
	v_add_u32_e32 v122, v11, v17
	v_add_u32_e32 v123, v15, v17
	v_add_u32_e32 v124, v16, v17
	v_add_u32_e32 v17, 0x900, v17
	s_lshl_b32 s1, s22, 8
	s_mov_b32 s17, 0
	v_or_b32_e32 v109, 1, v107
	v_or_b32_e32 v111, 2, v107
	v_or_b32_e32 v113, 3, v107
	v_mul_u32_u24_e32 v21, 0x110, v20
	v_mul_u32_u24_e32 v83, 0x90, v20
	v_mul_u32_u24_e32 v20, 0x110, v4
	v_add_u32_e32 v125, v11, v17
	v_mul_u32_u24_e32 v11, 0x90, v4
	s_add_i32 s21, s21, s1
	v_sub_u32_e32 v96, 63, v68
	v_ashrrev_i32_e32 v69, 31, v68
	v_sub_u32_e32 v98, 63, v97
	v_sub_u32_e32 v100, 63, v99
	v_sub_u32_e32 v102, 63, v101
	v_sub_u32_e32 v108, 63, v107
	v_sub_u32_e32 v110, 63, v109
	v_sub_u32_e32 v112, 63, v111
	v_sub_u32_e32 v114, 63, v113
	v_add_u32_e32 v126, v15, v17
	v_add_u32_e32 v127, v16, v17
	v_add_u32_e32 v128, 0xfffffe00, v5
	v_add_u32_e32 v129, s21, v10
	v_lshlrev_b32_e32 v84, 1, v6
	v_lshlrev_b32_e32 v70, 1, v8
	s_mov_b32 s20, 0x3db504f3
	v_lshlrev_b32_e32 v86, 1, v4
	s_lshl_b32 s22, s12, 1
	s_mov_b32 s23, s17
	v_add_u32_e32 v130, v13, v18
	v_add_u32_e32 v131, v19, v12
	v_add_u32_e32 v132, v13, v21
	v_add_u32_e32 v133, v14, v20
	v_add_u32_e32 v134, v7, v11
	v_add_u32_e32 v135, v9, v20
	s_mov_b32 s1, s94
	s_branch .LBB0_2542

.LBB0_2603:
	s_or_b64 exec, exec, s[16:17]
.LBB0_2604:
	s_or_b64 exec, exec, s[10:11]
	s_andn2_b64 vcc, exec, s[28:29]
	s_waitcnt lgkmcnt(0)
	s_barrier
	v_mbcnt_lo_u32_b32 v8, -1, 0
	v_mbcnt_hi_u32_b32 v8, -1, v8
	s_cbranch_vccnz .LBB0_2609
	v_lshlrev_b32_e32 v0, 5, v8
	v_readlane_b32 s12, v240, 18
	v_and_b32_e32 v4, 0x1e0, v0
	v_readlane_b32 s13, v240, 19
	s_nop 4
	global_load_dwordx4 v[0:3], v4, s[12:13] offset:16
	s_nop 0
	global_load_dwordx4 v[4:7], v4, s[12:13]
	v_readlane_b32 s1, v238, 5
	s_lshl_b32 s1, s1, 9
	s_waitcnt vmcnt(12)
	v_mov_b32_e32 v22, 0x358637bd
	v_lshl_add_u32 v10, v8, 3, s1
	s_add_i32 s1, s26, -2
	v_ashrrev_i32_e32 v11, 31, v10
	v_lshlrev_b32_e32 v8, 2, v8
	s_add_u32 s2, s52, 0x4000
	v_xor_b32_e32 v23, 4, v8
	s_waitcnt vmcnt(6)
	v_xor_b32_e32 v44, 8, v8
	v_xor_b32_e32 v45, 16, v8
	v_xor_b32_e32 v46, 32, v8
	v_lshlrev_b64 v[20:21], 1, v[10:11]
	s_addc_u32 s3, s53, 0
	s_add_i32 s12, s26, 1
	s_mov_b32 s4, 0x800000
	v_readlane_b32 s14, v240, 20
	v_readlane_b32 s15, v240, 21

.LBB0_2660:
	s_or_b64 exec, exec, s[16:17]
.LBB0_2661:
	s_or_b64 exec, exec, s[10:11]
	s_waitcnt lgkmcnt(0)
	s_barrier
	s_barrier
	v_mbcnt_lo_u32_b32 v0, -1, 0
	v_mbcnt_hi_u32_b32 v0, -1, v0
	s_and_b64 vcc, exec, s[76:77]
	s_waitcnt vmcnt(11)
	v_add_u32_e32 v16, s78, v0
	s_nop 0
	v_readfirstlane_b32 s1, v16
	s_cbranch_vccnz .LBB0_2681
	s_ashr_i32 s2, s94, 31
	s_lshr_b32 s3, s2, 29
	s_add_i32 s3, s94, s3
	s_and_b32 s4, s3, -8
	s_sub_i32 s5, s94, s4
	s_cmp_gt_i32 s5, -1
	s_cbranch_scc0 .LBB0_2664
	s_lshl_b32 s4, s5, 5
	s_cbranch_execz .LBB0_2665
	s_branch .LBB0_2666

.LBB0_2744:
	s_or_b64 exec, exec, s[16:17]
.LBB0_2745:
	s_or_b64 exec, exec, s[10:11]
	v_readlane_b32 s2, v238, 22
	v_readlane_b32 s3, v238, 23
	s_and_b64 vcc, exec, s[2:3]
	s_waitcnt lgkmcnt(0)
	s_barrier
	v_mbcnt_lo_u32_b32 v0, -1, 0
	v_mbcnt_hi_u32_b32 v0, -1, v0
	s_cbranch_vccnz .LBB0_2753
	v_lshlrev_b32_e32 v32, 2, v0
	v_ashrrev_i32_e32 v33, 31, v32
	v_lshlrev_b64 v[0:1], 2, v[32:33]
	v_lshl_add_u64 v[2:3], s[44:45], 0, v[0:1]
	s_mov_b64 s[2:3], 0x64000
	s_mov_b64 s[36:37], s[82:83]
	s_mov_b64 s[34:35], s[80:81]
	v_lshl_add_u64 v[36:37], v[2:3], 0, s[2:3]
	s_mov_b32 s2, s90
	v_readlane_b32 s76, v239, 3
	v_readlane_b32 s77, v239, 4
	v_readlane_b32 s78, v239, 5
	v_readlane_b32 s79, v239, 6
	v_readlane_b32 s80, v239, 7
	v_readlane_b32 s81, v239, 8
	v_readlane_b32 s82, v239, 9
	v_readlane_b32 s83, v239, 10
	v_readlane_b32 s84, v239, 11
	v_readlane_b32 s85, v239, 12
	v_readlane_b32 s86, v239, 13
	v_readlane_b32 s87, v239, 14
	v_readlane_b32 s88, v239, 15
	v_readlane_b32 s89, v239, 16
	v_readlane_b32 s90, v239, 17
	v_readlane_b32 s91, v239, 18
	v_lshl_add_u64 v[4:5], s[88:89], 0, v[0:1]
	v_readlane_b32 s76, v239, 51
	v_readlane_b32 s90, v238, 1
	s_mov_b32 s90, s2
	s_mov_b64 s[2:3], 0xa000
	v_lshl_add_u64 v[38:39], v[4:5], 0, s[2:3]
	s_mov_b64 s[2:3], 0x65000
	v_lshl_add_u64 v[40:41], v[2:3], 0, s[2:3]
	s_mov_b64 s[2:3], 0x65400
	v_lshl_add_u64 v[42:43], v[2:3], 0, s[2:3]
	s_mov_b64 s[2:3], 0x65800
	v_lshl_add_u64 v[44:45], v[2:3], 0, s[2:3]
	s_mov_b64 s[2:3], 0x65c00
	v_lshl_add_u64 v[46:47], v[2:3], 0, s[2:3]
	s_mov_b64 s[2:3], 0xb000
	v_readlane_b32 s80, v239, 55
	v_readlane_b32 s81, v239, 56
	v_lshl_add_u64 v[48:49], v[4:5], 0, s[2:3]
	s_mov_b64 s[2:3], 0xb400
	s_cmp_lg_u64 s[80:81], 0
	v_lshl_add_u64 v[50:51], v[4:5], 0, s[2:3]
	s_mov_b64 s[2:3], 0xb800
	s_cselect_b64 s[10:11], -1, 0
	v_lshl_add_u64 v[52:53], v[4:5], 0, s[2:3]
	s_mov_b64 s[2:3], 0xbc00
	s_ashr_i32 s93, s92, 31
	v_lshl_add_u64 v[54:55], v[4:5], 0, s[2:3]
	s_lshl_b64 s[2:3], s[92:93], 13
	s_add_u32 s2, s48, s2
	v_readlane_b32 s91, v238, 2
	s_addc_u32 s3, s49, s3
	v_lshl_add_u64 v[34:35], s[58:59], 0, v[0:1]
	v_lshl_add_u64 v[0:1], s[2:3], 0, v[0:1]
	s_mov_b64 s[2:3], 0x1000
	s_ashr_i32 s91, s90, 31
	v_lshl_add_u64 v[56:57], v[0:1], 0, s[2:3]
	s_lshl_b64 s[12:13], s[90:91], 13
	s_lshl_b64 s[2:3], s[92:93], 12
	s_add_u32 s2, s80, s2
	s_addc_u32 s3, s81, s3
	v_lshl_add_u64 v[0:1], v[32:33], 1, s[2:3]
	s_mov_b64 s[2:3], 0x800
	v_lshl_add_u64 v[58:59], v[0:1], 0, s[2:3]
	s_lshl_b64 s[14:15], s[90:91], 12
	s_mov_b32 s17, 0
	s_mov_b32 s1, 0x401000
	s_mov_b32 s2, 0x801000
	s_mov_b32 s3, 0xc01000
	s_mov_b32 s4, 0x1001000
	s_mov_b32 s5, 0x1401000
	s_mov_b32 s22, 0x1801000
	s_mov_b32 s23, 0x1c01000
	s_mov_b64 s[18:19], 0x8000
	s_mov_b64 s[20:21], 0x6000
	v_mov_b32_e32 v76, 0x358637bd
	s_movk_i32 s26, 0x7000
	s_mov_b32 s27, 0x9000
	s_mov_b32 s28, s92
	v_readlane_b32 s77, v239, 52
	v_readlane_b32 s78, v239, 53
	v_readlane_b32 s79, v239, 54
	v_readlane_b32 s82, v239, 57
	v_readlane_b32 s83, v239, 58
	v_readlane_b32 s84, v239, 59
	v_readlane_b32 s85, v239, 60
	v_readlane_b32 s86, v239, 61
	v_readlane_b32 s87, v239, 62
	v_readlane_b32 s88, v239, 63
	v_readlane_b32 s89, v238, 0
	s_branch .LBB0_2748

.LBB0_2804:
	s_or_b64 exec, exec, s[16:17]
.LBB0_2805:
	s_or_b64 exec, exec, s[10:11]
	s_waitcnt lgkmcnt(0)
	s_barrier
	s_barrier
	v_mbcnt_lo_u32_b32 v0, -1, 0
	v_mbcnt_hi_u32_b32 v0, -1, v0
	s_and_b64 vcc, exec, s[8:9]
	v_add_u32_e32 v12, s78, v0
	s_nop 0
	v_readfirstlane_b32 s1, v12
	s_cbranch_vccnz .LBB0_2817
	v_lshlrev_b32_e32 v0, 4, v12
	v_add_u32_e32 v1, 0x2000, v0
	v_ashrrev_i32_e32 v2, 31, v1
	v_lshrrev_b32_e32 v2, 22, v2
	v_add_u32_e32 v2, v1, v2
	v_ashrrev_i32_e32 v8, 10, v2
	v_mul_i32_i24_e32 v2, 0x400, v8
	v_sub_u32_e32 v1, v1, v2
	v_lshrrev_b32_e32 v2, 4, v1
	v_bitop3_b32 v1, v2, v1, 32 bitop3:0x6c
	v_ashrrev_i32_e32 v2, 31, v1
	v_lshrrev_b32_e32 v2, 26, v2
	v_add_u32_e32 v2, v1, v2
	v_ashrrev_i32_e32 v9, 6, v2
	v_and_b32_e32 v2, 0xc0, v2
	s_ashr_i32 s3, s94, 31
	v_sub_u32_e32 v1, v1, v2
	v_mov_b32_e32 v2, 1
	s_lshr_b32 s4, s3, 29
	v_ashrrev_i16_sdwa v1, v2, sext(v1) dst_sel:DWORD dst_unused:UNUSED_PAD src0_sel:DWORD src1_sel:BYTE_0
	s_add_i32 s4, s94, s4
	s_ashr_i32 s10, s1, 6
	v_bfe_i32 v11, v1, 0, 16
	v_bfe_i32 v1, v12, 27, 1
	s_ashr_i32 s5, s4, 3
	s_and_b32 s4, s4, -8
	s_ashr_i32 s9, s1, 8
	s_lshl_b32 s2, s10, 10
	v_lshrrev_b32_e32 v1, 22, v1
	s_sub_i32 s8, s94, s4
	v_add_u32_e32 v1, v0, v1
	s_cmp_lt_i32 s8, 0
	s_movk_i32 s4, 0xbc
	v_and_b32_e32 v1, 0xfffffc00, v1
	s_cselect_b32 s11, s4, 0xbb
	v_sub_u32_e32 v0, v0, v1
	s_mul_i32 s8, s11, s8
	v_lshrrev_b32_e32 v1, 4, v0
	s_add_i32 s8, s8, s5
	v_bitop3_b32 v0, v1, v0, 32 bitop3:0x6c
	s_mul_hi_i32 s5, s8, 0x2e8ba2e9
	v_ashrrev_i32_e32 v1, 31, v0
	s_lshr_b32 s11, s5, 31
	s_ashr_i32 s5, s5, 6
	v_lshrrev_b32_e32 v1, 26, v1
	s_add_i32 s5, s5, s11
	v_add_u32_e32 v1, v0, v1
	s_lshl_b32 s11, s5, 3
	v_ashrrev_i32_e32 v13, 6, v1
	v_and_b32_e32 v1, 0xc0, v1
	s_sub_i32 s12, 34, s11
	s_mulk_i32 s5, 0x160
	v_sub_u32_e32 v0, v0, v1
	s_min_u32 s14, s12, 8
	s_sub_i32 s5, s8, s5
	v_ashrrev_i16_sdwa v0, v2, sext(v0) dst_sel:DWORD dst_unused:UNUSED_PAD src0_sel:DWORD src1_sel:BYTE_0
	s_sext_i32_i16 s8, s5
	v_cvt_f32_ubyte0_e32 v1, s14
	v_bfe_i32 v16, v0, 0, 16
	v_cvt_f32_i32_e32 v0, s8
	v_rcp_iflag_f32_e32 v2, v1
	s_ashr_i32 s8, s8, 30
	v_lshlrev_b32_e32 v3, 3, v8
	s_or_b32 s8, s8, 1
	v_mul_f32_e32 v2, v0, v2
	v_trunc_f32_e32 v2, v2
	v_fma_f32 v0, -v2, v1, v0
	v_cvt_i32_f32_e32 v2, v2
	v_cmp_ge_f32_e64 s[12:13], |v0|, v1
	v_and_b32_e32 v3, 0xffff0, v3
	v_lshlrev_b32_e32 v4, 5, v8
	s_and_b64 s[12:13], s[12:13], exec
	v_add_u32_e32 v3, v9, v3
	v_and_b32_e32 v10, 32, v4
	s_cselect_b32 s8, s8, 0
	v_readfirstlane_b32 s12, v2
	v_lshl_or_b32 v3, v3, 11, v10
	s_add_i32 s8, s12, s8
	v_add_lshl_u32 v128, v3, v11, 1
	v_ashrrev_i32_e32 v3, 31, v12
	s_mul_i32 s12, s8, s14
	v_lshrrev_b32_e32 v3, 26, v3
	s_sub_i32 s5, s5, s12
	v_add_u32_e32 v3, v12, v3
	s_sext_i32_i16 s5, s5
	v_ashrrev_i32_e32 v14, 6, v3
	s_add_i32 s20, s11, s5
	v_lshlrev_b32_e32 v3, 3, v14
	s_ashr_i32 s21, s20, 31
	s_bfe_i64 s[14:15], s[8:9], 0x100000
	v_readlane_b32 s36, v239, 51
	v_and_b32_e32 v3, 0xffff0, v3
	v_lshlrev_b32_e32 v4, 5, v14
	s_lshl_b64 s[12:13], s[20:21], 20
	s_lshl_b64 s[14:15], s[14:15], 20
	v_readlane_b32 s44, v239, 59
	v_add_u32_e32 v3, v13, v3
	v_and_b32_e32 v15, 32, v4
	v_readlane_b32 s45, v239, 60
	s_add_u32 s26, s44, s14
	v_lshl_or_b32 v3, v3, 11, v15
	s_addc_u32 s27, s45, s15
	s_add_i32 s5, s2, 0
	v_add_lshl_u32 v130, v3, v16, 1
	s_add_i32 m0, s5, 0x10000
	v_readlane_b32 s40, v239, 55
	global_load_lds_dwordx4 v130, s[26:27]
	s_add_i32 m0, s5, 0x12000
	v_readlane_b32 s41, v239, 56
	s_add_u32 s22, s40, s12
	global_load_lds_dwordx4 v128, s[26:27]
	s_addc_u32 s23, s41, s13
	s_mov_b32 m0, s5
	s_add_i32 s34, s5, 0x2000
	global_load_lds_dwordx4 v130, s[22:23]
	s_mov_b32 m0, s34
	s_add_u32 s12, s26, 0x80000
	global_load_lds_dwordx4 v128, s[22:23]
	s_addc_u32 s13, s27, 0
	s_add_i32 m0, s5, 0x14000
	v_mov_b32_e32 v131, 0
	global_load_lds_dwordx4 v130, s[12:13]
	s_add_i32 m0, s5, 0x16000
	v_readlane_b32 s37, v239, 52
	global_load_lds_dwordx4 v128, s[12:13]
	s_add_u32 s12, s22, 0x80000
	s_addc_u32 s13, s23, 0
	s_add_i32 s35, s5, 0x4000
	s_mov_b32 m0, s35
	s_add_i32 s36, s5, 0x6000
	global_load_lds_dwordx4 v130, s[12:13]
	s_mov_b32 m0, s36
	v_mov_b32_e32 v129, v131
	global_load_lds_dwordx4 v128, s[12:13]
	s_mov_b32 s37, 0
	v_lshl_add_u64 v[6:7], s[26:27], 0, v[130:131]
	v_lshl_add_u64 v[4:5], s[26:27], 0, v[128:129]
	v_lshl_add_u64 v[2:3], s[22:23], 0, v[130:131]
	s_cmp_lg_u32 s9, 1
	v_lshl_add_u64 v[0:1], s[22:23], 0, v[128:129]
	v_readlane_b32 s38, v239, 53
	v_readlane_b32 s39, v239, 54
	v_readlane_b32 s42, v239, 57
	v_readlane_b32 s43, v239, 58
	v_readlane_b32 s46, v239, 61
	v_readlane_b32 s47, v239, 62
	v_readlane_b32 s48, v239, 63
	v_readlane_b32 s49, v238, 0
	v_readlane_b32 s50, v238, 1
	v_readlane_b32 s51, v238, 2
	s_cbranch_scc1 .LBB0_2808
	s_barrier

.LBB0_2891:
	s_or_b64 exec, exec, s[14:15]
.LBB0_2892:
	s_or_b64 exec, exec, s[8:9]
	s_waitcnt lgkmcnt(0)
	s_barrier
	s_barrier
	v_mbcnt_lo_u32_b32 v0, -1, 0
	v_mbcnt_hi_u32_b32 v0, -1, v0
	s_and_b64 vcc, exec, s[76:77]
	s_waitcnt vmcnt(13)
	v_add_u32_e32 v9, s78, v0
	s_nop 0
	v_readfirstlane_b32 s1, v9
	s_cbranch_vccnz .LBB0_2916
	s_ashr_i32 s2, s94, 31
	s_lshr_b32 s3, s2, 29
	s_add_i32 s3, s94, s3
	s_and_b32 s4, s3, -8
	s_sub_i32 s5, s94, s4
	s_cmp_gt_i32 s5, -1
	s_cbranch_scc0 .LBB0_2895
	s_lshl_b32 s4, s5, 5
	s_cbranch_execz .LBB0_2896
	s_branch .LBB0_2897

.LBB0_2983:
	s_or_b64 exec, exec, s[12:13]
.LBB0_2984:
	s_or_b64 exec, exec, s[6:7]
	v_readlane_b32 s2, v238, 13
	v_readlane_b32 s3, v238, 14
	s_waitcnt lgkmcnt(0)
	s_barrier
	v_mbcnt_lo_u32_b32 v0, -1, 0
	v_mbcnt_hi_u32_b32 v0, -1, v0
	s_and_b64 vcc, exec, s[2:3]
	v_add_u32_e32 v64, s78, v0
	s_cbranch_vccnz .LBB0_3007
	v_readlane_b32 s4, v240, 49
	v_readlane_b32 s6, v240, 51
	v_readlane_b32 s7, v240, 52
	v_readlane_b32 s10, v240, 55
	v_readlane_b32 s11, v240, 56
	s_mov_b64 s[6:7], s[10:11]
	s_add_u32 s6, s6, 0x2000000
	v_readlane_b32 s2, v238, 8
	v_lshlrev_b32_e32 v0, 2, v64
	s_addc_u32 s7, s7, 0
	v_ashrrev_i32_e32 v68, 7, v64
	s_lshl_b32 s1, s94, 4
	s_and_b32 s2, s2, 0x600
	v_and_b32_e32 v69, 0x1fc, v0
	s_and_b32 s1, s1, 0x7c0
	v_or_b32_e32 v2, s2, v69
	v_add_u32_e32 v70, 4, v68
	v_add_u32_e32 v71, 8, v68
	v_add_u32_e32 v72, 12, v68
	v_add_u32_e32 v73, 16, v68
	v_add_u32_e32 v74, 20, v68
	v_add_u32_e32 v75, 24, v68
	v_add_u32_e32 v76, 28, v68
	v_add_u32_e32 v77, 32, v68
	v_add_u32_e32 v78, 36, v68
	v_add_u32_e32 v79, 40, v68
	v_add_u32_e32 v80, 44, v68
	v_add_u32_e32 v81, 48, v68
	v_add_u32_e32 v82, 52, v68
	v_add_u32_e32 v83, 56, v68
	v_add_u32_e32 v84, 60, v68
	v_add_u32_e32 v0, s1, v68
	v_lshlrev_b32_e32 v66, 2, v2
	v_add_u32_e32 v2, s1, v70
	v_add_u32_e32 v8, s1, v71
	v_add_u32_e32 v10, s1, v72
	v_add_u32_e32 v16, s1, v73
	v_add_u32_e32 v18, s1, v74
	v_add_u32_e32 v24, s1, v75
	v_add_u32_e32 v26, s1, v76
	v_add_u32_e32 v32, s1, v77
	v_add_u32_e32 v34, s1, v78
	v_add_u32_e32 v40, s1, v79
	v_add_u32_e32 v42, s1, v80
	v_add_u32_e32 v48, s1, v81
	v_add_u32_e32 v50, s1, v82
	v_add_u32_e32 v56, s1, v83
	v_add_u32_e32 v58, s1, v84
	v_ashrrev_i32_e32 v1, 31, v0
	v_ashrrev_i32_e32 v3, 31, v2
	v_ashrrev_i32_e32 v9, 31, v8
	v_ashrrev_i32_e32 v11, 31, v10
	v_ashrrev_i32_e32 v17, 31, v16
	v_ashrrev_i32_e32 v19, 31, v18
	v_ashrrev_i32_e32 v25, 31, v24
	v_ashrrev_i32_e32 v27, 31, v26
	v_ashrrev_i32_e32 v33, 31, v32
	v_ashrrev_i32_e32 v35, 31, v34
	v_ashrrev_i32_e32 v41, 31, v40
	v_ashrrev_i32_e32 v43, 31, v42
	v_ashrrev_i32_e32 v49, 31, v48
	v_ashrrev_i32_e32 v51, 31, v50
	v_ashrrev_i32_e32 v57, 31, v56
	v_ashrrev_i32_e32 v59, 31, v58
	v_lshlrev_b64 v[0:1], 14, v[0:1]
	v_lshlrev_b64 v[2:3], 14, v[2:3]
	v_lshlrev_b64 v[8:9], 14, v[8:9]
	v_lshlrev_b64 v[10:11], 14, v[10:11]
	v_lshlrev_b64 v[16:17], 14, v[16:17]
	v_lshlrev_b64 v[18:19], 14, v[18:19]
	v_lshlrev_b64 v[24:25], 14, v[24:25]
	v_lshlrev_b64 v[26:27], 14, v[26:27]
	v_lshlrev_b64 v[32:33], 14, v[32:33]
	v_lshlrev_b64 v[34:35], 14, v[34:35]
	v_lshlrev_b64 v[40:41], 14, v[40:41]
	v_lshlrev_b64 v[42:43], 14, v[42:43]
	v_lshlrev_b64 v[48:49], 14, v[48:49]
	v_lshlrev_b64 v[50:51], 14, v[50:51]
	v_lshlrev_b64 v[56:57], 14, v[56:57]
	v_lshlrev_b64 v[58:59], 14, v[58:59]
	v_lshl_add_u64 v[0:1], s[6:7], 0, v[0:1]
	v_mov_b32_e32 v67, 0
	v_lshl_add_u64 v[2:3], s[6:7], 0, v[2:3]
	v_lshl_add_u64 v[8:9], s[6:7], 0, v[8:9]
	v_lshl_add_u64 v[10:11], s[6:7], 0, v[10:11]
	v_lshl_add_u64 v[16:17], s[6:7], 0, v[16:17]
	v_lshl_add_u64 v[18:19], s[6:7], 0, v[18:19]
	v_lshl_add_u64 v[24:25], s[6:7], 0, v[24:25]
	v_lshl_add_u64 v[26:27], s[6:7], 0, v[26:27]
	v_lshl_add_u64 v[32:33], s[6:7], 0, v[32:33]
	v_lshl_add_u64 v[34:35], s[6:7], 0, v[34:35]
	v_lshl_add_u64 v[40:41], s[6:7], 0, v[40:41]
	v_lshl_add_u64 v[42:43], s[6:7], 0, v[42:43]
	v_lshl_add_u64 v[48:49], s[6:7], 0, v[48:49]
	v_lshl_add_u64 v[50:51], s[6:7], 0, v[50:51]
	v_lshl_add_u64 v[56:57], s[6:7], 0, v[56:57]
	v_lshl_add_u64 v[58:59], s[6:7], 0, v[58:59]
	v_lshl_add_u64 v[0:1], v[0:1], 0, v[66:67]
	v_lshl_add_u64 v[4:5], v[2:3], 0, v[66:67]
	v_lshl_add_u64 v[8:9], v[8:9], 0, v[66:67]
	v_lshl_add_u64 v[12:13], v[10:11], 0, v[66:67]
	v_lshl_add_u64 v[16:17], v[16:17], 0, v[66:67]
	v_lshl_add_u64 v[20:21], v[18:19], 0, v[66:67]
	v_lshl_add_u64 v[24:25], v[24:25], 0, v[66:67]
	v_lshl_add_u64 v[28:29], v[26:27], 0, v[66:67]
	v_lshl_add_u64 v[32:33], v[32:33], 0, v[66:67]
	v_lshl_add_u64 v[36:37], v[34:35], 0, v[66:67]
	v_lshl_add_u64 v[40:41], v[40:41], 0, v[66:67]
	v_lshl_add_u64 v[44:45], v[42:43], 0, v[66:67]
	v_lshl_add_u64 v[48:49], v[48:49], 0, v[66:67]
	v_lshl_add_u64 v[52:53], v[50:51], 0, v[66:67]
	v_lshl_add_u64 v[56:57], v[56:57], 0, v[66:67]
	v_lshl_add_u64 v[60:61], v[58:59], 0, v[66:67]
	global_load_dwordx4 v[0:3], v[0:1], off
	s_nop 0
	global_load_dwordx4 v[4:7], v[4:5], off
	s_nop 0
	global_load_dwordx4 v[8:11], v[8:9], off
	s_nop 0
	global_load_dwordx4 v[12:15], v[12:13], off
	s_nop 0
	global_load_dwordx4 v[16:19], v[16:17], off
	s_nop 0
	global_load_dwordx4 v[20:23], v[20:21], off
	s_nop 0
	global_load_dwordx4 v[24:27], v[24:25], off
	s_nop 0
	global_load_dwordx4 v[28:31], v[28:29], off
	s_nop 0
	global_load_dwordx4 v[32:35], v[32:33], off
	s_nop 0
	global_load_dwordx4 v[36:39], v[36:37], off
	s_nop 0
	global_load_dwordx4 v[40:43], v[40:41], off
	s_nop 0
	global_load_dwordx4 v[44:47], v[44:45], off
	s_nop 0
	global_load_dwordx4 v[48:51], v[48:49], off
	s_nop 0
	global_load_dwordx4 v[52:55], v[52:53], off
	s_nop 0
	global_load_dwordx4 v[56:59], v[56:57], off
	s_nop 0
	global_load_dwordx4 v[60:63], v[60:61], off
	v_bfe_u32 v85, v64, 5, 1
	v_lshlrev_b32_e32 v95, 1, v85
	v_readlane_b32 s2, v238, 5
	v_readlane_b32 s8, v240, 53
	v_readlane_b32 s9, v240, 54
	v_readlane_b32 s12, v240, 57
	v_readlane_b32 s13, v240, 58
	v_readlane_b32 s14, v240, 59
	v_readlane_b32 s15, v240, 60
	v_readlane_b32 s16, v240, 61
	v_readlane_b32 s17, v240, 62
	v_readlane_b32 s18, v240, 63
	v_readlane_b32 s19, v239, 0
	v_lshlrev_b32_e32 v64, 1, v64
	v_lshl_or_b32 v95, s2, 7, v95
	s_lshl_b32 s2, s2, 8
	v_and_b32_e32 v97, 62, v64
	v_readlane_b32 s8, v239, 51
	s_movk_i32 s1, 0x810
	v_mov_b32_e32 v98, s2
	v_lshlrev_b32_e32 v66, 1, v97
	v_readlane_b32 s20, v239, 63
	v_readlane_b32 s21, v238, 0
	v_mul_lo_u32 v87, v68, s1
	v_mad_u32_u24 v97, v97, s1, v98
	v_lshl_add_u32 v86, v69, 2, 0
	v_lshl_add_u64 v[64:65], s[20:21], 0, v[66:67]
	v_add_u32_e32 v66, 0xc180, v87
	v_add_u32_e32 v67, 0xe1c0, v87
	v_add_u32_e32 v100, 0x10200, v87
	v_lshl_or_b32 v97, v85, 2, v97
	v_readlane_b32 s5, v240, 50
	v_readlane_b32 s9, v239, 52
	v_readlane_b32 s10, v239, 53
	v_readlane_b32 s11, v239, 54
	v_readlane_b32 s12, v239, 55
	v_readlane_b32 s13, v239, 56
	v_readlane_b32 s14, v239, 57
	v_readlane_b32 s15, v239, 58
	v_readlane_b32 s16, v239, 59
	v_readlane_b32 s17, v239, 60
	v_readlane_b32 s18, v239, 61
	v_readlane_b32 s19, v239, 62
	v_readlane_b32 s22, v238, 1
	v_readlane_b32 s23, v238, 2
	v_or_b32_e32 v88, 2, v85
	v_or_b32_e32 v89, 4, v85
	v_or_b32_e32 v90, 6, v85
	v_or_b32_e32 v91, 8, v85
	v_or_b32_e32 v92, 10, v85
	v_or_b32_e32 v93, 12, v85
	v_or_b32_e32 v94, 14, v85
	v_add3_u32 v96, s78, v85, 14
	v_add_u32_e32 v97, 0, v97
	v_add_u32_e32 v98, v86, v66
	v_add_u32_e32 v99, v86, v67
	v_add_u32_e32 v100, v86, v100
	s_movk_i32 s1, 0x800
	s_movk_i32 s2, 0xffe0
	s_mov_b32 s4, s94
	s_branch .LBB0_2987

.LBB0_3057:
	s_or_b64 exec, exec, s[12:13]
	v_cvt_f32_u32_e32 v4, v2
	s_waitcnt vmcnt(0)
	v_readfirstlane_b32 s2, v3
	v_sub_u32_e32 v3, 0, v2
	v_rcp_iflag_f32_e32 v4, v4
	v_add_u32_e32 v5, s2, v1
	v_mul_f32_e32 v4, 0x4f7ffffe, v4
	v_cvt_u32_f32_e32 v4, v4
	v_mul_lo_u32 v1, v3, v4
	v_mul_hi_u32 v1, v4, v1
	v_add_u32_e32 v1, v4, v1
	v_mul_hi_u32 v1, v5, v1
	v_mul_lo_u32 v3, v1, v2
	v_sub_u32_e32 v3, v5, v3
	v_add_u32_e32 v4, 1, v1
	v_cmp_ge_u32_e32 vcc, v3, v2
	s_nop 1
	v_cndmask_b32_e32 v1, v1, v4, vcc
	v_sub_u32_e32 v4, v3, v2
	v_cndmask_b32_e32 v3, v3, v4, vcc
	v_add_u32_e32 v4, 1, v1
	v_cmp_ge_u32_e32 vcc, v3, v2
	v_add_u32_e32 v3, 1, v5
	s_nop 0
	v_cndmask_b32_e32 v1, v1, v4, vcc
	v_mul_lo_u32 v4, v2, v1
	v_add_u32_e32 v2, v4, v2
	v_cmp_ne_u32_e32 vcc, v3, v2
	s_and_saveexec_b64 s[4:5], vcc
	s_xor_b64 s[10:11], exec, s[4:5]
	s_cbranch_execz .LBB0_3071
	s_waitcnt lgkmcnt(0)
	v_mov_b32_e32 v0, 0x3500
	global_load_dword v0, v0, s[96:97] sc1
	s_add_u32 s14, s96, 0x3500
	s_addc_u32 s15, s97, 0
	s_waitcnt vmcnt(0)
	v_cmp_eq_u32_e32 vcc, v0, v1
	s_and_saveexec_b64 s[12:13], vcc
	s_cbranch_execz .LBB0_3070
	s_mov_b32 s2, 1
	s_mov_b64 s[16:17], 0
	v_mov_b32_e32 v0, 0
	s_branch .LBB0_3061

.LBB0_3088:
	s_or_b64 exec, exec, s[10:11]
	s_mov_b64 s[10:11], exec
	v_mbcnt_lo_u32_b32 v0, s10, 0
	v_mbcnt_hi_u32_b32 v0, s11, v0
	v_cmp_eq_u32_e32 vcc, 0, v0
	s_and_saveexec_b64 s[12:13], vcc
	s_cbranch_execz .LBB0_3090
	s_bcnt1_i32_b64 s2, s[10:11]
	v_mov_b32_e32 v0, 0x2000
	v_mov_b32_e32 v1, s2
.LBB0_3090:
	s_or_b64 exec, exec, s[12:13]
.LBB0_3091:
	s_or_b64 exec, exec, s[6:7]
	s_and_b64 vcc, exec, s[76:77]
	s_waitcnt lgkmcnt(0)
	s_barrier
	v_mbcnt_lo_u32_b32 v0, -1, 0
	v_mbcnt_hi_u32_b32 v0, -1, v0
	s_cbranch_vccnz .LBB0_3124
	v_add_u32_e32 v4, s78, v0
	v_ashrrev_i32_e32 v4, 5, v4
	v_lshlrev_b32_e32 v5, 3, v0
	v_and_b32_e32 v1, 15, v0
	v_readlane_b32 s2, v238, 16
	v_and_b32_e32 v6, 0xf8, v5
	v_ashrrev_i32_e32 v5, 31, v4
	s_movk_i32 s4, 0x210
	v_or_b32_e32 v72, s2, v1
	s_lshl_b32 s2, s0, 7
	v_lshlrev_b64 v[80:81], 10, v[4:5]
	v_mul_lo_u32 v4, v4, s4
	v_readlane_b32 s4, v238, 21
	s_cmpk_lt_u32 s4, 0x100
	v_lshlrev_b32_e32 v5, 1, v6
	s_cselect_b64 vcc, -1, 0
	s_mov_b64 s[4:5], 0x40000
	v_ashrrev_i32_e32 v7, 4, v0
	v_add3_u32 v73, 0, v4, v5
	v_mul_u32_u24_e32 v4, 0x210, v1
	v_and_b32_e32 v5, -16, v0
	v_lshl_add_u64 v[84:85], v[80:81], 0, s[4:5]
	s_and_b64 s[4:5], vcc, exec
	v_add3_u32 v150, 0, v4, v5
	v_sub_u32_e32 v4, 3, v7
	v_lshlrev_b32_e32 v152, 2, v7
	s_cselect_b32 s4, 0, 3
	v_cndmask_b32_e32 v151, v4, v7, vcc
	v_or_b32_e32 v4, s4, v152
	s_cselect_b32 s5, 1, 2
	v_ashrrev_i32_e32 v5, 31, v4
	v_lshlrev_b64 v[86:87], 10, v[4:5]
	v_or_b32_e32 v4, s5, v152
	s_cselect_b32 s28, 2, 1
	v_ashrrev_i32_e32 v5, 31, v4
	v_lshlrev_b64 v[88:89], 10, v[4:5]
	v_or_b32_e32 v4, s28, v152
	s_cselect_b32 s29, 3, 0
	v_ashrrev_i32_e32 v5, 31, v4
	v_lshlrev_b32_e32 v1, 2, v1
	v_lshlrev_b64 v[90:91], 10, v[4:5]
	v_or_b32_e32 v4, s29, v152
	s_cselect_b32 s6, 0x100, 16
	v_lshl_or_b32 v153, s4, 6, v1
	v_lshl_or_b32 v154, s5, 6, v1
	v_lshl_or_b32 v155, s28, 6, v1
	v_lshl_or_b32 v156, s29, 6, v1
	v_ashrrev_i32_e32 v5, 31, v4
	v_add_u32_e32 v1, s6, v152
	v_lshlrev_b64 v[92:93], 10, v[4:5]
	v_or_b32_e32 v4, s4, v1
	v_ashrrev_i32_e32 v5, 31, v4
	v_lshlrev_b64 v[94:95], 10, v[4:5]
	v_or_b32_e32 v4, s5, v1
	v_ashrrev_i32_e32 v5, 31, v4
	v_lshlrev_b64 v[96:97], 10, v[4:5]
	v_or_b32_e32 v4, s28, v1
	v_ashrrev_i32_e32 v5, 31, v4
	v_and_b32_e32 v0, 31, v0
	v_lshlrev_b64 v[98:99], 10, v[4:5]
	v_or_b32_e32 v4, s29, v1
	v_lshl_or_b32 v0, v0, 4, v80
	v_mov_b32_e32 v1, v81
	v_or_b32_e32 v74, s2, v72
	v_mov_b32_e32 v75, 0
	v_lshlrev_b32_e32 v2, 3, v7
	v_lshl_add_u64 v[0:1], s[54:55], 0, v[0:1]
	s_mov_b64 s[6:7], 0x3c000
	v_lshlrev_b64 v[76:77], 9, v[74:75]
	v_ashrrev_i32_e32 v3, 31, v2
	v_or_b32_e32 v74, 64, v74
	s_mov_b64 s[18:19], 0x4000
	v_ashrrev_i32_e32 v5, 31, v4
	v_lshl_add_u64 v[102:103], v[0:1], 0, s[6:7]
	s_mov_b64 s[6:7], 0x8000
	s_movk_i32 s20, 0xc000
	s_mov_b32 s17, 0
	v_lshlrev_b64 v[78:79], 9, v[74:75]
	v_cmp_eq_u32_e64 s[8:9], 2, v151
	v_lshl_add_u64 v[82:83], v[80:81], 0, s[18:19]
	v_lshlrev_b64 v[100:101], 10, v[4:5]
	s_lshl_b32 s30, s94, 2
	s_lshl_b32 s31, s33, 2
	v_lshl_add_u64 v[104:105], v[0:1], 0, s[6:7]
	s_mov_b32 s34, 0x3fb8aa3b
	s_mov_b32 s35, 0xc2ce8ed0
	s_mov_b32 s36, 0x42b17218
	s_mov_b32 s37, 0xbfc90fda
	v_mov_b32_e32 v157, 0x3c0881c4
	v_mov_b32_e32 v158, 0xbab64f3b
	s_movk_i32 s38, 0x1f8
	v_lshlrev_b64 v[106:107], 1, v[2:3]
	v_lshlrev_b32_e32 v74, 1, v6
	s_mov_b32 s21, -1
	v_lshlrev_b32_e32 v108, 1, v72
	v_mov_b32_e32 v159, 0x7f800000
	v_not_b32_e32 v160, 63
	v_not_b32_e32 v161, 31
	v_mov_b32_e32 v162, 0x7fc00000
	s_mov_b32 s39, s94
	s_branch .LBB0_3094

.LBB0_3227:
	s_or_b64 exec, exec, s[12:13]
	v_cvt_f32_u32_e32 v4, v2
	s_waitcnt vmcnt(0)
	v_readfirstlane_b32 s0, v3
	v_sub_u32_e32 v3, 0, v2
	v_rcp_iflag_f32_e32 v4, v4
	v_add_u32_e32 v5, s0, v1
	v_mul_f32_e32 v4, 0x4f7ffffe, v4
	v_cvt_u32_f32_e32 v4, v4
	v_mul_lo_u32 v1, v3, v4
	v_mul_hi_u32 v1, v4, v1
	v_add_u32_e32 v1, v4, v1
	v_mul_hi_u32 v1, v5, v1
	v_mul_lo_u32 v3, v1, v2
	v_sub_u32_e32 v3, v5, v3
	v_add_u32_e32 v4, 1, v1
	v_cmp_ge_u32_e32 vcc, v3, v2
	s_nop 1
	v_cndmask_b32_e32 v1, v1, v4, vcc
	v_sub_u32_e32 v4, v3, v2
	v_cndmask_b32_e32 v3, v3, v4, vcc
	v_add_u32_e32 v4, 1, v1
	v_cmp_ge_u32_e32 vcc, v3, v2
	v_add_u32_e32 v3, 1, v5
	s_nop 0
	v_cndmask_b32_e32 v1, v1, v4, vcc
	v_mul_lo_u32 v4, v2, v1
	v_add_u32_e32 v2, v4, v2
	v_cmp_ne_u32_e32 vcc, v3, v2
	s_and_saveexec_b64 s[4:5], vcc
	s_xor_b64 s[10:11], exec, s[4:5]
	s_cbranch_execz .LBB0_3241
	s_waitcnt lgkmcnt(0)
	v_mov_b32_e32 v0, 0x3500
	global_load_dword v0, v0, s[96:97] sc1
	s_add_u32 s14, s96, 0x3500
	s_addc_u32 s15, s97, 0
	s_waitcnt vmcnt(0)
	v_cmp_eq_u32_e32 vcc, v0, v1
	s_and_saveexec_b64 s[12:13], vcc
	s_cbranch_execz .LBB0_3240
	s_mov_b32 s0, 1
	s_mov_b64 s[16:17], 0
	v_mov_b32_e32 v0, 0
	s_branch .LBB0_3231

.LBB0_3258:
	s_or_b64 exec, exec, s[10:11]
	s_mov_b64 s[10:11], exec
	v_mbcnt_lo_u32_b32 v0, s10, 0
	v_mbcnt_hi_u32_b32 v0, s11, v0
	v_cmp_eq_u32_e32 vcc, 0, v0
	s_and_saveexec_b64 s[12:13], vcc
	s_cbranch_execz .LBB0_3260
	s_bcnt1_i32_b64 s0, s[10:11]
	v_mov_b32_e32 v0, 0x2000
	v_mov_b32_e32 v1, s0
.LBB0_3260:
	s_or_b64 exec, exec, s[12:13]
.LBB0_3261:
	s_or_b64 exec, exec, s[6:7]
	s_waitcnt lgkmcnt(0)
	s_barrier
	s_barrier
	v_mbcnt_lo_u32_b32 v0, -1, 0
	v_mbcnt_hi_u32_b32 v0, -1, v0
	s_cmpk_gt_i32 s94, 0x1ff
	v_add_u32_e32 v8, s78, v0
	s_nop 0
	v_readfirstlane_b32 s0, v8
	s_cbranch_scc1 .LBB0_3281
	s_ashr_i32 s2, s94, 31
	s_lshr_b32 s4, s2, 29
	s_add_i32 s4, s94, s4
	s_and_b32 s5, s4, -8
	s_sub_i32 s8, s94, s5
	s_cmp_gt_i32 s8, -1
	s_cbranch_scc0 .LBB0_3264
	s_lshl_b32 s5, s8, 6
	s_cbranch_execz .LBB0_3265
	s_branch .LBB0_3266

.LBB0_3332:
	s_or_b64 exec, exec, s[12:13]
.LBB0_3333:
	s_or_b64 exec, exec, s[6:7]
	s_waitcnt lgkmcnt(0)
	s_barrier
	v_mbcnt_lo_u32_b32 v0, -1, 0
	v_mbcnt_hi_u32_b32 v0, -1, v0
	s_andn2_b64 vcc, exec, s[80:81]
	v_add_u32_e32 v66, s78, v0
	v_cndmask_b32_e64 v0, 0, 1, s[80:81]
	v_cmp_ne_u32_e64 s[6:7], 1, v0
	s_mul_i32 s0, s94, 0x75
	s_cbranch_vccnz .LBB0_3356
	v_readlane_b32 s8, v240, 0
	v_readlane_b32 s9, v240, 1
	s_add_u32 s8, s8, 0x8400000
	s_addc_u32 s9, s9, 0
	s_lshr_b32 s4, s0, 8
	s_sub_i32 s4, s94, s4
	s_bfe_u32 s2, s0, 0x80008
	s_bfe_u32 s4, s4, 0x70001
	s_add_i32 s4, s4, s2
	v_readlane_b32 s10, v240, 2
	s_bfe_u32 s2, s4, 0x50003
	s_lshl_b32 s10, s2, 6
	s_mul_i32 s2, s2, 11
	v_lshlrev_b32_e32 v0, 2, v66
	v_readlane_b32 s11, v240, 3
	v_ashrrev_i32_e32 v70, 7, v66
	s_sub_i32 s2, s94, s2
	v_and_b32_e32 v71, 0x1fc, v0
	s_and_b32 s11, s2, 0xff
	v_add_u32_e32 v0, s10, v70
	s_movk_i32 s2, 0x5800
	s_waitcnt vmcnt(1)
	v_mov_b64_e32 v[56:57], s[8:9]
	v_lshlrev_b32_e32 v67, 2, v71
	v_mad_i64_i32 v[0:1], s[4:5], v0, s2, v[56:57]
	v_lshl_or_b32 v64, s11, 11, v67
	v_mov_b32_e32 v65, 0
	v_add_u32_e32 v72, 4, v70
	v_lshl_add_u64 v[8:9], v[0:1], 0, v[64:65]
	v_add_u32_e32 v0, s10, v72
	v_mad_i64_i32 v[0:1], s[4:5], v0, s2, v[56:57]
	v_add_u32_e32 v73, 8, v70
	v_lshl_add_u64 v[10:11], v[0:1], 0, v[64:65]
	global_load_dwordx4 v[0:3], v[8:9], off
	global_load_dwordx4 v[4:7], v[10:11], off
	v_add_u32_e32 v8, s10, v73
	v_mad_i64_i32 v[8:9], s[4:5], v8, s2, v[56:57]
	v_add_u32_e32 v74, 12, v70
	v_lshl_add_u64 v[16:17], v[8:9], 0, v[64:65]
	v_add_u32_e32 v8, s10, v74
	v_mad_i64_i32 v[8:9], s[4:5], v8, s2, v[56:57]
	v_add_u32_e32 v75, 16, v70
	v_lshl_add_u64 v[18:19], v[8:9], 0, v[64:65]
	global_load_dwordx4 v[8:11], v[16:17], off
	global_load_dwordx4 v[12:15], v[18:19], off
	v_add_u32_e32 v16, s10, v75
	v_mad_i64_i32 v[16:17], s[4:5], v16, s2, v[56:57]
	v_add_u32_e32 v76, 20, v70
	v_lshl_add_u64 v[24:25], v[16:17], 0, v[64:65]
	v_add_u32_e32 v16, s10, v76
	v_mad_i64_i32 v[16:17], s[4:5], v16, s2, v[56:57]
	v_add_u32_e32 v77, 24, v70
	v_lshl_add_u64 v[26:27], v[16:17], 0, v[64:65]
	global_load_dwordx4 v[16:19], v[24:25], off
	global_load_dwordx4 v[20:23], v[26:27], off
	v_add_u32_e32 v24, s10, v77
	v_mad_i64_i32 v[24:25], s[4:5], v24, s2, v[56:57]
	v_add_u32_e32 v78, 28, v70
	v_lshl_add_u64 v[32:33], v[24:25], 0, v[64:65]
	v_add_u32_e32 v24, s10, v78
	v_mad_i64_i32 v[24:25], s[4:5], v24, s2, v[56:57]
	v_add_u32_e32 v79, 32, v70
	v_lshl_add_u64 v[34:35], v[24:25], 0, v[64:65]
	global_load_dwordx4 v[24:27], v[32:33], off
	global_load_dwordx4 v[28:31], v[34:35], off
	v_add_u32_e32 v32, s10, v79
	v_mad_i64_i32 v[32:33], s[4:5], v32, s2, v[56:57]
	v_add_u32_e32 v80, 36, v70
	v_lshl_add_u64 v[40:41], v[32:33], 0, v[64:65]
	v_add_u32_e32 v32, s10, v80
	v_mad_i64_i32 v[32:33], s[4:5], v32, s2, v[56:57]
	v_add_u32_e32 v81, 40, v70
	v_lshl_add_u64 v[42:43], v[32:33], 0, v[64:65]
	global_load_dwordx4 v[32:35], v[40:41], off
	global_load_dwordx4 v[36:39], v[42:43], off
	v_add_u32_e32 v40, s10, v81
	v_mad_i64_i32 v[40:41], s[4:5], v40, s2, v[56:57]
	v_add_u32_e32 v82, 44, v70
	v_lshl_add_u64 v[48:49], v[40:41], 0, v[64:65]
	v_add_u32_e32 v40, s10, v82
	v_mad_i64_i32 v[40:41], s[4:5], v40, s2, v[56:57]
	v_add_u32_e32 v83, 48, v70
	v_lshl_add_u64 v[50:51], v[40:41], 0, v[64:65]
	global_load_dwordx4 v[40:43], v[48:49], off
	global_load_dwordx4 v[44:47], v[50:51], off
	v_add_u32_e32 v48, s10, v83
	v_mad_i64_i32 v[48:49], s[4:5], v48, s2, v[56:57]
	v_add_u32_e32 v84, 52, v70
	v_lshl_add_u64 v[58:59], v[48:49], 0, v[64:65]
	v_add_u32_e32 v48, s10, v84
	v_mad_i64_i32 v[48:49], s[4:5], v48, s2, v[56:57]
	v_add_u32_e32 v85, 56, v70
	s_waitcnt vmcnt(12)
	v_lshl_add_u64 v[60:61], v[48:49], 0, v[64:65]
	global_load_dwordx4 v[48:51], v[58:59], off
	global_load_dwordx4 v[52:55], v[60:61], off
	v_add_u32_e32 v58, s10, v85
	v_mad_i64_i32 v[58:59], s[4:5], v58, s2, v[56:57]
	v_add_u32_e32 v86, 60, v70
	v_lshl_add_u64 v[68:69], v[58:59], 0, v[64:65]
	v_add_u32_e32 v58, s10, v86
	v_mad_i64_i32 v[56:57], s[4:5], v58, s2, v[56:57]
	v_lshl_add_u64 v[88:89], v[56:57], 0, v[64:65]
	global_load_dwordx4 v[56:59], v[68:69], off
	global_load_dwordx4 v[60:63], v[88:89], off
	v_bfe_u32 v87, v66, 5, 1
	v_lshlrev_b32_e32 v97, 1, v87
	v_readlane_b32 s5, v238, 5
	v_readlane_b32 s12, v240, 4
	v_readlane_b32 s13, v240, 5
	v_readlane_b32 s14, v240, 6
	v_readlane_b32 s15, v240, 7
	v_readlane_b32 s16, v240, 8
	v_readlane_b32 s17, v240, 9
	v_readlane_b32 s18, v240, 10
	v_readlane_b32 s19, v240, 11
	v_readlane_b32 s20, v240, 12
	v_readlane_b32 s21, v240, 13
	v_readlane_b32 s22, v240, 14
	v_readlane_b32 s23, v240, 15
	v_lshlrev_b32_e32 v64, 1, v66
	v_lshl_or_b32 v97, s5, 7, v97
	s_lshl_b32 s5, s5, 8
	v_and_b32_e32 v68, 62, v64
	v_readlane_b32 s12, v239, 51
	s_movk_i32 s4, 0x810
	v_mov_b32_e32 v99, s5
	v_lshlrev_b32_e32 v64, 1, v68
	v_readlane_b32 s20, v239, 59
	v_readlane_b32 s21, v239, 60
	v_mul_lo_u32 v89, v70, s4
	v_mad_u32_u24 v68, v68, s4, v99
	v_add_u32_e32 v88, 0, v67
	v_readlane_b32 s14, v239, 53
	v_lshl_add_u64 v[66:67], s[20:21], 0, v[64:65]
	v_add_u32_e32 v64, 0xc180, v89
	v_add_u32_e32 v69, 0xe1c0, v89
	v_add_u32_e32 v102, 0x10200, v89
	v_lshl_or_b32 v68, v87, 2, v68
	s_mov_b32 s11, 0
	v_readlane_b32 s13, v239, 52
	v_readlane_b32 s15, v239, 54
	v_readlane_b32 s16, v239, 55
	v_readlane_b32 s17, v239, 56
	v_readlane_b32 s18, v239, 57
	v_readlane_b32 s19, v239, 58
	v_readlane_b32 s22, v239, 61
	v_readlane_b32 s23, v239, 62
	v_readlane_b32 s24, v239, 63
	v_readlane_b32 s25, v238, 0
	v_readlane_b32 s26, v238, 1
	v_readlane_b32 s27, v238, 2
	v_or_b32_e32 v90, 2, v87
	v_or_b32_e32 v91, 4, v87
	v_or_b32_e32 v92, 6, v87
	v_or_b32_e32 v93, 8, v87
	v_or_b32_e32 v94, 10, v87
	v_or_b32_e32 v95, 12, v87
	v_or_b32_e32 v96, 14, v87
	v_add3_u32 v98, s78, v87, 14
	v_add_u32_e32 v99, 0, v68
	v_add_u32_e32 v100, v88, v64
	v_add_u32_e32 v101, v88, v69
	v_add_u32_e32 v102, v88, v102
	s_movk_i32 s4, 0x1600
	s_movk_i32 s5, 0xffe0
	s_mov_b32 s14, s94
	s_branch .LBB0_3336

.LBB0_3402:
	s_or_b64 exec, exec, s[10:11]
	v_cvt_f32_u32_e32 v4, v2
	s_waitcnt vmcnt(0)
	v_readfirstlane_b32 s0, v3
	v_sub_u32_e32 v3, 0, v2
	v_rcp_iflag_f32_e32 v4, v4
	v_add_u32_e32 v5, s0, v1
	v_mul_f32_e32 v4, 0x4f7ffffe, v4
	v_cvt_u32_f32_e32 v4, v4
	v_mul_lo_u32 v1, v3, v4
	v_mul_hi_u32 v1, v4, v1
	v_add_u32_e32 v1, v4, v1
	v_mul_hi_u32 v1, v5, v1
	v_mul_lo_u32 v3, v1, v2
	v_sub_u32_e32 v3, v5, v3
	v_add_u32_e32 v4, 1, v1
	v_cmp_ge_u32_e32 vcc, v3, v2
	s_nop 1
	v_cndmask_b32_e32 v1, v1, v4, vcc
	v_sub_u32_e32 v4, v3, v2
	v_cndmask_b32_e32 v3, v3, v4, vcc
	v_add_u32_e32 v4, 1, v1
	v_cmp_ge_u32_e32 vcc, v3, v2
	v_add_u32_e32 v3, 1, v5
	s_nop 0
	v_cndmask_b32_e32 v1, v1, v4, vcc
	v_mul_lo_u32 v4, v2, v1
	v_add_u32_e32 v2, v4, v2
	v_cmp_ne_u32_e32 vcc, v3, v2
	s_and_saveexec_b64 s[0:1], vcc
	s_xor_b64 s[8:9], exec, s[0:1]
	s_cbranch_execz .LBB0_3416
	s_waitcnt lgkmcnt(0)
	v_mov_b32_e32 v0, 0x3500
	global_load_dword v0, v0, s[96:97] sc1
	s_add_u32 s12, s96, 0x3500
	s_addc_u32 s13, s97, 0
	s_waitcnt vmcnt(0)
	v_cmp_eq_u32_e32 vcc, v0, v1
	s_and_saveexec_b64 s[10:11], vcc
	s_cbranch_execz .LBB0_3415
	s_mov_b32 s0, 1
	s_mov_b64 s[14:15], 0
	v_mov_b32_e32 v0, 0
	s_branch .LBB0_3406

.LBB0_3433:
	s_or_b64 exec, exec, s[8:9]
	s_mov_b64 s[8:9], exec
	v_mbcnt_lo_u32_b32 v0, s8, 0
	v_mbcnt_hi_u32_b32 v0, s9, v0
	v_cmp_eq_u32_e32 vcc, 0, v0
	s_and_saveexec_b64 s[10:11], vcc
	s_cbranch_execz .LBB0_3435
	s_bcnt1_i32_b64 s0, s[8:9]
	v_mov_b32_e32 v0, 0x2000
	v_mov_b32_e32 v1, s0
.LBB0_3435:
	s_or_b64 exec, exec, s[10:11]
.LBB0_3436:
	s_or_b64 exec, exec, s[4:5]
	s_waitcnt lgkmcnt(0)
	s_barrier
	s_barrier
	v_mbcnt_lo_u32_b32 v0, -1, 0
	v_mbcnt_hi_u32_b32 v0, -1, v0
	s_cmpk_gt_i32 s94, 0x57f
	s_waitcnt vmcnt(12)
	v_add_u32_e32 v12, s78, v0
	s_nop 0
	v_readfirstlane_b32 s0, v12
	s_cbranch_scc1 .LBB0_3448
	v_lshlrev_b32_e32 v0, 4, v12
	v_add_u32_e32 v1, 0x2000, v0
	v_ashrrev_i32_e32 v2, 31, v1
	v_lshrrev_b32_e32 v2, 22, v2
	v_add_u32_e32 v2, v1, v2
	v_ashrrev_i32_e32 v8, 10, v2
	s_ashr_i32 s2, s94, 31
	v_mul_i32_i24_e32 v2, 0x400, v8
	s_lshr_b32 s3, s2, 29
	v_sub_u32_e32 v1, v1, v2
	s_add_i32 s3, s94, s3
	s_ashr_i32 s6, s0, 6
	v_lshrrev_b32_e32 v2, 4, v1
	s_ashr_i32 s4, s3, 3
	s_and_b32 s3, s3, -8
	s_ashr_i32 s5, s0, 8
	s_lshl_b32 s1, s6, 10
	v_bitop3_b32 v1, v2, v1, 32 bitop3:0x6c
	s_sub_i32 s7, s94, s3
	v_ashrrev_i32_e32 v2, 31, v1
	s_cmp_lt_i32 s7, 0
	s_movk_i32 s3, 0xb1
	v_lshrrev_b32_e32 v2, 26, v2
	s_cselect_b32 s8, s3, 0xb0
	v_add_u32_e32 v2, v1, v2
	s_mul_i32 s7, s8, s7
	v_ashrrev_i32_e32 v9, 6, v2
	v_and_b32_e32 v2, 0xc0, v2
	s_add_i32 s7, s7, s4
	v_sub_u32_e32 v1, v1, v2
	v_mov_b32_e32 v2, 1
	s_mul_hi_i32 s4, s7, 0x2e8ba2e9
	v_ashrrev_i16_sdwa v1, v2, sext(v1) dst_sel:DWORD dst_unused:UNUSED_PAD src0_sel:DWORD src1_sel:BYTE_0
	s_lshr_b32 s8, s4, 31
	s_ashr_i32 s4, s4, 6
	v_bfe_i32 v11, v1, 0, 16
	v_bfe_i32 v1, v12, 27, 1
	s_add_i32 s4, s4, s8
	v_lshrrev_b32_e32 v1, 22, v1
	s_lshl_b32 s8, s4, 3
	s_mulk_i32 s4, 0x160
	v_lshlrev_b32_e32 v3, 3, v8
	v_add_u32_e32 v1, v0, v1
	s_sub_i32 s7, s7, s4
	v_and_b32_e32 v3, 0xffff0, v3
	v_lshlrev_b32_e32 v4, 5, v8
	v_and_b32_e32 v1, 0xfffffc00, v1
	s_sext_i32_i16 s4, s7
	v_add_u32_e32 v3, v9, v3
	v_and_b32_e32 v10, 32, v4
	v_sub_u32_e32 v0, v0, v1
	s_bfe_u32 s4, s4, 0x3001c
	v_lshl_or_b32 v3, v3, 11, v10
	v_lshrrev_b32_e32 v1, 4, v0
	s_add_i32 s9, s7, s4
	v_add_lshl_u32 v128, v3, v11, 1
	v_bitop3_b32 v0, v1, v0, 32 bitop3:0x6c
	v_ashrrev_i32_e32 v3, 31, v12
	s_sext_i32_i16 s4, s9
	s_and_b32 s9, s9, 0xfff8
	v_ashrrev_i32_e32 v1, 31, v0
	v_lshrrev_b32_e32 v3, 26, v3
	s_sub_i32 s7, s7, s9
	v_lshrrev_b32_e32 v1, 26, v1
	v_add_u32_e32 v3, v12, v3
	s_sext_i32_i16 s7, s7
	v_readlane_b32 s52, v239, 51
	v_add_u32_e32 v1, v0, v1
	v_ashrrev_i32_e32 v14, 6, v3
	s_lshr_b32 s4, s4, 3
	s_add_i32 s16, s8, s7
	v_readlane_b32 s53, v239, 52
	v_readlane_b32 s54, v239, 53
	v_readlane_b32 s55, v239, 54
	v_readlane_b32 s56, v239, 55
	v_readlane_b32 s57, v239, 56
	v_readlane_b32 s58, v239, 57
	v_readlane_b32 s59, v239, 58
	v_ashrrev_i32_e32 v13, 6, v1
	v_lshlrev_b32_e32 v3, 3, v14
	v_and_b32_e32 v1, 0xc0, v1
	s_ashr_i32 s17, s16, 31
	s_bfe_i64 s[10:11], s[4:5], 0x100000
	v_readlane_b32 s60, v239, 59
	v_readlane_b32 s61, v239, 60
	v_readlane_b32 s62, v239, 61
	v_readlane_b32 s63, v239, 62
	s_mov_b64 s[52:53], s[56:57]
	v_and_b32_e32 v3, 0xffff0, v3
	v_lshlrev_b32_e32 v4, 5, v14
	v_sub_u32_e32 v0, v0, v1
	s_lshl_b64 s[8:9], s[16:17], 20
	s_lshl_b64 s[10:11], s[10:11], 20
	s_mov_b64 s[54:55], s[58:59]
	s_mov_b64 s[56:57], s[60:61]
	v_add_u32_e32 v3, v13, v3
	v_and_b32_e32 v15, 32, v4
	v_ashrrev_i16_sdwa v0, v2, sext(v0) dst_sel:DWORD dst_unused:UNUSED_PAD src0_sel:DWORD src1_sel:BYTE_0
	s_add_u32 s20, s56, s10
	v_lshl_or_b32 v3, v3, 11, v15
	s_waitcnt vmcnt(11)
	v_bfe_i32 v16, v0, 0, 16
	s_addc_u32 s21, s57, s11
	s_add_i32 s26, s1, 0
	v_add_lshl_u32 v130, v3, v16, 1
	s_add_i32 m0, s26, 0x10000
	v_mov_b32_e32 v131, 0
	global_load_lds_dwordx4 v130, s[20:21]
	s_add_i32 m0, s26, 0x12000
	s_add_u32 s18, s52, s8
	global_load_lds_dwordx4 v128, s[20:21]
	s_addc_u32 s19, s53, s9
	s_mov_b32 m0, s26
	s_add_i32 s27, s26, 0x2000
	global_load_lds_dwordx4 v130, s[18:19]
	s_mov_b32 m0, s27
	s_add_u32 s8, s20, 0x80000
	global_load_lds_dwordx4 v128, s[18:19]
	s_addc_u32 s9, s21, 0
	s_add_i32 m0, s26, 0x14000
	v_mov_b32_e32 v129, v131
	global_load_lds_dwordx4 v130, s[8:9]
	s_add_i32 m0, s26, 0x16000
	s_mov_b32 s30, 0
	global_load_lds_dwordx4 v128, s[8:9]
	s_add_u32 s8, s18, 0x80000
	s_addc_u32 s9, s19, 0
	s_add_i32 s28, s26, 0x4000
	s_mov_b32 m0, s28
	s_add_i32 s29, s26, 0x6000
	global_load_lds_dwordx4 v130, s[8:9]
	s_mov_b32 m0, s29
	v_lshl_add_u64 v[6:7], s[20:21], 0, v[130:131]
	global_load_lds_dwordx4 v128, s[8:9]
	v_lshl_add_u64 v[4:5], s[20:21], 0, v[128:129]
	v_lshl_add_u64 v[2:3], s[18:19], 0, v[130:131]
	s_cmp_lg_u32 s5, 1
	v_lshl_add_u64 v[0:1], s[18:19], 0, v[128:129]
	v_readlane_b32 s64, v239, 63
	v_readlane_b32 s65, v238, 0
	v_readlane_b32 s66, v238, 1
	v_readlane_b32 s67, v238, 2
	s_mov_b64 s[58:59], s[62:63]
	s_cbranch_scc1 .LBB0_3439
	s_barrier

.LBB0_3522:
	s_or_b64 exec, exec, s[10:11]
.LBB0_3523:
	s_or_b64 exec, exec, s[4:5]
	s_waitcnt lgkmcnt(0)
	s_barrier
	s_barrier
	v_mbcnt_lo_u32_b32 v0, -1, 0
	v_mbcnt_hi_u32_b32 v0, -1, v0
	s_and_b64 vcc, exec, s[76:77]
	s_waitcnt vmcnt(13)
	v_add_u32_e32 v8, s78, v0
	s_nop 0
	v_readfirstlane_b32 s2, v8
	s_cbranch_vccnz .LBB0_3547
	s_ashr_i32 s3, s94, 31
	s_lshr_b32 s0, s3, 29
	s_add_i32 s6, s94, s0
	s_and_b32 s0, s6, -8
	s_sub_i32 s5, s94, s0
	s_cmp_gt_i32 s5, -1
	s_cbranch_scc0 .LBB0_3526
	s_lshl_b32 s4, s5, 5
	s_ashr_i32 s6, s6, 3
	s_cbranch_execz .LBB0_3527
	s_branch .LBB0_3528

.LBB0_3565:
	s_or_b64 exec, exec, s[6:7]
	v_cvt_f32_u32_e32 v4, v2
	s_waitcnt vmcnt(0)
	v_readfirstlane_b32 s4, v3
	v_sub_u32_e32 v3, 0, v2
	v_rcp_iflag_f32_e32 v4, v4
	v_add_u32_e32 v5, s4, v1
	v_mul_f32_e32 v4, 0x4f7ffffe, v4
	v_cvt_u32_f32_e32 v4, v4
	v_mul_lo_u32 v1, v3, v4
	v_mul_hi_u32 v1, v4, v1
	v_add_u32_e32 v1, v4, v1
	v_mul_hi_u32 v1, v5, v1
	v_mul_lo_u32 v3, v1, v2
	v_sub_u32_e32 v3, v5, v3
	v_add_u32_e32 v4, 1, v1
	v_cmp_ge_u32_e32 vcc, v3, v2
	s_nop 1
	v_cndmask_b32_e32 v1, v1, v4, vcc
	v_sub_u32_e32 v4, v3, v2
	v_cndmask_b32_e32 v3, v3, v4, vcc
	v_add_u32_e32 v4, 1, v1
	v_cmp_ge_u32_e32 vcc, v3, v2
	v_add_u32_e32 v3, 1, v5
	s_nop 0
	v_cndmask_b32_e32 v1, v1, v4, vcc
	v_mul_lo_u32 v4, v2, v1
	v_add_u32_e32 v2, v4, v2
	v_cmp_ne_u32_e32 vcc, v3, v2
	s_and_saveexec_b64 s[4:5], vcc
	s_xor_b64 s[4:5], exec, s[4:5]
	s_cbranch_execz .LBB0_3579
	s_waitcnt lgkmcnt(0)
	v_mov_b32_e32 v0, 0x3500
	global_load_dword v0, v0, s[96:97] sc1
	s_add_u32 s8, s96, 0x3500
	s_addc_u32 s9, s97, 0
	s_waitcnt vmcnt(0)
	v_cmp_eq_u32_e32 vcc, v0, v1
	s_and_saveexec_b64 s[6:7], vcc
	s_cbranch_execz .LBB0_3578
	s_mov_b32 s20, 1
	s_mov_b64 s[10:11], 0
	v_mov_b32_e32 v0, 0
	s_branch .LBB0_3569

.LBB0_3596:
	s_or_b64 exec, exec, s[4:5]
	s_mov_b64 s[4:5], exec
	v_mbcnt_lo_u32_b32 v0, s4, 0
	v_mbcnt_hi_u32_b32 v0, s5, v0
	v_cmp_eq_u32_e32 vcc, 0, v0
	s_and_saveexec_b64 s[6:7], vcc
	s_cbranch_execz .LBB0_3598
	s_bcnt1_i32_b64 s4, s[4:5]
	v_mov_b32_e32 v0, 0x2000
	v_mov_b32_e32 v1, s4
.LBB0_3598:
	s_or_b64 exec, exec, s[6:7]
.LBB0_3599:
	s_or_b64 exec, exec, s[0:1]
	s_cmpk_gt_i32 s92, 0x1fff
	s_waitcnt lgkmcnt(0)
	s_barrier
	v_mbcnt_lo_u32_b32 v0, -1, 0
	v_mbcnt_hi_u32_b32 v0, -1, v0
	s_cbranch_scc1 .LBB0_3602
	v_lshlrev_b32_e32 v0, 2, v0
	v_ashrrev_i32_e32 v1, 31, v0
	v_readlane_b32 s0, v239, 3
	v_lshlrev_b64 v[4:5], 2, v[0:1]
	v_readlane_b32 s1, v239, 4
	v_readlane_b32 s14, v239, 17
	v_readlane_b32 s15, v239, 18
	s_mov_b64 s[0:1], 0x1000
	v_readlane_b32 s4, v239, 7
	v_lshl_add_u64 v[6:7], s[14:15], 0, v[4:5]
	v_lshl_add_u64 v[8:9], v[6:7], 0, s[0:1]
	s_mov_b64 s[0:1], 0x1400
	v_readlane_b32 s5, v239, 8
	v_lshl_add_u64 v[10:11], v[6:7], 0, s[0:1]
	s_mov_b64 s[0:1], 0x1800
	s_ashr_i32 s93, s92, 31
	s_waitcnt vmcnt(12)
	v_lshl_add_u64 v[12:13], v[6:7], 0, s[0:1]
	s_mov_b64 s[0:1], 0x1c00
	s_lshl_b64 s[4:5], s[92:93], 13
	v_lshl_add_u64 v[14:15], v[6:7], 0, s[0:1]
	s_add_u32 s0, s48, s4
	v_readlane_b32 s2, v239, 5
	v_readlane_b32 s3, v239, 6
	v_readlane_b32 s6, v239, 9
	v_readlane_b32 s7, v239, 10
	s_addc_u32 s1, s49, s5
	s_ashr_i32 s91, s90, 31
	s_lshl_b64 s[2:3], s[90:91], 13
	v_readlane_b32 s6, v240, 16
	v_readlane_b32 s7, v240, 17
	s_add_u32 s4, s6, s4
	s_addc_u32 s5, s7, s5
	s_movk_i32 s6, 0x1000
	s_waitcnt vmcnt(11)
	v_mov_b32_e32 v16, 0x358637bd
	s_mov_b32 s7, 0x800000
	v_readlane_b32 s8, v239, 11
	v_readlane_b32 s9, v239, 12
	v_readlane_b32 s10, v239, 13
	v_readlane_b32 s11, v239, 14
	v_readlane_b32 s12, v239, 15
	v_readlane_b32 s13, v239, 16
